# GEMM K-loops: second A-buffer LDS address held in one persistent VGPR with immediate offsets (2 VALU fewer per K-iteration in the load segment)
# speedup vs baseline: 1.0022x; 1.0022x over previous
; #define PG8_STAGE(bufoff, gbase, voff) do { _Pragma("unroll") for (int _i = 0; _i < 2; ++_i) \
;         __builtin_amdgcn_global_load_lds((const unsigned*)((const char*)(gbase) + (voff)[_i]), (LAS unsigned*)(lds + (bufoff) + ldsw + _i * 8192), 16, 0, 0); } while (0)
; #define PG8_LDA(dst, b, h) do { _Pragma("unroll") for (int m = 0; m < 4; ++m) _Pragma("unroll") for (int k = 0; k < 2; ++k) dst[m][k] = *(const LAS bf16x8*)(lds + PG8_SA(b, h) + aoff + m * 2048 + k * 1024); } while (0)
; #define PG8_LDB(dst, b, h) do { _Pragma("unroll") for (int n = 0; n < 2; ++n) _Pragma("unroll") for (int k = 0; k < 2; ++k) dst[n][k] = *(const LAS bf16x8*)(lds + PG8_SB(b, h) + boff + n * 2048 + k * 1024); } while (0)
; #define PG8_MMA(ai, bj, At, Bt) do { __builtin_amdgcn_s_setprio(1); _Pragma("unroll") for (int m = 0; m < 4; ++m) _Pragma("unroll") for (int n = 0; n < 2; ++n) _Pragma("unroll") for (int k = 0; k < 2; ++k) \
;         acc[ai][bj][m][n] = __builtin_amdgcn_mfma_f32_16x16x32_bf16(Bt[n][k], At[m][k], acc[ai][bj][m][n], 0, 0, 0); __builtin_amdgcn_s_setprio(0); } while (0)
; #define PG8_WAIT_V(n) asm volatile("s_waitcnt vmcnt(" #n ")" ::: "memory")
; #define PG8_WAIT_L(n) asm volatile("s_waitcnt lgkmcnt(" #n ")" ::: "memory")
; #define PG8_BAR __builtin_amdgcn_s_barrier()
; #define PG8_SCHED __builtin_amdgcn_sched_barrier(0)
; template <class Epi>
; __device__ __forceinline__ void gemm_phase(LAS unsigned char* lds, const Gemm g, const StaticOrder& S, const Epi& E, const int wid) {
;     ...
;     for (;;) {
;         const bool has_next = S.next(ui + 1, nxt);
;         const char* nA = has_next ? PG8_TILEA(nxt.pm) : cA; const char* nB = has_next ? PG8_TILEB(nxt.pn) : cB;
;         for (int t = 0; t < nt; t += 2) {
;             const bool last = (t == nt - 2);
;             const char* a1 = cA + (size_t)(t + 1) * kstep;
;             const char* a2 = last ? nA : cA + (size_t)(t + 2) * kstep; const char* b2 = last ? nB : cB + (size_t)(t + 2) * kstep;
;             const char* a3 = a2 + kstep; const char* b3 = b2 + kstep;
;             PG8_LDB(B0, 0, 0); PG8_LDB(B1, 0, 1); PG8_SCHED; PG8_LDA(At, 0, 0); PG8_STAGE(PG8_SA(1, 1), a1 + hstepA, voffA);
;             PG8_WAIT_V(8); PG8_WAIT_L(0); PG8_BAR; PG8_MMA(0, 0, At, B0); PG8_MMA(0, 1, At, B1); PG8_BAR; PG8_SCHED;
.LBB0_156:
	s_ashr_i32 s49, s48, 31
	s_lshl_b64 s[20:21], s[48:49], 20
	s_add_u32 s52, s36, s20
	s_addc_u32 s53, s37, s21
	s_and_b64 s[8:9], s[8:9], exec
	s_cselect_b32 s20, s53, s57
	s_cselect_b32 s21, s52, s56
	s_add_u32 s49, s56, 0x100
	v_mov_b32_e32 v0, 0
	s_addc_u32 s55, s57, 0
	s_mov_b32 s60, -2
	v_mov_b32_e32 v1, v0
	v_mov_b32_e32 v2, v0
	v_mov_b32_e32 v3, v0
	v_mov_b32_e32 v4, v0
	v_mov_b32_e32 v5, v0
	v_mov_b32_e32 v6, v0
	v_mov_b32_e32 v7, v0
	v_mov_b32_e32 v8, v0
	v_mov_b32_e32 v9, v0
	v_mov_b32_e32 v10, v0
	v_mov_b32_e32 v11, v0
	v_mov_b32_e32 v12, v0
	v_mov_b32_e32 v13, v0
	v_mov_b32_e32 v14, v0
	v_mov_b32_e32 v15, v0
	v_mov_b32_e32 v16, v0
	v_mov_b32_e32 v17, v0
	v_mov_b32_e32 v18, v0
	v_mov_b32_e32 v19, v0
	v_mov_b32_e32 v20, v0
	v_mov_b32_e32 v21, v0
	v_mov_b32_e32 v22, v0
	v_mov_b32_e32 v23, v0
	v_mov_b32_e32 v24, v0
	v_mov_b32_e32 v25, v0
	v_mov_b32_e32 v26, v0
	v_mov_b32_e32 v27, v0
	v_mov_b32_e32 v28, v0
	v_mov_b32_e32 v29, v0
	v_mov_b32_e32 v30, v0
	v_mov_b32_e32 v31, v0
	v_mov_b32_e32 v64, v0
	v_mov_b32_e32 v65, v0
	v_mov_b32_e32 v66, v0
	v_mov_b32_e32 v67, v0
	v_mov_b32_e32 v68, v0
	v_mov_b32_e32 v69, v0
	v_mov_b32_e32 v70, v0
	v_mov_b32_e32 v71, v0
	v_mov_b32_e32 v72, v0
	v_mov_b32_e32 v73, v0
	v_mov_b32_e32 v74, v0
	v_mov_b32_e32 v75, v0
	v_mov_b32_e32 v76, v0
	v_mov_b32_e32 v77, v0
	v_mov_b32_e32 v78, v0
	v_mov_b32_e32 v79, v0
	v_mov_b32_e32 v80, v0
	v_mov_b32_e32 v81, v0
	v_mov_b32_e32 v82, v0
	v_mov_b32_e32 v83, v0
	v_mov_b32_e32 v84, v0
	v_mov_b32_e32 v85, v0
	v_mov_b32_e32 v86, v0
	v_mov_b32_e32 v87, v0
	v_mov_b32_e32 v88, v0
	v_mov_b32_e32 v89, v0
	v_mov_b32_e32 v90, v0
	v_mov_b32_e32 v91, v0
	v_mov_b32_e32 v92, v0
	v_mov_b32_e32 v93, v0
	v_mov_b32_e32 v94, v0
	v_mov_b32_e32 v95, v0
	v_mov_b32_e32 v32, v0
	v_mov_b32_e32 v33, v0
	v_mov_b32_e32 v34, v0
	v_mov_b32_e32 v35, v0
	v_mov_b32_e32 v36, v0
	v_mov_b32_e32 v37, v0
	v_mov_b32_e32 v38, v0
	v_mov_b32_e32 v39, v0
	v_mov_b32_e32 v40, v0
	v_mov_b32_e32 v41, v0
	v_mov_b32_e32 v42, v0
	v_mov_b32_e32 v43, v0
	v_mov_b32_e32 v44, v0
	v_mov_b32_e32 v45, v0
	v_mov_b32_e32 v46, v0
	v_mov_b32_e32 v47, v0
	v_mov_b32_e32 v48, v0
	v_mov_b32_e32 v49, v0
	v_mov_b32_e32 v50, v0
	v_mov_b32_e32 v51, v0
	v_mov_b32_e32 v52, v0
	v_mov_b32_e32 v53, v0
	v_mov_b32_e32 v54, v0
	v_mov_b32_e32 v55, v0
	v_mov_b32_e32 v56, v0
	v_mov_b32_e32 v57, v0
	v_mov_b32_e32 v58, v0
	v_mov_b32_e32 v59, v0
	v_mov_b32_e32 v60, v0
	v_mov_b32_e32 v61, v0
	v_mov_b32_e32 v62, v0
	v_mov_b32_e32 v63, v0
	v_mov_b32_e32 v96, v0
	v_mov_b32_e32 v97, v0
	v_mov_b32_e32 v98, v0
	v_mov_b32_e32 v99, v0
	v_mov_b32_e32 v100, v0
	v_mov_b32_e32 v101, v0
	v_mov_b32_e32 v102, v0
	v_mov_b32_e32 v103, v0
	v_mov_b32_e32 v104, v0
	v_mov_b32_e32 v105, v0
	v_mov_b32_e32 v106, v0
	v_mov_b32_e32 v107, v0
	v_mov_b32_e32 v108, v0
	v_mov_b32_e32 v109, v0
	v_mov_b32_e32 v110, v0
	v_mov_b32_e32 v111, v0
	v_mov_b32_e32 v112, v0
	v_mov_b32_e32 v113, v0
	v_mov_b32_e32 v114, v0
	v_mov_b32_e32 v115, v0
	v_mov_b32_e32 v116, v0
	v_mov_b32_e32 v117, v0
	v_mov_b32_e32 v118, v0
	v_mov_b32_e32 v119, v0
	v_mov_b32_e32 v120, v0
	v_mov_b32_e32 v121, v0
	v_mov_b32_e32 v122, v0
	v_mov_b32_e32 v123, v0
	v_mov_b32_e32 v124, v0
	v_mov_b32_e32 v125, v0
	v_mov_b32_e32 v126, v0
	v_mov_b32_e32 v127, v0
	v_add_u32_e32 v252, 0x18000, v139
.LBB0_157:
	ds_read_b128 v[150:153], v157
	ds_read_b128 v[160:163], v157 offset:1024
	ds_read_b128 v[164:167], v157 offset:2048
	ds_read_b128 v[168:171], v157 offset:3072
	ds_read_b128 v[172:175], v158
	ds_read_b128 v[176:179], v158 offset:1024
	ds_read_b128 v[180:183], v158 offset:2048
	ds_read_b128 v[184:187], v158 offset:3072
	s_add_u32 s8, s10, 0x100
	s_addc_u32 s9, s11, 0
	s_cmp_eq_u32 s60, 28
	s_cselect_b32 s59, s51, s9
	s_cselect_b32 s58, s50, s8
	s_cselect_b32 s57, s20, s55
	s_cselect_b32 s56, s21, s49
	s_add_i32 m0, s0, 0xc000
	ds_read_b128 v[188:191], v159
	global_load_lds_dwordx4 v142, s[10:11]
	s_add_i32 m0, s0, 0xe000
	ds_read_b128 v[192:195], v159 offset:1024
	global_load_lds_dwordx4 v144, s[10:11]
	ds_read_b128 v[196:199], v159 offset:2048
	ds_read_b128 v[200:203], v159 offset:3072
	ds_read_b128 v[204:207], v159 offset:4096
	ds_read_b128 v[208:211], v159 offset:5120
	ds_read_b128 v[212:215], v159 offset:6144
	ds_read_b128 v[216:219], v159 offset:7168
	s_waitcnt vmcnt(8)
	s_waitcnt lgkmcnt(0)
	s_barrier
	v_mfma_f32_16x16x32_bf16 v[124:127], v[150:153], v[188:191], v[124:127]
	v_mfma_f32_16x16x32_bf16 v[120:123], v[164:167], v[188:191], v[120:123]
	v_mfma_f32_16x16x32_bf16 v[116:119], v[150:153], v[196:199], v[116:119]
	v_mfma_f32_16x16x32_bf16 v[112:115], v[164:167], v[196:199], v[112:115]
	v_mfma_f32_16x16x32_bf16 v[108:111], v[150:153], v[204:207], v[108:111]
	v_mfma_f32_16x16x32_bf16 v[104:107], v[164:167], v[204:207], v[104:107]
	v_mfma_f32_16x16x32_bf16 v[100:103], v[150:153], v[212:215], v[100:103]
	v_mfma_f32_16x16x32_bf16 v[96:99], v[164:167], v[212:215], v[96:99]
	v_mfma_f32_16x16x32_bf16 v[124:127], v[160:163], v[192:195], v[124:127]
	v_mfma_f32_16x16x32_bf16 v[120:123], v[168:171], v[192:195], v[120:123]
	v_mfma_f32_16x16x32_bf16 v[116:119], v[160:163], v[200:203], v[116:119]
	v_mfma_f32_16x16x32_bf16 v[112:115], v[168:171], v[200:203], v[112:115]
	v_mfma_f32_16x16x32_bf16 v[108:111], v[160:163], v[208:211], v[108:111]
	v_mfma_f32_16x16x32_bf16 v[104:107], v[168:171], v[208:211], v[104:107]
	v_mfma_f32_16x16x32_bf16 v[100:103], v[160:163], v[216:219], v[100:103]
	v_mfma_f32_16x16x32_bf16 v[96:99], v[168:171], v[216:219], v[96:99]
	v_mfma_f32_16x16x32_bf16 v[60:63], v[172:175], v[188:191], v[60:63]
	v_mfma_f32_16x16x32_bf16 v[56:59], v[180:183], v[188:191], v[56:59]
	v_mfma_f32_16x16x32_bf16 v[52:55], v[172:175], v[196:199], v[52:55]
	v_mfma_f32_16x16x32_bf16 v[48:51], v[180:183], v[196:199], v[48:51]
	v_mfma_f32_16x16x32_bf16 v[44:47], v[172:175], v[204:207], v[44:47]
	v_mfma_f32_16x16x32_bf16 v[40:43], v[180:183], v[204:207], v[40:43]
	v_mfma_f32_16x16x32_bf16 v[36:39], v[172:175], v[212:215], v[36:39]
	v_mfma_f32_16x16x32_bf16 v[32:35], v[180:183], v[212:215], v[32:35]
	v_mfma_f32_16x16x32_bf16 v[60:63], v[176:179], v[192:195], v[60:63]
	v_mfma_f32_16x16x32_bf16 v[56:59], v[184:187], v[192:195], v[56:59]
	v_mfma_f32_16x16x32_bf16 v[52:55], v[176:179], v[200:203], v[52:55]
	v_mfma_f32_16x16x32_bf16 v[48:51], v[184:187], v[200:203], v[48:51]
	v_mfma_f32_16x16x32_bf16 v[44:47], v[176:179], v[208:211], v[44:47]
	v_mfma_f32_16x16x32_bf16 v[40:43], v[184:187], v[208:211], v[40:43]
	v_mfma_f32_16x16x32_bf16 v[36:39], v[176:179], v[216:219], v[36:39]
	v_mfma_f32_16x16x32_bf16 v[32:35], v[184:187], v[216:219], v[32:35]
	s_barrier
; #define PG8_STAGE(bufoff, gbase, voff) do { _Pragma("unroll") for (int _i = 0; _i < 2; ++_i) \
;         __builtin_amdgcn_global_load_lds((const unsigned*)((const char*)(gbase) + (voff)[_i]), (LAS unsigned*)(lds + (bufoff) + ldsw + _i * 8192), 16, 0, 0); } while (0)
; #define PG8_LDA(dst, b, h) do { _Pragma("unroll") for (int m = 0; m < 4; ++m) _Pragma("unroll") for (int k = 0; k < 2; ++k) dst[m][k] = *(const LAS bf16x8*)(lds + PG8_SA(b, h) + aoff + m * 2048 + k * 1024); } while (0)
; #define PG8_LDB(dst, b, h) do { _Pragma("unroll") for (int n = 0; n < 2; ++n) _Pragma("unroll") for (int k = 0; k < 2; ++k) dst[n][k] = *(const LAS bf16x8*)(lds + PG8_SB(b, h) + boff + n * 2048 + k * 1024); } while (0)
; #define PG8_MMA(ai, bj, At, Bt) do { __builtin_amdgcn_s_setprio(1); _Pragma("unroll") for (int m = 0; m < 4; ++m) _Pragma("unroll") for (int n = 0; n < 2; ++n) _Pragma("unroll") for (int k = 0; k < 2; ++k) \
;         acc[ai][bj][m][n] = __builtin_amdgcn_mfma_f32_16x16x32_bf16(Bt[n][k], At[m][k], acc[ai][bj][m][n], 0, 0, 0); __builtin_amdgcn_s_setprio(0); } while (0)
; #define PG8_WAIT_V(n) asm volatile("s_waitcnt vmcnt(" #n ")" ::: "memory")
; #define PG8_WAIT_L(n) asm volatile("s_waitcnt lgkmcnt(" #n ")" ::: "memory")
; #define PG8_BAR __builtin_amdgcn_s_barrier()
; #define PG8_SCHED __builtin_amdgcn_sched_barrier(0)
; template <class Epi>
; __device__ __forceinline__ void gemm_phase(LAS unsigned char* lds, const Gemm g, const StaticOrder& S, const Epi& E, const int wid) {
;     ...
;             PG8_LDA(At, 0, 1); PG8_STAGE(PG8_SB(0, 0), b2, voffB); PG8_STAGE(PG8_SB(0, 1), b2 + hstepB, voffB); PG8_STAGE(PG8_SA(0, 0), a2, voffA);
;             PG8_WAIT_V(8); PG8_WAIT_L(0); PG8_BAR; PG8_MMA(1, 0, At, B0); PG8_MMA(1, 1, At, B1); PG8_BAR; PG8_SCHED;
;             PG8_LDB(B0, 1, 0); PG8_LDB(B1, 1, 1); PG8_SCHED; PG8_LDA(At, 1, 0); PG8_STAGE(PG8_SA(0, 1), a2 + hstepA, voffA);
;             PG8_WAIT_V(8); PG8_WAIT_L(0); PG8_BAR; PG8_MMA(0, 0, At, B0); PG8_MMA(0, 1, At, B1); PG8_BAR; PG8_SCHED;
	s_add_i32 s10, s68, s94
	s_mov_b32 m0, s10
	ds_read_b128 v[188:191], v159 offset:16384
	global_load_lds_dwordx4 v130, s[56:57]
	s_add_i32 m0, s10, 0x2000
	s_add_u32 s10, s56, 0x80000
	s_addc_u32 s11, s57, 0
	s_add_i32 s24, s69, s94
	global_load_lds_dwordx4 v134, s[56:57]
	s_mov_b32 m0, s24
	ds_read_b128 v[192:195], v159 offset:17408
	global_load_lds_dwordx4 v130, s[10:11]
	s_add_i32 m0, s24, 0x2000
	ds_read_b128 v[196:199], v159 offset:18432
	global_load_lds_dwordx4 v134, s[10:11]
	s_mov_b32 m0, s0
	ds_read_b128 v[200:203], v159 offset:19456
	global_load_lds_dwordx4 v128, s[58:59]
	s_mov_b32 m0, s1
	ds_read_b128 v[204:207], v159 offset:20480
	global_load_lds_dwordx4 v132, s[58:59]
	ds_read_b128 v[208:211], v159 offset:21504
	ds_read_b128 v[212:215], v159 offset:22528
	ds_read_b128 v[216:219], v159 offset:23552
	s_waitcnt vmcnt(8)
	s_waitcnt lgkmcnt(0)
	s_barrier
	v_mfma_f32_16x16x32_bf16 v[92:95], v[150:153], v[188:191], v[92:95]
	v_mfma_f32_16x16x32_bf16 v[88:91], v[164:167], v[188:191], v[88:91]
	v_mfma_f32_16x16x32_bf16 v[84:87], v[150:153], v[196:199], v[84:87]
	v_mfma_f32_16x16x32_bf16 v[80:83], v[164:167], v[196:199], v[80:83]
	v_mfma_f32_16x16x32_bf16 v[76:79], v[150:153], v[204:207], v[76:79]
	v_mfma_f32_16x16x32_bf16 v[72:75], v[164:167], v[204:207], v[72:75]
	v_mfma_f32_16x16x32_bf16 v[68:71], v[150:153], v[212:215], v[68:71]
	v_mfma_f32_16x16x32_bf16 v[64:67], v[164:167], v[212:215], v[64:67]
	v_mfma_f32_16x16x32_bf16 v[92:95], v[160:163], v[192:195], v[92:95]
	v_mfma_f32_16x16x32_bf16 v[88:91], v[168:171], v[192:195], v[88:91]
	v_mfma_f32_16x16x32_bf16 v[84:87], v[160:163], v[200:203], v[84:87]
	v_mfma_f32_16x16x32_bf16 v[80:83], v[168:171], v[200:203], v[80:83]
	v_mfma_f32_16x16x32_bf16 v[76:79], v[160:163], v[208:211], v[76:79]
	v_mfma_f32_16x16x32_bf16 v[72:75], v[168:171], v[208:211], v[72:75]
	v_mfma_f32_16x16x32_bf16 v[68:71], v[160:163], v[216:219], v[68:71]
	v_mfma_f32_16x16x32_bf16 v[64:67], v[168:171], v[216:219], v[64:67]
	v_mfma_f32_16x16x32_bf16 v[28:31], v[172:175], v[188:191], v[28:31]
	v_mfma_f32_16x16x32_bf16 v[24:27], v[180:183], v[188:191], v[24:27]
	v_mfma_f32_16x16x32_bf16 v[20:23], v[172:175], v[196:199], v[20:23]
	v_mfma_f32_16x16x32_bf16 v[16:19], v[180:183], v[196:199], v[16:19]
	v_mfma_f32_16x16x32_bf16 v[12:15], v[172:175], v[204:207], v[12:15]
	v_mfma_f32_16x16x32_bf16 v[8:11], v[180:183], v[204:207], v[8:11]
	v_mfma_f32_16x16x32_bf16 v[4:7], v[172:175], v[212:215], v[4:7]
	v_mfma_f32_16x16x32_bf16 v[0:3], v[180:183], v[212:215], v[0:3]
	v_mfma_f32_16x16x32_bf16 v[28:31], v[176:179], v[192:195], v[28:31]
	v_mfma_f32_16x16x32_bf16 v[24:27], v[184:187], v[192:195], v[24:27]
	v_mfma_f32_16x16x32_bf16 v[20:23], v[176:179], v[200:203], v[20:23]
	v_mfma_f32_16x16x32_bf16 v[16:19], v[184:187], v[200:203], v[16:19]
	v_mfma_f32_16x16x32_bf16 v[12:15], v[176:179], v[208:211], v[12:15]
	v_mfma_f32_16x16x32_bf16 v[8:11], v[184:187], v[208:211], v[8:11]
	v_mfma_f32_16x16x32_bf16 v[4:7], v[176:179], v[216:219], v[4:7]
	v_mfma_f32_16x16x32_bf16 v[0:3], v[184:187], v[216:219], v[0:3]
	s_barrier
	s_add_i32 s24, 0, 0x18000
	s_add_i32 s25, 0, 0x1c000
	ds_read_b128 v[150:153], v252
	ds_read_b128 v[160:163], v252 offset:1024
	ds_read_b128 v[164:167], v252 offset:2048
	ds_read_b128 v[168:171], v252 offset:3072
	ds_read_b128 v[172:175], v252 offset:16384
	ds_read_b128 v[176:179], v252 offset:17408
	ds_read_b128 v[180:183], v252 offset:18432
	ds_read_b128 v[184:187], v252 offset:19456
	s_add_u32 s10, s58, 0x80000
	s_addc_u32 s11, s59, 0
	s_mov_b32 m0, s15
	ds_read_b128 v[188:191], v159 offset:32768
	global_load_lds_dwordx4 v128, s[10:11]
	s_mov_b32 m0, s26
	ds_read_b128 v[192:195], v159 offset:33792
	global_load_lds_dwordx4 v132, s[10:11]
	ds_read_b128 v[196:199], v159 offset:34816
	ds_read_b128 v[200:203], v159 offset:35840
	ds_read_b128 v[204:207], v159 offset:36864
	ds_read_b128 v[208:211], v159 offset:37888
	ds_read_b128 v[212:215], v159 offset:38912
	ds_read_b128 v[216:219], v159 offset:39936
	s_waitcnt vmcnt(8)
	s_waitcnt lgkmcnt(0)
	s_barrier
; #define PG8_STAGE(bufoff, gbase, voff) do { _Pragma("unroll") for (int _i = 0; _i < 2; ++_i) \
;         __builtin_amdgcn_global_load_lds((const unsigned*)((const char*)(gbase) + (voff)[_i]), (LAS unsigned*)(lds + (bufoff) + ldsw + _i * 8192), 16, 0, 0); } while (0)
; #define PG8_LDA(dst, b, h) do { _Pragma("unroll") for (int m = 0; m < 4; ++m) _Pragma("unroll") for (int k = 0; k < 2; ++k) dst[m][k] = *(const LAS bf16x8*)(lds + PG8_SA(b, h) + aoff + m * 2048 + k * 1024); } while (0)
; #define PG8_MMA(ai, bj, At, Bt) do { __builtin_amdgcn_s_setprio(1); _Pragma("unroll") for (int m = 0; m < 4; ++m) _Pragma("unroll") for (int n = 0; n < 2; ++n) _Pragma("unroll") for (int k = 0; k < 2; ++k) \
;         acc[ai][bj][m][n] = __builtin_amdgcn_mfma_f32_16x16x32_bf16(Bt[n][k], At[m][k], acc[ai][bj][m][n], 0, 0, 0); __builtin_amdgcn_s_setprio(0); } while (0)
; #define PG8_WAIT_V(n) asm volatile("s_waitcnt vmcnt(" #n ")" ::: "memory")
; #define PG8_WAIT_L(n) asm volatile("s_waitcnt lgkmcnt(" #n ")" ::: "memory")
; #define PG8_BAR __builtin_amdgcn_s_barrier()
; #define PG8_SCHED __builtin_amdgcn_sched_barrier(0)
; template <class Epi>
; __device__ __forceinline__ void gemm_phase(LAS unsigned char* lds, const Gemm g, const StaticOrder& S, const Epi& E, const int wid) {
;     ...
;             PG8_WAIT_V(8); PG8_WAIT_L(0); PG8_BAR; PG8_MMA(0, 0, At, B0); PG8_MMA(0, 1, At, B1); PG8_BAR; PG8_SCHED;
;             PG8_LDA(At, 1, 1); PG8_STAGE(PG8_SB(1, 0), b3, voffB); PG8_STAGE(PG8_SB(1, 1), b3 + hstepB, voffB); PG8_STAGE(PG8_SA(1, 0), a3, voffA);
;             PG8_WAIT_V(8); PG8_WAIT_L(0); PG8_BAR; PG8_MMA(1, 0, At, B0); PG8_MMA(1, 1, At, B1); PG8_BAR; PG8_SCHED;
;         }
;         if (wr == 0) PG8_BAR;
	v_mfma_f32_16x16x32_bf16 v[124:127], v[150:153], v[188:191], v[124:127]
	v_mfma_f32_16x16x32_bf16 v[120:123], v[164:167], v[188:191], v[120:123]
	v_mfma_f32_16x16x32_bf16 v[116:119], v[150:153], v[196:199], v[116:119]
	v_mfma_f32_16x16x32_bf16 v[112:115], v[164:167], v[196:199], v[112:115]
	v_mfma_f32_16x16x32_bf16 v[108:111], v[150:153], v[204:207], v[108:111]
	v_mfma_f32_16x16x32_bf16 v[104:107], v[164:167], v[204:207], v[104:107]
	v_mfma_f32_16x16x32_bf16 v[100:103], v[150:153], v[212:215], v[100:103]
	v_mfma_f32_16x16x32_bf16 v[96:99], v[164:167], v[212:215], v[96:99]
	v_mfma_f32_16x16x32_bf16 v[124:127], v[160:163], v[192:195], v[124:127]
	v_mfma_f32_16x16x32_bf16 v[120:123], v[168:171], v[192:195], v[120:123]
	v_mfma_f32_16x16x32_bf16 v[116:119], v[160:163], v[200:203], v[116:119]
	v_mfma_f32_16x16x32_bf16 v[112:115], v[168:171], v[200:203], v[112:115]
	v_mfma_f32_16x16x32_bf16 v[108:111], v[160:163], v[208:211], v[108:111]
	v_mfma_f32_16x16x32_bf16 v[104:107], v[168:171], v[208:211], v[104:107]
	v_mfma_f32_16x16x32_bf16 v[100:103], v[160:163], v[216:219], v[100:103]
	v_mfma_f32_16x16x32_bf16 v[96:99], v[168:171], v[216:219], v[96:99]
	v_mfma_f32_16x16x32_bf16 v[60:63], v[172:175], v[188:191], v[60:63]
	v_mfma_f32_16x16x32_bf16 v[56:59], v[180:183], v[188:191], v[56:59]
	v_mfma_f32_16x16x32_bf16 v[52:55], v[172:175], v[196:199], v[52:55]
	v_mfma_f32_16x16x32_bf16 v[48:51], v[180:183], v[196:199], v[48:51]
	v_mfma_f32_16x16x32_bf16 v[44:47], v[172:175], v[204:207], v[44:47]
	v_mfma_f32_16x16x32_bf16 v[40:43], v[180:183], v[204:207], v[40:43]
	v_mfma_f32_16x16x32_bf16 v[36:39], v[172:175], v[212:215], v[36:39]
	v_mfma_f32_16x16x32_bf16 v[32:35], v[180:183], v[212:215], v[32:35]
	v_mfma_f32_16x16x32_bf16 v[60:63], v[176:179], v[192:195], v[60:63]
	v_mfma_f32_16x16x32_bf16 v[56:59], v[184:187], v[192:195], v[56:59]
	v_mfma_f32_16x16x32_bf16 v[52:55], v[176:179], v[200:203], v[52:55]
	v_mfma_f32_16x16x32_bf16 v[48:51], v[184:187], v[200:203], v[48:51]
	v_mfma_f32_16x16x32_bf16 v[44:47], v[176:179], v[208:211], v[44:47]
	v_mfma_f32_16x16x32_bf16 v[40:43], v[184:187], v[208:211], v[40:43]
	v_mfma_f32_16x16x32_bf16 v[36:39], v[176:179], v[216:219], v[36:39]
	v_mfma_f32_16x16x32_bf16 v[32:35], v[184:187], v[216:219], v[32:35]
	s_barrier
	s_add_i32 s10, s24, s94
	s_add_u32 s98, s56, 0x80
	s_addc_u32 s99, s57, 0
	s_mov_b32 m0, s10
	ds_read_b128 v[188:191], v159 offset:49152
	global_load_lds_dwordx4 v130, s[98:99]
	s_add_i32 m0, s10, 0x2000
	s_add_u32 s10, s56, 0x80080
	s_addc_u32 s11, s57, 0
	s_add_i32 s24, s25, s94
	global_load_lds_dwordx4 v134, s[98:99]
	s_mov_b32 m0, s24
	ds_read_b128 v[192:195], v159 offset:50176
	global_load_lds_dwordx4 v130, s[10:11]
	s_add_i32 m0, s24, 0x2000
	ds_read_b128 v[196:199], v159 offset:51200
	global_load_lds_dwordx4 v134, s[10:11]
	s_add_u32 s100, s58, 0x80
	s_addc_u32 s101, s59, 0
	s_mov_b32 m0, s66
	ds_read_b128 v[200:203], v159 offset:52224
	global_load_lds_dwordx4 v128, s[100:101]
	s_mov_b32 m0, s67
	ds_read_b128 v[204:207], v159 offset:53248
	global_load_lds_dwordx4 v132, s[100:101]
	ds_read_b128 v[208:211], v159 offset:54272
	ds_read_b128 v[212:215], v159 offset:55296
	ds_read_b128 v[216:219], v159 offset:56320
	s_waitcnt vmcnt(8)
	s_waitcnt lgkmcnt(0)
	s_barrier
	v_mfma_f32_16x16x32_bf16 v[92:95], v[150:153], v[188:191], v[92:95]
	v_mfma_f32_16x16x32_bf16 v[88:91], v[164:167], v[188:191], v[88:91]
	v_mfma_f32_16x16x32_bf16 v[84:87], v[150:153], v[196:199], v[84:87]
	v_mfma_f32_16x16x32_bf16 v[80:83], v[164:167], v[196:199], v[80:83]
	v_mfma_f32_16x16x32_bf16 v[76:79], v[150:153], v[204:207], v[76:79]
	v_mfma_f32_16x16x32_bf16 v[72:75], v[164:167], v[204:207], v[72:75]
	v_mfma_f32_16x16x32_bf16 v[68:71], v[150:153], v[212:215], v[68:71]
	v_mfma_f32_16x16x32_bf16 v[64:67], v[164:167], v[212:215], v[64:67]
	v_mfma_f32_16x16x32_bf16 v[92:95], v[160:163], v[192:195], v[92:95]
	v_mfma_f32_16x16x32_bf16 v[88:91], v[168:171], v[192:195], v[88:91]
	v_mfma_f32_16x16x32_bf16 v[84:87], v[160:163], v[200:203], v[84:87]
	v_mfma_f32_16x16x32_bf16 v[80:83], v[168:171], v[200:203], v[80:83]
	v_mfma_f32_16x16x32_bf16 v[76:79], v[160:163], v[208:211], v[76:79]
	v_mfma_f32_16x16x32_bf16 v[72:75], v[168:171], v[208:211], v[72:75]
	v_mfma_f32_16x16x32_bf16 v[68:71], v[160:163], v[216:219], v[68:71]
	v_mfma_f32_16x16x32_bf16 v[64:67], v[168:171], v[216:219], v[64:67]
	v_mfma_f32_16x16x32_bf16 v[28:31], v[172:175], v[188:191], v[28:31]
	v_mfma_f32_16x16x32_bf16 v[24:27], v[180:183], v[188:191], v[24:27]
	v_mfma_f32_16x16x32_bf16 v[20:23], v[172:175], v[196:199], v[20:23]
	v_mfma_f32_16x16x32_bf16 v[16:19], v[180:183], v[196:199], v[16:19]
	v_mfma_f32_16x16x32_bf16 v[12:15], v[172:175], v[204:207], v[12:15]
	v_mfma_f32_16x16x32_bf16 v[8:11], v[180:183], v[204:207], v[8:11]
	v_mfma_f32_16x16x32_bf16 v[4:7], v[172:175], v[212:215], v[4:7]
	v_mfma_f32_16x16x32_bf16 v[0:3], v[180:183], v[212:215], v[0:3]
	v_mfma_f32_16x16x32_bf16 v[28:31], v[176:179], v[192:195], v[28:31]
	v_mfma_f32_16x16x32_bf16 v[24:27], v[184:187], v[192:195], v[24:27]
	v_mfma_f32_16x16x32_bf16 v[20:23], v[176:179], v[200:203], v[20:23]
	v_mfma_f32_16x16x32_bf16 v[16:19], v[184:187], v[200:203], v[16:19]
	v_mfma_f32_16x16x32_bf16 v[12:15], v[176:179], v[208:211], v[12:15]
	v_mfma_f32_16x16x32_bf16 v[8:11], v[184:187], v[208:211], v[8:11]
	v_mfma_f32_16x16x32_bf16 v[4:7], v[176:179], v[216:219], v[4:7]
	v_mfma_f32_16x16x32_bf16 v[0:3], v[184:187], v[216:219], v[0:3]
	s_barrier
	s_add_i32 s60, s60, 2
	s_add_u32 s49, s49, 0x100
	s_addc_u32 s55, s55, 0
	s_cmp_gt_u32 s60, 29
	s_mov_b64 s[10:11], s[8:9]
	s_cbranch_scc0 .LBB0_157
	s_and_b64 vcc, exec, s[22:23]
	s_cbranch_vccz .LBB0_160
	s_barrier

; #define PG8_STAGE(bufoff, gbase, voff) do { _Pragma("unroll") for (int _i = 0; _i < 2; ++_i) \
;         __builtin_amdgcn_global_load_lds((const unsigned*)((const char*)(gbase) + (voff)[_i]), (LAS unsigned*)(lds + (bufoff) + ldsw + _i * 8192), 16, 0, 0); } while (0)
; #define PG8_LDA(dst, b, h) do { _Pragma("unroll") for (int m = 0; m < 4; ++m) _Pragma("unroll") for (int k = 0; k < 2; ++k) dst[m][k] = *(const LAS bf16x8*)(lds + PG8_SA(b, h) + aoff + m * 2048 + k * 1024); } while (0)
; #define PG8_LDB(dst, b, h) do { _Pragma("unroll") for (int n = 0; n < 2; ++n) _Pragma("unroll") for (int k = 0; k < 2; ++k) dst[n][k] = *(const LAS bf16x8*)(lds + PG8_SB(b, h) + boff + n * 2048 + k * 1024); } while (0)
; #define PG8_MMA(ai, bj, At, Bt) do { __builtin_amdgcn_s_setprio(1); _Pragma("unroll") for (int m = 0; m < 4; ++m) _Pragma("unroll") for (int n = 0; n < 2; ++n) _Pragma("unroll") for (int k = 0; k < 2; ++k) \
;         acc[ai][bj][m][n] = __builtin_amdgcn_mfma_f32_16x16x32_bf16(Bt[n][k], At[m][k], acc[ai][bj][m][n], 0, 0, 0); __builtin_amdgcn_s_setprio(0); } while (0)
; #define PG8_WAIT_V(n) asm volatile("s_waitcnt vmcnt(" #n ")" ::: "memory")
; #define PG8_WAIT_L(n) asm volatile("s_waitcnt lgkmcnt(" #n ")" ::: "memory")
; #define PG8_BAR __builtin_amdgcn_s_barrier()
; #define PG8_SCHED __builtin_amdgcn_sched_barrier(0)
; template <class Epi>
; __device__ __forceinline__ void gemm_phase(LAS unsigned char* lds, const Gemm g, const StaticOrder& S, const Epi& E, const int wid) {
;     ...
;     for (;;) {
;         const bool has_next = S.next(ui + 1, nxt);
;         const char* nA = has_next ? PG8_TILEA(nxt.pm) : cA; const char* nB = has_next ? PG8_TILEB(nxt.pn) : cB;
;         for (int t = 0; t < nt; t += 2) {
;             const bool last = (t == nt - 2);
;             const char* a1 = cA + (size_t)(t + 1) * kstep;
;             const char* a2 = last ? nA : cA + (size_t)(t + 2) * kstep; const char* b2 = last ? nB : cB + (size_t)(t + 2) * kstep;
;             const char* a3 = a2 + kstep; const char* b3 = b2 + kstep;
;             PG8_LDB(B0, 0, 0); PG8_LDB(B1, 0, 1); PG8_SCHED; PG8_LDA(At, 0, 0); PG8_STAGE(PG8_SA(1, 1), a1 + hstepA, voffA);
;             PG8_WAIT_V(8); PG8_WAIT_L(0); PG8_BAR; PG8_MMA(0, 0, At, B0); PG8_MMA(0, 1, At, B1); PG8_BAR; PG8_SCHED;
.LBB0_1668:
	s_ashr_i32 s11, s10, 31
	s_lshl_b64 s[24:25], s[10:11], 19
	v_readlane_b32 s11, v251, 12
	s_add_u32 s44, s11, s24
	v_readlane_b32 s11, v251, 13
	s_addc_u32 s45, s11, s25
	s_and_b64 s[6:7], s[6:7], exec
	s_cselect_b32 s11, s45, s49
	s_cselect_b32 s21, s44, s48
	s_add_u32 s53, s48, 0x100
	v_mov_b32_e32 v0, 0
	s_addc_u32 s54, s49, 0
	s_mov_b32 s55, -2
	v_mov_b32_e32 v1, v0
	v_mov_b32_e32 v2, v0
	v_mov_b32_e32 v3, v0
	v_mov_b32_e32 v4, v0
	v_mov_b32_e32 v5, v0
	v_mov_b32_e32 v6, v0
	v_mov_b32_e32 v7, v0
	v_mov_b32_e32 v8, v0
	v_mov_b32_e32 v9, v0
	v_mov_b32_e32 v10, v0
	v_mov_b32_e32 v11, v0
	v_mov_b32_e32 v12, v0
	v_mov_b32_e32 v13, v0
	v_mov_b32_e32 v14, v0
	v_mov_b32_e32 v15, v0
	v_mov_b32_e32 v16, v0
	v_mov_b32_e32 v17, v0
	v_mov_b32_e32 v18, v0
	v_mov_b32_e32 v19, v0
	v_mov_b32_e32 v20, v0
	v_mov_b32_e32 v21, v0
	v_mov_b32_e32 v22, v0
	v_mov_b32_e32 v23, v0
	v_mov_b32_e32 v24, v0
	v_mov_b32_e32 v25, v0
	v_mov_b32_e32 v26, v0
	v_mov_b32_e32 v27, v0
	v_mov_b32_e32 v28, v0
	v_mov_b32_e32 v29, v0
	v_mov_b32_e32 v30, v0
	v_mov_b32_e32 v31, v0
	v_mov_b32_e32 v56, v0
	v_mov_b32_e32 v57, v0
	v_mov_b32_e32 v58, v0
	v_mov_b32_e32 v59, v0
	v_mov_b32_e32 v64, v0
	v_mov_b32_e32 v65, v0
	v_mov_b32_e32 v66, v0
	v_mov_b32_e32 v67, v0
	v_mov_b32_e32 v72, v0
	v_mov_b32_e32 v73, v0
	v_mov_b32_e32 v74, v0
	v_mov_b32_e32 v75, v0
	v_mov_b32_e32 v76, v0
	v_mov_b32_e32 v77, v0
	v_mov_b32_e32 v78, v0
	v_mov_b32_e32 v79, v0
	v_mov_b32_e32 v80, v0
	v_mov_b32_e32 v81, v0
	v_mov_b32_e32 v82, v0
	v_mov_b32_e32 v83, v0
	v_mov_b32_e32 v84, v0
	v_mov_b32_e32 v85, v0
	v_mov_b32_e32 v86, v0
	v_mov_b32_e32 v87, v0
	v_mov_b32_e32 v88, v0
	v_mov_b32_e32 v89, v0
	v_mov_b32_e32 v90, v0
	v_mov_b32_e32 v91, v0
	v_mov_b32_e32 v92, v0
	v_mov_b32_e32 v93, v0
	v_mov_b32_e32 v94, v0
	v_mov_b32_e32 v95, v0
	v_mov_b32_e32 v32, v0
	v_mov_b32_e32 v33, v0
	v_mov_b32_e32 v34, v0
	v_mov_b32_e32 v35, v0
	v_mov_b32_e32 v36, v0
	v_mov_b32_e32 v37, v0
	v_mov_b32_e32 v38, v0
	v_mov_b32_e32 v39, v0
	v_mov_b32_e32 v40, v0
	v_mov_b32_e32 v41, v0
	v_mov_b32_e32 v42, v0
	v_mov_b32_e32 v43, v0
	v_mov_b32_e32 v44, v0
	v_mov_b32_e32 v45, v0
	v_mov_b32_e32 v46, v0
	v_mov_b32_e32 v47, v0
	v_mov_b32_e32 v48, v0
	v_mov_b32_e32 v49, v0
	v_mov_b32_e32 v50, v0
	v_mov_b32_e32 v51, v0
	v_mov_b32_e32 v52, v0
	v_mov_b32_e32 v53, v0
	v_mov_b32_e32 v54, v0
	v_mov_b32_e32 v55, v0
	v_mov_b32_e32 v60, v0
	v_mov_b32_e32 v61, v0
	v_mov_b32_e32 v62, v0
	v_mov_b32_e32 v63, v0
	v_mov_b32_e32 v68, v0
	v_mov_b32_e32 v69, v0
	v_mov_b32_e32 v70, v0
	v_mov_b32_e32 v71, v0
	v_mov_b32_e32 v96, v0
	v_mov_b32_e32 v97, v0
	v_mov_b32_e32 v98, v0
	v_mov_b32_e32 v99, v0
	v_mov_b32_e32 v100, v0
	v_mov_b32_e32 v101, v0
	v_mov_b32_e32 v102, v0
	v_mov_b32_e32 v103, v0
	v_mov_b32_e32 v104, v0
	v_mov_b32_e32 v105, v0
	v_mov_b32_e32 v106, v0
	v_mov_b32_e32 v107, v0
	v_mov_b32_e32 v108, v0
	v_mov_b32_e32 v109, v0
	v_mov_b32_e32 v110, v0
	v_mov_b32_e32 v111, v0
	v_mov_b32_e32 v112, v0
	v_mov_b32_e32 v113, v0
	v_mov_b32_e32 v114, v0
	v_mov_b32_e32 v115, v0
	v_mov_b32_e32 v116, v0
	v_mov_b32_e32 v117, v0
	v_mov_b32_e32 v118, v0
	v_mov_b32_e32 v119, v0
	v_mov_b32_e32 v120, v0
	v_mov_b32_e32 v121, v0
	v_mov_b32_e32 v122, v0
	v_mov_b32_e32 v123, v0
	v_mov_b32_e32 v124, v0
	v_mov_b32_e32 v125, v0
	v_mov_b32_e32 v126, v0
	v_mov_b32_e32 v127, v0
	v_add_u32_e32 v252, 0x18000, v154
.LBB0_1669:
	ds_read_b128 v[144:147], v157
	ds_read_b128 v[148:151], v157 offset:1024
	ds_read_b128 v[160:163], v157 offset:2048
	ds_read_b128 v[164:167], v157 offset:3072
	ds_read_b128 v[168:171], v158
	ds_read_b128 v[172:175], v158 offset:1024
	ds_read_b128 v[176:179], v158 offset:2048
	ds_read_b128 v[180:183], v158 offset:3072
	s_add_u32 s6, s46, 0x100
	s_addc_u32 s7, s47, 0
	s_cmp_eq_u32 s55, 12
	s_cselect_b32 s51, s43, s7
	s_cselect_b32 s50, s42, s6
	s_cselect_b32 s49, s11, s54
	s_cselect_b32 s48, s21, s53
	s_add_i32 m0, s0, 0xc000
	ds_read_b128 v[184:187], v159
	global_load_lds_dwordx4 v136, s[46:47]
	s_add_i32 m0, s0, 0xe000
	ds_read_b128 v[188:191], v159 offset:1024
	global_load_lds_dwordx4 v138, s[46:47]
	ds_read_b128 v[192:195], v159 offset:2048
	ds_read_b128 v[196:199], v159 offset:3072
	ds_read_b128 v[200:203], v159 offset:4096
	ds_read_b128 v[204:207], v159 offset:5120
	ds_read_b128 v[208:211], v159 offset:6144
	ds_read_b128 v[212:215], v159 offset:7168
	s_waitcnt vmcnt(8)
	s_waitcnt lgkmcnt(0)
	s_barrier
	v_mfma_f32_16x16x32_bf16 v[124:127], v[144:147], v[184:187], v[124:127]
	v_mfma_f32_16x16x32_bf16 v[120:123], v[160:163], v[184:187], v[120:123]
	v_mfma_f32_16x16x32_bf16 v[116:119], v[144:147], v[192:195], v[116:119]
	v_mfma_f32_16x16x32_bf16 v[112:115], v[160:163], v[192:195], v[112:115]
	v_mfma_f32_16x16x32_bf16 v[108:111], v[144:147], v[200:203], v[108:111]
	v_mfma_f32_16x16x32_bf16 v[104:107], v[160:163], v[200:203], v[104:107]
	v_mfma_f32_16x16x32_bf16 v[100:103], v[144:147], v[208:211], v[100:103]
	v_mfma_f32_16x16x32_bf16 v[96:99], v[160:163], v[208:211], v[96:99]
	v_mfma_f32_16x16x32_bf16 v[124:127], v[148:151], v[188:191], v[124:127]
	v_mfma_f32_16x16x32_bf16 v[120:123], v[164:167], v[188:191], v[120:123]
	v_mfma_f32_16x16x32_bf16 v[116:119], v[148:151], v[196:199], v[116:119]
	v_mfma_f32_16x16x32_bf16 v[112:115], v[164:167], v[196:199], v[112:115]
	v_mfma_f32_16x16x32_bf16 v[108:111], v[148:151], v[204:207], v[108:111]
	v_mfma_f32_16x16x32_bf16 v[104:107], v[164:167], v[204:207], v[104:107]
	v_mfma_f32_16x16x32_bf16 v[100:103], v[148:151], v[212:215], v[100:103]
	v_mfma_f32_16x16x32_bf16 v[96:99], v[164:167], v[212:215], v[96:99]
	v_mfma_f32_16x16x32_bf16 v[68:71], v[168:171], v[184:187], v[68:71]
	v_mfma_f32_16x16x32_bf16 v[60:63], v[176:179], v[184:187], v[60:63]
	v_mfma_f32_16x16x32_bf16 v[52:55], v[168:171], v[192:195], v[52:55]
	v_mfma_f32_16x16x32_bf16 v[48:51], v[176:179], v[192:195], v[48:51]
	v_mfma_f32_16x16x32_bf16 v[44:47], v[168:171], v[200:203], v[44:47]
	v_mfma_f32_16x16x32_bf16 v[40:43], v[176:179], v[200:203], v[40:43]
	v_mfma_f32_16x16x32_bf16 v[36:39], v[168:171], v[208:211], v[36:39]
	v_mfma_f32_16x16x32_bf16 v[32:35], v[176:179], v[208:211], v[32:35]
	v_mfma_f32_16x16x32_bf16 v[68:71], v[172:175], v[188:191], v[68:71]
	v_mfma_f32_16x16x32_bf16 v[60:63], v[180:183], v[188:191], v[60:63]
	v_mfma_f32_16x16x32_bf16 v[52:55], v[172:175], v[196:199], v[52:55]
	v_mfma_f32_16x16x32_bf16 v[48:51], v[180:183], v[196:199], v[48:51]
	v_mfma_f32_16x16x32_bf16 v[44:47], v[172:175], v[204:207], v[44:47]
	v_mfma_f32_16x16x32_bf16 v[40:43], v[180:183], v[204:207], v[40:43]
	v_mfma_f32_16x16x32_bf16 v[36:39], v[172:175], v[212:215], v[36:39]
	v_mfma_f32_16x16x32_bf16 v[32:35], v[180:183], v[212:215], v[32:35]
	s_barrier
; #define PG8_STAGE(bufoff, gbase, voff) do { _Pragma("unroll") for (int _i = 0; _i < 2; ++_i) \
;         __builtin_amdgcn_global_load_lds((const unsigned*)((const char*)(gbase) + (voff)[_i]), (LAS unsigned*)(lds + (bufoff) + ldsw + _i * 8192), 16, 0, 0); } while (0)
; #define PG8_LDA(dst, b, h) do { _Pragma("unroll") for (int m = 0; m < 4; ++m) _Pragma("unroll") for (int k = 0; k < 2; ++k) dst[m][k] = *(const LAS bf16x8*)(lds + PG8_SA(b, h) + aoff + m * 2048 + k * 1024); } while (0)
; #define PG8_LDB(dst, b, h) do { _Pragma("unroll") for (int n = 0; n < 2; ++n) _Pragma("unroll") for (int k = 0; k < 2; ++k) dst[n][k] = *(const LAS bf16x8*)(lds + PG8_SB(b, h) + boff + n * 2048 + k * 1024); } while (0)
; #define PG8_MMA(ai, bj, At, Bt) do { __builtin_amdgcn_s_setprio(1); _Pragma("unroll") for (int m = 0; m < 4; ++m) _Pragma("unroll") for (int n = 0; n < 2; ++n) _Pragma("unroll") for (int k = 0; k < 2; ++k) \
;         acc[ai][bj][m][n] = __builtin_amdgcn_mfma_f32_16x16x32_bf16(Bt[n][k], At[m][k], acc[ai][bj][m][n], 0, 0, 0); __builtin_amdgcn_s_setprio(0); } while (0)
; #define PG8_WAIT_V(n) asm volatile("s_waitcnt vmcnt(" #n ")" ::: "memory")
; #define PG8_WAIT_L(n) asm volatile("s_waitcnt lgkmcnt(" #n ")" ::: "memory")
; #define PG8_BAR __builtin_amdgcn_s_barrier()
; #define PG8_SCHED __builtin_amdgcn_sched_barrier(0)
; template <class Epi>
; __device__ __forceinline__ void gemm_phase(LAS unsigned char* lds, const Gemm g, const StaticOrder& S, const Epi& E, const int wid) {
;     ...
;             PG8_LDA(At, 0, 1); PG8_STAGE(PG8_SB(0, 0), b2, voffB); PG8_STAGE(PG8_SB(0, 1), b2 + hstepB, voffB); PG8_STAGE(PG8_SA(0, 0), a2, voffA);
;             PG8_WAIT_V(8); PG8_WAIT_L(0); PG8_BAR; PG8_MMA(1, 0, At, B0); PG8_MMA(1, 1, At, B1); PG8_BAR; PG8_SCHED;
;             PG8_LDB(B0, 1, 0); PG8_LDB(B1, 1, 1); PG8_SCHED; PG8_LDA(At, 1, 0); PG8_STAGE(PG8_SA(0, 1), a2 + hstepA, voffA);
;             PG8_WAIT_V(8); PG8_WAIT_L(0); PG8_BAR; PG8_MMA(0, 0, At, B0); PG8_MMA(0, 1, At, B1); PG8_BAR; PG8_SCHED;
	s_add_i32 s24, s36, s94
	s_mov_b32 m0, s24
	ds_read_b128 v[184:187], v159 offset:16384
	global_load_lds_dwordx4 v132, s[48:49]
	s_add_i32 m0, s24, 0x2000
	s_add_u32 s24, s48, 0x40000
	s_addc_u32 s25, s49, 0
	s_add_i32 s46, s37, s94
	global_load_lds_dwordx4 v128, s[48:49]
	s_mov_b32 m0, s46
	ds_read_b128 v[188:191], v159 offset:17408
	global_load_lds_dwordx4 v132, s[24:25]
	s_add_i32 m0, s46, 0x2000
	ds_read_b128 v[192:195], v159 offset:18432
	global_load_lds_dwordx4 v128, s[24:25]
	s_mov_b32 m0, s0
	ds_read_b128 v[196:199], v159 offset:19456
	global_load_lds_dwordx4 v134, s[50:51]
	s_mov_b32 m0, s1
	ds_read_b128 v[200:203], v159 offset:20480
	global_load_lds_dwordx4 v130, s[50:51]
	ds_read_b128 v[204:207], v159 offset:21504
	ds_read_b128 v[208:211], v159 offset:22528
	ds_read_b128 v[212:215], v159 offset:23552
	s_waitcnt vmcnt(8)
	s_waitcnt lgkmcnt(0)
	s_barrier
	v_mfma_f32_16x16x32_bf16 v[92:95], v[144:147], v[184:187], v[92:95]
	v_mfma_f32_16x16x32_bf16 v[88:91], v[160:163], v[184:187], v[88:91]
	v_mfma_f32_16x16x32_bf16 v[84:87], v[144:147], v[192:195], v[84:87]
	v_mfma_f32_16x16x32_bf16 v[80:83], v[160:163], v[192:195], v[80:83]
	v_mfma_f32_16x16x32_bf16 v[76:79], v[144:147], v[200:203], v[76:79]
	v_mfma_f32_16x16x32_bf16 v[72:75], v[160:163], v[200:203], v[72:75]
	v_mfma_f32_16x16x32_bf16 v[64:67], v[144:147], v[208:211], v[64:67]
	v_mfma_f32_16x16x32_bf16 v[56:59], v[160:163], v[208:211], v[56:59]
	v_mfma_f32_16x16x32_bf16 v[92:95], v[148:151], v[188:191], v[92:95]
	v_mfma_f32_16x16x32_bf16 v[88:91], v[164:167], v[188:191], v[88:91]
	v_mfma_f32_16x16x32_bf16 v[84:87], v[148:151], v[196:199], v[84:87]
	v_mfma_f32_16x16x32_bf16 v[80:83], v[164:167], v[196:199], v[80:83]
	v_mfma_f32_16x16x32_bf16 v[76:79], v[148:151], v[204:207], v[76:79]
	v_mfma_f32_16x16x32_bf16 v[72:75], v[164:167], v[204:207], v[72:75]
	v_mfma_f32_16x16x32_bf16 v[64:67], v[148:151], v[212:215], v[64:67]
	v_mfma_f32_16x16x32_bf16 v[56:59], v[164:167], v[212:215], v[56:59]
	v_mfma_f32_16x16x32_bf16 v[28:31], v[168:171], v[184:187], v[28:31]
	v_mfma_f32_16x16x32_bf16 v[24:27], v[176:179], v[184:187], v[24:27]
	v_mfma_f32_16x16x32_bf16 v[20:23], v[168:171], v[192:195], v[20:23]
	v_mfma_f32_16x16x32_bf16 v[16:19], v[176:179], v[192:195], v[16:19]
	v_mfma_f32_16x16x32_bf16 v[12:15], v[168:171], v[200:203], v[12:15]
	v_mfma_f32_16x16x32_bf16 v[8:11], v[176:179], v[200:203], v[8:11]
	v_mfma_f32_16x16x32_bf16 v[4:7], v[168:171], v[208:211], v[4:7]
	v_mfma_f32_16x16x32_bf16 v[0:3], v[176:179], v[208:211], v[0:3]
	v_mfma_f32_16x16x32_bf16 v[28:31], v[172:175], v[188:191], v[28:31]
	v_mfma_f32_16x16x32_bf16 v[24:27], v[180:183], v[188:191], v[24:27]
	v_mfma_f32_16x16x32_bf16 v[20:23], v[172:175], v[196:199], v[20:23]
	v_mfma_f32_16x16x32_bf16 v[16:19], v[180:183], v[196:199], v[16:19]
	v_mfma_f32_16x16x32_bf16 v[12:15], v[172:175], v[204:207], v[12:15]
	v_mfma_f32_16x16x32_bf16 v[8:11], v[180:183], v[204:207], v[8:11]
	v_mfma_f32_16x16x32_bf16 v[4:7], v[172:175], v[212:215], v[4:7]
	v_mfma_f32_16x16x32_bf16 v[0:3], v[180:183], v[212:215], v[0:3]
	s_barrier
	s_add_i32 s46, 0, 0x18000
	s_add_i32 s47, 0, 0x1c000
	ds_read_b128 v[144:147], v252
	ds_read_b128 v[148:151], v252 offset:1024
	ds_read_b128 v[160:163], v252 offset:2048
	ds_read_b128 v[164:167], v252 offset:3072
	ds_read_b128 v[168:171], v252 offset:16384
	ds_read_b128 v[172:175], v252 offset:17408
	ds_read_b128 v[176:179], v252 offset:18432
	ds_read_b128 v[180:183], v252 offset:19456
	s_add_u32 s24, s50, 0x40000
	s_addc_u32 s25, s51, 0
	s_mov_b32 m0, s15
	ds_read_b128 v[184:187], v159 offset:32768
	global_load_lds_dwordx4 v134, s[24:25]
	s_mov_b32 m0, s26
	ds_read_b128 v[188:191], v159 offset:33792
	global_load_lds_dwordx4 v130, s[24:25]
	ds_read_b128 v[192:195], v159 offset:34816
	ds_read_b128 v[196:199], v159 offset:35840
	ds_read_b128 v[200:203], v159 offset:36864
	ds_read_b128 v[204:207], v159 offset:37888
	ds_read_b128 v[208:211], v159 offset:38912
	ds_read_b128 v[212:215], v159 offset:39936
	s_waitcnt vmcnt(8)
	s_waitcnt lgkmcnt(0)
	s_barrier
; #define PG8_STAGE(bufoff, gbase, voff) do { _Pragma("unroll") for (int _i = 0; _i < 2; ++_i) \
;         __builtin_amdgcn_global_load_lds((const unsigned*)((const char*)(gbase) + (voff)[_i]), (LAS unsigned*)(lds + (bufoff) + ldsw + _i * 8192), 16, 0, 0); } while (0)
; #define PG8_LDA(dst, b, h) do { _Pragma("unroll") for (int m = 0; m < 4; ++m) _Pragma("unroll") for (int k = 0; k < 2; ++k) dst[m][k] = *(const LAS bf16x8*)(lds + PG8_SA(b, h) + aoff + m * 2048 + k * 1024); } while (0)
; #define PG8_MMA(ai, bj, At, Bt) do { __builtin_amdgcn_s_setprio(1); _Pragma("unroll") for (int m = 0; m < 4; ++m) _Pragma("unroll") for (int n = 0; n < 2; ++n) _Pragma("unroll") for (int k = 0; k < 2; ++k) \
;         acc[ai][bj][m][n] = __builtin_amdgcn_mfma_f32_16x16x32_bf16(Bt[n][k], At[m][k], acc[ai][bj][m][n], 0, 0, 0); __builtin_amdgcn_s_setprio(0); } while (0)
; #define PG8_WAIT_V(n) asm volatile("s_waitcnt vmcnt(" #n ")" ::: "memory")
; #define PG8_WAIT_L(n) asm volatile("s_waitcnt lgkmcnt(" #n ")" ::: "memory")
; #define PG8_BAR __builtin_amdgcn_s_barrier()
; #define PG8_SCHED __builtin_amdgcn_sched_barrier(0)
; template <class Epi>
; __device__ __forceinline__ void gemm_phase(LAS unsigned char* lds, const Gemm g, const StaticOrder& S, const Epi& E, const int wid) {
;     ...
;             PG8_WAIT_V(8); PG8_WAIT_L(0); PG8_BAR; PG8_MMA(0, 0, At, B0); PG8_MMA(0, 1, At, B1); PG8_BAR; PG8_SCHED;
;             PG8_LDA(At, 1, 1); PG8_STAGE(PG8_SB(1, 0), b3, voffB); PG8_STAGE(PG8_SB(1, 1), b3 + hstepB, voffB); PG8_STAGE(PG8_SA(1, 0), a3, voffA);
;             PG8_WAIT_V(8); PG8_WAIT_L(0); PG8_BAR; PG8_MMA(1, 0, At, B0); PG8_MMA(1, 1, At, B1); PG8_BAR; PG8_SCHED;
;         }
;         if (wr == 0) PG8_BAR;
	v_mfma_f32_16x16x32_bf16 v[124:127], v[144:147], v[184:187], v[124:127]
	v_mfma_f32_16x16x32_bf16 v[120:123], v[160:163], v[184:187], v[120:123]
	v_mfma_f32_16x16x32_bf16 v[116:119], v[144:147], v[192:195], v[116:119]
	v_mfma_f32_16x16x32_bf16 v[112:115], v[160:163], v[192:195], v[112:115]
	v_mfma_f32_16x16x32_bf16 v[108:111], v[144:147], v[200:203], v[108:111]
	v_mfma_f32_16x16x32_bf16 v[104:107], v[160:163], v[200:203], v[104:107]
	v_mfma_f32_16x16x32_bf16 v[100:103], v[144:147], v[208:211], v[100:103]
	v_mfma_f32_16x16x32_bf16 v[96:99], v[160:163], v[208:211], v[96:99]
	v_mfma_f32_16x16x32_bf16 v[124:127], v[148:151], v[188:191], v[124:127]
	v_mfma_f32_16x16x32_bf16 v[120:123], v[164:167], v[188:191], v[120:123]
	v_mfma_f32_16x16x32_bf16 v[116:119], v[148:151], v[196:199], v[116:119]
	v_mfma_f32_16x16x32_bf16 v[112:115], v[164:167], v[196:199], v[112:115]
	v_mfma_f32_16x16x32_bf16 v[108:111], v[148:151], v[204:207], v[108:111]
	v_mfma_f32_16x16x32_bf16 v[104:107], v[164:167], v[204:207], v[104:107]
	v_mfma_f32_16x16x32_bf16 v[100:103], v[148:151], v[212:215], v[100:103]
	v_mfma_f32_16x16x32_bf16 v[96:99], v[164:167], v[212:215], v[96:99]
	v_mfma_f32_16x16x32_bf16 v[68:71], v[168:171], v[184:187], v[68:71]
	v_mfma_f32_16x16x32_bf16 v[60:63], v[176:179], v[184:187], v[60:63]
	v_mfma_f32_16x16x32_bf16 v[52:55], v[168:171], v[192:195], v[52:55]
	v_mfma_f32_16x16x32_bf16 v[48:51], v[176:179], v[192:195], v[48:51]
	v_mfma_f32_16x16x32_bf16 v[44:47], v[168:171], v[200:203], v[44:47]
	v_mfma_f32_16x16x32_bf16 v[40:43], v[176:179], v[200:203], v[40:43]
	v_mfma_f32_16x16x32_bf16 v[36:39], v[168:171], v[208:211], v[36:39]
	v_mfma_f32_16x16x32_bf16 v[32:35], v[176:179], v[208:211], v[32:35]
	v_mfma_f32_16x16x32_bf16 v[68:71], v[172:175], v[188:191], v[68:71]
	v_mfma_f32_16x16x32_bf16 v[60:63], v[180:183], v[188:191], v[60:63]
	v_mfma_f32_16x16x32_bf16 v[52:55], v[172:175], v[196:199], v[52:55]
	v_mfma_f32_16x16x32_bf16 v[48:51], v[180:183], v[196:199], v[48:51]
	v_mfma_f32_16x16x32_bf16 v[44:47], v[172:175], v[204:207], v[44:47]
	v_mfma_f32_16x16x32_bf16 v[40:43], v[180:183], v[204:207], v[40:43]
	v_mfma_f32_16x16x32_bf16 v[36:39], v[172:175], v[212:215], v[36:39]
	v_mfma_f32_16x16x32_bf16 v[32:35], v[180:183], v[212:215], v[32:35]
	s_barrier
	s_add_i32 s24, s46, s94
	s_add_u32 s98, s48, 0x80
	s_addc_u32 s99, s49, 0
	s_mov_b32 m0, s24
	ds_read_b128 v[184:187], v159 offset:49152
	global_load_lds_dwordx4 v132, s[98:99]
	s_add_i32 m0, s24, 0x2000
	s_add_u32 s24, s48, 0x40080
	s_addc_u32 s25, s49, 0
	s_add_i32 s46, s47, s94
	global_load_lds_dwordx4 v128, s[98:99]
	s_mov_b32 m0, s46
	ds_read_b128 v[188:191], v159 offset:50176
	global_load_lds_dwordx4 v132, s[24:25]
	s_add_i32 m0, s46, 0x2000
	ds_read_b128 v[192:195], v159 offset:51200
	global_load_lds_dwordx4 v128, s[24:25]
	s_add_u32 s100, s50, 0x80
	s_addc_u32 s101, s51, 0
	s_mov_b32 m0, s28
	ds_read_b128 v[196:199], v159 offset:52224
	global_load_lds_dwordx4 v134, s[100:101]
	s_mov_b32 m0, s29
	ds_read_b128 v[200:203], v159 offset:53248
	global_load_lds_dwordx4 v130, s[100:101]
	ds_read_b128 v[204:207], v159 offset:54272
	ds_read_b128 v[208:211], v159 offset:55296
	ds_read_b128 v[212:215], v159 offset:56320
	s_waitcnt vmcnt(8)
	s_waitcnt lgkmcnt(0)
	s_barrier
	v_mfma_f32_16x16x32_bf16 v[92:95], v[144:147], v[184:187], v[92:95]
	v_mfma_f32_16x16x32_bf16 v[88:91], v[160:163], v[184:187], v[88:91]
	v_mfma_f32_16x16x32_bf16 v[84:87], v[144:147], v[192:195], v[84:87]
	v_mfma_f32_16x16x32_bf16 v[80:83], v[160:163], v[192:195], v[80:83]
	v_mfma_f32_16x16x32_bf16 v[76:79], v[144:147], v[200:203], v[76:79]
	v_mfma_f32_16x16x32_bf16 v[72:75], v[160:163], v[200:203], v[72:75]
	v_mfma_f32_16x16x32_bf16 v[64:67], v[144:147], v[208:211], v[64:67]
	v_mfma_f32_16x16x32_bf16 v[56:59], v[160:163], v[208:211], v[56:59]
	v_mfma_f32_16x16x32_bf16 v[92:95], v[148:151], v[188:191], v[92:95]
	v_mfma_f32_16x16x32_bf16 v[88:91], v[164:167], v[188:191], v[88:91]
	v_mfma_f32_16x16x32_bf16 v[84:87], v[148:151], v[196:199], v[84:87]
	v_mfma_f32_16x16x32_bf16 v[80:83], v[164:167], v[196:199], v[80:83]
	v_mfma_f32_16x16x32_bf16 v[76:79], v[148:151], v[204:207], v[76:79]
	v_mfma_f32_16x16x32_bf16 v[72:75], v[164:167], v[204:207], v[72:75]
	v_mfma_f32_16x16x32_bf16 v[64:67], v[148:151], v[212:215], v[64:67]
	v_mfma_f32_16x16x32_bf16 v[56:59], v[164:167], v[212:215], v[56:59]
	v_mfma_f32_16x16x32_bf16 v[28:31], v[168:171], v[184:187], v[28:31]
	v_mfma_f32_16x16x32_bf16 v[24:27], v[176:179], v[184:187], v[24:27]
	v_mfma_f32_16x16x32_bf16 v[20:23], v[168:171], v[192:195], v[20:23]
	v_mfma_f32_16x16x32_bf16 v[16:19], v[176:179], v[192:195], v[16:19]
	v_mfma_f32_16x16x32_bf16 v[12:15], v[168:171], v[200:203], v[12:15]
	v_mfma_f32_16x16x32_bf16 v[8:11], v[176:179], v[200:203], v[8:11]
	v_mfma_f32_16x16x32_bf16 v[4:7], v[168:171], v[208:211], v[4:7]
	v_mfma_f32_16x16x32_bf16 v[0:3], v[176:179], v[208:211], v[0:3]
	v_mfma_f32_16x16x32_bf16 v[28:31], v[172:175], v[188:191], v[28:31]
	v_mfma_f32_16x16x32_bf16 v[24:27], v[180:183], v[188:191], v[24:27]
	v_mfma_f32_16x16x32_bf16 v[20:23], v[172:175], v[196:199], v[20:23]
	v_mfma_f32_16x16x32_bf16 v[16:19], v[180:183], v[196:199], v[16:19]
	v_mfma_f32_16x16x32_bf16 v[12:15], v[172:175], v[204:207], v[12:15]
	v_mfma_f32_16x16x32_bf16 v[8:11], v[180:183], v[204:207], v[8:11]
	v_mfma_f32_16x16x32_bf16 v[4:7], v[172:175], v[212:215], v[4:7]
	v_mfma_f32_16x16x32_bf16 v[0:3], v[180:183], v[212:215], v[0:3]
	s_barrier
	s_add_i32 s55, s55, 2
	s_add_u32 s53, s53, 0x100
	s_addc_u32 s54, s54, 0
	s_cmp_gt_u32 s55, 13
	s_mov_b64 s[46:47], s[6:7]
	s_cbranch_scc0 .LBB0_1669
	s_and_b64 vcc, exec, s[22:23]
	s_cbranch_vccz .LBB0_1672
	s_barrier

; #define PG8_STAGE(bufoff, gbase, voff) do { _Pragma("unroll") for (int _i = 0; _i < 2; ++_i) \
;         __builtin_amdgcn_global_load_lds((const unsigned*)((const char*)(gbase) + (voff)[_i]), (LAS unsigned*)(lds + (bufoff) + ldsw + _i * 8192), 16, 0, 0); } while (0)
; #define PG8_LDA(dst, b, h) do { _Pragma("unroll") for (int m = 0; m < 4; ++m) _Pragma("unroll") for (int k = 0; k < 2; ++k) dst[m][k] = *(const LAS bf16x8*)(lds + PG8_SA(b, h) + aoff + m * 2048 + k * 1024); } while (0)
; #define PG8_LDB(dst, b, h) do { _Pragma("unroll") for (int n = 0; n < 2; ++n) _Pragma("unroll") for (int k = 0; k < 2; ++k) dst[n][k] = *(const LAS bf16x8*)(lds + PG8_SB(b, h) + boff + n * 2048 + k * 1024); } while (0)
; #define PG8_MMA(ai, bj, At, Bt) do { __builtin_amdgcn_s_setprio(1); _Pragma("unroll") for (int m = 0; m < 4; ++m) _Pragma("unroll") for (int n = 0; n < 2; ++n) _Pragma("unroll") for (int k = 0; k < 2; ++k) \
;         acc[ai][bj][m][n] = __builtin_amdgcn_mfma_f32_16x16x32_bf16(Bt[n][k], At[m][k], acc[ai][bj][m][n], 0, 0, 0); __builtin_amdgcn_s_setprio(0); } while (0)
; #define PG8_WAIT_V(n) asm volatile("s_waitcnt vmcnt(" #n ")" ::: "memory")
; #define PG8_WAIT_L(n) asm volatile("s_waitcnt lgkmcnt(" #n ")" ::: "memory")
; #define PG8_BAR __builtin_amdgcn_s_barrier()
; #define PG8_SCHED __builtin_amdgcn_sched_barrier(0)
; template <class Epi>
; __device__ __forceinline__ void gemm_phase(LAS unsigned char* lds, const Gemm g, const StaticOrder& S, const Epi& E, const int wid) {
;     ...
;     for (;;) {
;         const bool has_next = S.next(ui + 1, nxt);
;         const char* nA = has_next ? PG8_TILEA(nxt.pm) : cA; const char* nB = has_next ? PG8_TILEB(nxt.pn) : cB;
;         for (int t = 0; t < nt; t += 2) {
;             const bool last = (t == nt - 2);
;             const char* a1 = cA + (size_t)(t + 1) * kstep;
;             const char* a2 = last ? nA : cA + (size_t)(t + 2) * kstep; const char* b2 = last ? nB : cB + (size_t)(t + 2) * kstep;
;             const char* a3 = a2 + kstep; const char* b3 = b2 + kstep;
;             PG8_LDB(B0, 0, 0); PG8_LDB(B1, 0, 1); PG8_SCHED; PG8_LDA(At, 0, 0); PG8_STAGE(PG8_SA(1, 1), a1 + hstepA, voffA);
;             PG8_WAIT_V(8); PG8_WAIT_L(0); PG8_BAR; PG8_MMA(0, 0, At, B0); PG8_MMA(0, 1, At, B1); PG8_BAR; PG8_SCHED;
.LBB0_1691:
	s_ashr_i32 s45, s44, 31
	s_lshl_b64 s[24:25], s[44:45], 19
	v_readlane_b32 s21, v251, 10
	s_add_u32 s48, s21, s24
	v_readlane_b32 s21, v251, 11
	s_addc_u32 s49, s21, s25
	s_and_b64 s[6:7], s[6:7], exec
	s_cselect_b32 s21, s49, s53
	s_cselect_b32 s38, s48, s52
	s_add_u32 s45, s52, 0x100
	v_mov_b32_e32 v0, 0
	s_addc_u32 s57, s53, 0
	s_mov_b32 s58, -2
	v_mov_b32_e32 v1, v0
	v_mov_b32_e32 v2, v0
	v_mov_b32_e32 v3, v0
	v_mov_b32_e32 v4, v0
	v_mov_b32_e32 v5, v0
	v_mov_b32_e32 v6, v0
	v_mov_b32_e32 v7, v0
	v_mov_b32_e32 v8, v0
	v_mov_b32_e32 v9, v0
	v_mov_b32_e32 v10, v0
	v_mov_b32_e32 v11, v0
	v_mov_b32_e32 v12, v0
	v_mov_b32_e32 v13, v0
	v_mov_b32_e32 v14, v0
	v_mov_b32_e32 v15, v0
	v_mov_b32_e32 v16, v0
	v_mov_b32_e32 v17, v0
	v_mov_b32_e32 v18, v0
	v_mov_b32_e32 v19, v0
	v_mov_b32_e32 v20, v0
	v_mov_b32_e32 v21, v0
	v_mov_b32_e32 v22, v0
	v_mov_b32_e32 v23, v0
	v_mov_b32_e32 v24, v0
	v_mov_b32_e32 v25, v0
	v_mov_b32_e32 v26, v0
	v_mov_b32_e32 v27, v0
	v_mov_b32_e32 v28, v0
	v_mov_b32_e32 v29, v0
	v_mov_b32_e32 v30, v0
	v_mov_b32_e32 v31, v0
	v_mov_b32_e32 v64, v0
	v_mov_b32_e32 v65, v0
	v_mov_b32_e32 v66, v0
	v_mov_b32_e32 v67, v0
	v_mov_b32_e32 v68, v0
	v_mov_b32_e32 v69, v0
	v_mov_b32_e32 v70, v0
	v_mov_b32_e32 v71, v0
	v_mov_b32_e32 v72, v0
	v_mov_b32_e32 v73, v0
	v_mov_b32_e32 v74, v0
	v_mov_b32_e32 v75, v0
	v_mov_b32_e32 v76, v0
	v_mov_b32_e32 v77, v0
	v_mov_b32_e32 v78, v0
	v_mov_b32_e32 v79, v0
	v_mov_b32_e32 v80, v0
	v_mov_b32_e32 v81, v0
	v_mov_b32_e32 v82, v0
	v_mov_b32_e32 v83, v0
	v_mov_b32_e32 v84, v0
	v_mov_b32_e32 v85, v0
	v_mov_b32_e32 v86, v0
	v_mov_b32_e32 v87, v0
	v_mov_b32_e32 v88, v0
	v_mov_b32_e32 v89, v0
	v_mov_b32_e32 v90, v0
	v_mov_b32_e32 v91, v0
	v_mov_b32_e32 v92, v0
	v_mov_b32_e32 v93, v0
	v_mov_b32_e32 v94, v0
	v_mov_b32_e32 v95, v0
	v_mov_b32_e32 v32, v0
	v_mov_b32_e32 v33, v0
	v_mov_b32_e32 v34, v0
	v_mov_b32_e32 v35, v0
	v_mov_b32_e32 v36, v0
	v_mov_b32_e32 v37, v0
	v_mov_b32_e32 v38, v0
	v_mov_b32_e32 v39, v0
	v_mov_b32_e32 v40, v0
	v_mov_b32_e32 v41, v0
	v_mov_b32_e32 v42, v0
	v_mov_b32_e32 v43, v0
	v_mov_b32_e32 v44, v0
	v_mov_b32_e32 v45, v0
	v_mov_b32_e32 v46, v0
	v_mov_b32_e32 v47, v0
	v_mov_b32_e32 v48, v0
	v_mov_b32_e32 v49, v0
	v_mov_b32_e32 v50, v0
	v_mov_b32_e32 v51, v0
	v_mov_b32_e32 v52, v0
	v_mov_b32_e32 v53, v0
	v_mov_b32_e32 v54, v0
	v_mov_b32_e32 v55, v0
	v_mov_b32_e32 v56, v0
	v_mov_b32_e32 v57, v0
	v_mov_b32_e32 v58, v0
	v_mov_b32_e32 v59, v0
	v_mov_b32_e32 v60, v0
	v_mov_b32_e32 v61, v0
	v_mov_b32_e32 v62, v0
	v_mov_b32_e32 v63, v0
	v_mov_b32_e32 v96, v0
	v_mov_b32_e32 v97, v0
	v_mov_b32_e32 v98, v0
	v_mov_b32_e32 v99, v0
	v_mov_b32_e32 v100, v0
	v_mov_b32_e32 v101, v0
	v_mov_b32_e32 v102, v0
	v_mov_b32_e32 v103, v0
	v_mov_b32_e32 v104, v0
	v_mov_b32_e32 v105, v0
	v_mov_b32_e32 v106, v0
	v_mov_b32_e32 v107, v0
	v_mov_b32_e32 v108, v0
	v_mov_b32_e32 v109, v0
	v_mov_b32_e32 v110, v0
	v_mov_b32_e32 v111, v0
	v_mov_b32_e32 v112, v0
	v_mov_b32_e32 v113, v0
	v_mov_b32_e32 v114, v0
	v_mov_b32_e32 v115, v0
	v_mov_b32_e32 v116, v0
	v_mov_b32_e32 v117, v0
	v_mov_b32_e32 v118, v0
	v_mov_b32_e32 v119, v0
	v_mov_b32_e32 v120, v0
	v_mov_b32_e32 v121, v0
	v_mov_b32_e32 v122, v0
	v_mov_b32_e32 v123, v0
	v_mov_b32_e32 v124, v0
	v_mov_b32_e32 v125, v0
	v_mov_b32_e32 v126, v0
	v_mov_b32_e32 v127, v0
	v_add_u32_e32 v252, 0x18000, v156
.LBB0_1692:
	ds_read_b128 v[144:147], v159
	ds_read_b128 v[148:151], v159 offset:1024
	ds_read_b128 v[152:155], v159 offset:2048
	ds_read_b128 v[162:165], v159 offset:3072
	ds_read_b128 v[166:169], v160
	ds_read_b128 v[170:173], v160 offset:1024
	ds_read_b128 v[174:177], v160 offset:2048
	ds_read_b128 v[178:181], v160 offset:3072
	s_add_u32 s6, s50, 0x100
	s_addc_u32 s7, s51, 0
	s_cmp_eq_u32 s58, 12
	s_cselect_b32 s55, s47, s7
	s_cselect_b32 s54, s46, s6
	s_cselect_b32 s53, s21, s57
	s_cselect_b32 s52, s38, s45
	s_add_i32 m0, s0, 0xc000
	ds_read_b128 v[182:185], v161
	global_load_lds_dwordx4 v136, s[50:51]
	s_add_i32 m0, s0, 0xe000
	ds_read_b128 v[186:189], v161 offset:1024
	global_load_lds_dwordx4 v138, s[50:51]
	ds_read_b128 v[190:193], v161 offset:2048
	ds_read_b128 v[194:197], v161 offset:3072
	ds_read_b128 v[198:201], v161 offset:4096
	ds_read_b128 v[202:205], v161 offset:5120
	ds_read_b128 v[206:209], v161 offset:6144
	ds_read_b128 v[210:213], v161 offset:7168
	s_waitcnt vmcnt(8)
	s_waitcnt lgkmcnt(0)
	s_barrier
	v_mfma_f32_16x16x32_bf16 v[124:127], v[144:147], v[182:185], v[124:127]
	v_mfma_f32_16x16x32_bf16 v[120:123], v[152:155], v[182:185], v[120:123]
	v_mfma_f32_16x16x32_bf16 v[116:119], v[144:147], v[190:193], v[116:119]
	v_mfma_f32_16x16x32_bf16 v[112:115], v[152:155], v[190:193], v[112:115]
	v_mfma_f32_16x16x32_bf16 v[108:111], v[144:147], v[198:201], v[108:111]
	v_mfma_f32_16x16x32_bf16 v[104:107], v[152:155], v[198:201], v[104:107]
	v_mfma_f32_16x16x32_bf16 v[100:103], v[144:147], v[206:209], v[100:103]
	v_mfma_f32_16x16x32_bf16 v[96:99], v[152:155], v[206:209], v[96:99]
	v_mfma_f32_16x16x32_bf16 v[124:127], v[148:151], v[186:189], v[124:127]
	v_mfma_f32_16x16x32_bf16 v[120:123], v[162:165], v[186:189], v[120:123]
	v_mfma_f32_16x16x32_bf16 v[116:119], v[148:151], v[194:197], v[116:119]
	v_mfma_f32_16x16x32_bf16 v[112:115], v[162:165], v[194:197], v[112:115]
	v_mfma_f32_16x16x32_bf16 v[108:111], v[148:151], v[202:205], v[108:111]
	v_mfma_f32_16x16x32_bf16 v[104:107], v[162:165], v[202:205], v[104:107]
	v_mfma_f32_16x16x32_bf16 v[100:103], v[148:151], v[210:213], v[100:103]
	v_mfma_f32_16x16x32_bf16 v[96:99], v[162:165], v[210:213], v[96:99]
	v_mfma_f32_16x16x32_bf16 v[60:63], v[166:169], v[182:185], v[60:63]
	v_mfma_f32_16x16x32_bf16 v[56:59], v[174:177], v[182:185], v[56:59]
	v_mfma_f32_16x16x32_bf16 v[52:55], v[166:169], v[190:193], v[52:55]
	v_mfma_f32_16x16x32_bf16 v[48:51], v[174:177], v[190:193], v[48:51]
	v_mfma_f32_16x16x32_bf16 v[44:47], v[166:169], v[198:201], v[44:47]
	v_mfma_f32_16x16x32_bf16 v[40:43], v[174:177], v[198:201], v[40:43]
	v_mfma_f32_16x16x32_bf16 v[36:39], v[166:169], v[206:209], v[36:39]
	v_mfma_f32_16x16x32_bf16 v[32:35], v[174:177], v[206:209], v[32:35]
	v_mfma_f32_16x16x32_bf16 v[60:63], v[170:173], v[186:189], v[60:63]
	v_mfma_f32_16x16x32_bf16 v[56:59], v[178:181], v[186:189], v[56:59]
	v_mfma_f32_16x16x32_bf16 v[52:55], v[170:173], v[194:197], v[52:55]
	v_mfma_f32_16x16x32_bf16 v[48:51], v[178:181], v[194:197], v[48:51]
	v_mfma_f32_16x16x32_bf16 v[44:47], v[170:173], v[202:205], v[44:47]
	v_mfma_f32_16x16x32_bf16 v[40:43], v[178:181], v[202:205], v[40:43]
	v_mfma_f32_16x16x32_bf16 v[36:39], v[170:173], v[210:213], v[36:39]
	v_mfma_f32_16x16x32_bf16 v[32:35], v[178:181], v[210:213], v[32:35]
	s_barrier
; #define PG8_STAGE(bufoff, gbase, voff) do { _Pragma("unroll") for (int _i = 0; _i < 2; ++_i) \
;         __builtin_amdgcn_global_load_lds((const unsigned*)((const char*)(gbase) + (voff)[_i]), (LAS unsigned*)(lds + (bufoff) + ldsw + _i * 8192), 16, 0, 0); } while (0)
; #define PG8_LDA(dst, b, h) do { _Pragma("unroll") for (int m = 0; m < 4; ++m) _Pragma("unroll") for (int k = 0; k < 2; ++k) dst[m][k] = *(const LAS bf16x8*)(lds + PG8_SA(b, h) + aoff + m * 2048 + k * 1024); } while (0)
; #define PG8_LDB(dst, b, h) do { _Pragma("unroll") for (int n = 0; n < 2; ++n) _Pragma("unroll") for (int k = 0; k < 2; ++k) dst[n][k] = *(const LAS bf16x8*)(lds + PG8_SB(b, h) + boff + n * 2048 + k * 1024); } while (0)
; #define PG8_MMA(ai, bj, At, Bt) do { __builtin_amdgcn_s_setprio(1); _Pragma("unroll") for (int m = 0; m < 4; ++m) _Pragma("unroll") for (int n = 0; n < 2; ++n) _Pragma("unroll") for (int k = 0; k < 2; ++k) \
;         acc[ai][bj][m][n] = __builtin_amdgcn_mfma_f32_16x16x32_bf16(Bt[n][k], At[m][k], acc[ai][bj][m][n], 0, 0, 0); __builtin_amdgcn_s_setprio(0); } while (0)
; #define PG8_WAIT_V(n) asm volatile("s_waitcnt vmcnt(" #n ")" ::: "memory")
; #define PG8_WAIT_L(n) asm volatile("s_waitcnt lgkmcnt(" #n ")" ::: "memory")
; #define PG8_BAR __builtin_amdgcn_s_barrier()
; #define PG8_SCHED __builtin_amdgcn_sched_barrier(0)
; template <class Epi>
; __device__ __forceinline__ void gemm_phase(LAS unsigned char* lds, const Gemm g, const StaticOrder& S, const Epi& E, const int wid) {
;     ...
;             PG8_LDA(At, 0, 1); PG8_STAGE(PG8_SB(0, 0), b2, voffB); PG8_STAGE(PG8_SB(0, 1), b2 + hstepB, voffB); PG8_STAGE(PG8_SA(0, 0), a2, voffA);
;             PG8_WAIT_V(8); PG8_WAIT_L(0); PG8_BAR; PG8_MMA(1, 0, At, B0); PG8_MMA(1, 1, At, B1); PG8_BAR; PG8_SCHED;
;             PG8_LDB(B0, 1, 0); PG8_LDB(B1, 1, 1); PG8_SCHED; PG8_LDA(At, 1, 0); PG8_STAGE(PG8_SA(0, 1), a2 + hstepA, voffA);
;             PG8_WAIT_V(8); PG8_WAIT_L(0); PG8_BAR; PG8_MMA(0, 0, At, B0); PG8_MMA(0, 1, At, B1); PG8_BAR; PG8_SCHED;
	s_add_i32 s24, s34, s94
	s_mov_b32 m0, s24
	ds_read_b128 v[182:185], v161 offset:16384
	global_load_lds_dwordx4 v132, s[52:53]
	s_add_i32 m0, s24, 0x2000
	s_add_u32 s24, s52, 0x40000
	s_addc_u32 s25, s53, 0
	s_add_i32 s50, s35, s94
	global_load_lds_dwordx4 v128, s[52:53]
	s_mov_b32 m0, s50
	ds_read_b128 v[186:189], v161 offset:17408
	global_load_lds_dwordx4 v132, s[24:25]
	s_add_i32 m0, s50, 0x2000
	ds_read_b128 v[190:193], v161 offset:18432
	global_load_lds_dwordx4 v128, s[24:25]
	s_mov_b32 m0, s0
	ds_read_b128 v[194:197], v161 offset:19456
	global_load_lds_dwordx4 v134, s[54:55]
	s_mov_b32 m0, s1
	ds_read_b128 v[198:201], v161 offset:20480
	global_load_lds_dwordx4 v130, s[54:55]
	ds_read_b128 v[202:205], v161 offset:21504
	ds_read_b128 v[206:209], v161 offset:22528
	ds_read_b128 v[210:213], v161 offset:23552
	s_waitcnt vmcnt(8)
	s_waitcnt lgkmcnt(0)
	s_barrier
	v_mfma_f32_16x16x32_bf16 v[92:95], v[144:147], v[182:185], v[92:95]
	v_mfma_f32_16x16x32_bf16 v[88:91], v[152:155], v[182:185], v[88:91]
	v_mfma_f32_16x16x32_bf16 v[84:87], v[144:147], v[190:193], v[84:87]
	v_mfma_f32_16x16x32_bf16 v[80:83], v[152:155], v[190:193], v[80:83]
	v_mfma_f32_16x16x32_bf16 v[76:79], v[144:147], v[198:201], v[76:79]
	v_mfma_f32_16x16x32_bf16 v[72:75], v[152:155], v[198:201], v[72:75]
	v_mfma_f32_16x16x32_bf16 v[68:71], v[144:147], v[206:209], v[68:71]
	v_mfma_f32_16x16x32_bf16 v[64:67], v[152:155], v[206:209], v[64:67]
	v_mfma_f32_16x16x32_bf16 v[92:95], v[148:151], v[186:189], v[92:95]
	v_mfma_f32_16x16x32_bf16 v[88:91], v[162:165], v[186:189], v[88:91]
	v_mfma_f32_16x16x32_bf16 v[84:87], v[148:151], v[194:197], v[84:87]
	v_mfma_f32_16x16x32_bf16 v[80:83], v[162:165], v[194:197], v[80:83]
	v_mfma_f32_16x16x32_bf16 v[76:79], v[148:151], v[202:205], v[76:79]
	v_mfma_f32_16x16x32_bf16 v[72:75], v[162:165], v[202:205], v[72:75]
	v_mfma_f32_16x16x32_bf16 v[68:71], v[148:151], v[210:213], v[68:71]
	v_mfma_f32_16x16x32_bf16 v[64:67], v[162:165], v[210:213], v[64:67]
	v_mfma_f32_16x16x32_bf16 v[28:31], v[166:169], v[182:185], v[28:31]
	v_mfma_f32_16x16x32_bf16 v[24:27], v[174:177], v[182:185], v[24:27]
	v_mfma_f32_16x16x32_bf16 v[20:23], v[166:169], v[190:193], v[20:23]
	v_mfma_f32_16x16x32_bf16 v[16:19], v[174:177], v[190:193], v[16:19]
	v_mfma_f32_16x16x32_bf16 v[12:15], v[166:169], v[198:201], v[12:15]
	v_mfma_f32_16x16x32_bf16 v[8:11], v[174:177], v[198:201], v[8:11]
	v_mfma_f32_16x16x32_bf16 v[4:7], v[166:169], v[206:209], v[4:7]
	v_mfma_f32_16x16x32_bf16 v[0:3], v[174:177], v[206:209], v[0:3]
	v_mfma_f32_16x16x32_bf16 v[28:31], v[170:173], v[186:189], v[28:31]
	v_mfma_f32_16x16x32_bf16 v[24:27], v[178:181], v[186:189], v[24:27]
	v_mfma_f32_16x16x32_bf16 v[20:23], v[170:173], v[194:197], v[20:23]
	v_mfma_f32_16x16x32_bf16 v[16:19], v[178:181], v[194:197], v[16:19]
	v_mfma_f32_16x16x32_bf16 v[12:15], v[170:173], v[202:205], v[12:15]
	v_mfma_f32_16x16x32_bf16 v[8:11], v[178:181], v[202:205], v[8:11]
	v_mfma_f32_16x16x32_bf16 v[4:7], v[170:173], v[210:213], v[4:7]
	v_mfma_f32_16x16x32_bf16 v[0:3], v[178:181], v[210:213], v[0:3]
	s_barrier
	s_add_i32 s50, 0, 0x18000
	s_add_i32 s51, 0, 0x1c000
	ds_read_b128 v[144:147], v252
	ds_read_b128 v[148:151], v252 offset:1024
	ds_read_b128 v[152:155], v252 offset:2048
	ds_read_b128 v[162:165], v252 offset:3072
	ds_read_b128 v[166:169], v252 offset:16384
	ds_read_b128 v[170:173], v252 offset:17408
	ds_read_b128 v[174:177], v252 offset:18432
	ds_read_b128 v[178:181], v252 offset:19456
	s_add_u32 s24, s54, 0x40000
	s_addc_u32 s25, s55, 0
	s_mov_b32 m0, s15
	ds_read_b128 v[182:185], v161 offset:32768
	global_load_lds_dwordx4 v134, s[24:25]
	s_mov_b32 m0, s26
	ds_read_b128 v[186:189], v161 offset:33792
	global_load_lds_dwordx4 v130, s[24:25]
	ds_read_b128 v[190:193], v161 offset:34816
	ds_read_b128 v[194:197], v161 offset:35840
	ds_read_b128 v[198:201], v161 offset:36864
	ds_read_b128 v[202:205], v161 offset:37888
	ds_read_b128 v[206:209], v161 offset:38912
	ds_read_b128 v[210:213], v161 offset:39936
	s_waitcnt vmcnt(8)
	s_waitcnt lgkmcnt(0)
	s_barrier
; #define PG8_STAGE(bufoff, gbase, voff) do { _Pragma("unroll") for (int _i = 0; _i < 2; ++_i) \
;         __builtin_amdgcn_global_load_lds((const unsigned*)((const char*)(gbase) + (voff)[_i]), (LAS unsigned*)(lds + (bufoff) + ldsw + _i * 8192), 16, 0, 0); } while (0)
; #define PG8_LDA(dst, b, h) do { _Pragma("unroll") for (int m = 0; m < 4; ++m) _Pragma("unroll") for (int k = 0; k < 2; ++k) dst[m][k] = *(const LAS bf16x8*)(lds + PG8_SA(b, h) + aoff + m * 2048 + k * 1024); } while (0)
; #define PG8_MMA(ai, bj, At, Bt) do { __builtin_amdgcn_s_setprio(1); _Pragma("unroll") for (int m = 0; m < 4; ++m) _Pragma("unroll") for (int n = 0; n < 2; ++n) _Pragma("unroll") for (int k = 0; k < 2; ++k) \
;         acc[ai][bj][m][n] = __builtin_amdgcn_mfma_f32_16x16x32_bf16(Bt[n][k], At[m][k], acc[ai][bj][m][n], 0, 0, 0); __builtin_amdgcn_s_setprio(0); } while (0)
; #define PG8_WAIT_V(n) asm volatile("s_waitcnt vmcnt(" #n ")" ::: "memory")
; #define PG8_WAIT_L(n) asm volatile("s_waitcnt lgkmcnt(" #n ")" ::: "memory")
; #define PG8_BAR __builtin_amdgcn_s_barrier()
; #define PG8_SCHED __builtin_amdgcn_sched_barrier(0)
; template <class Epi>
; __device__ __forceinline__ void gemm_phase(LAS unsigned char* lds, const Gemm g, const StaticOrder& S, const Epi& E, const int wid) {
;     ...
;             PG8_WAIT_V(8); PG8_WAIT_L(0); PG8_BAR; PG8_MMA(0, 0, At, B0); PG8_MMA(0, 1, At, B1); PG8_BAR; PG8_SCHED;
;             PG8_LDA(At, 1, 1); PG8_STAGE(PG8_SB(1, 0), b3, voffB); PG8_STAGE(PG8_SB(1, 1), b3 + hstepB, voffB); PG8_STAGE(PG8_SA(1, 0), a3, voffA);
;             PG8_WAIT_V(8); PG8_WAIT_L(0); PG8_BAR; PG8_MMA(1, 0, At, B0); PG8_MMA(1, 1, At, B1); PG8_BAR; PG8_SCHED;
;         }
;         if (wr == 0) PG8_BAR;
	v_mfma_f32_16x16x32_bf16 v[124:127], v[144:147], v[182:185], v[124:127]
	v_mfma_f32_16x16x32_bf16 v[120:123], v[152:155], v[182:185], v[120:123]
	v_mfma_f32_16x16x32_bf16 v[116:119], v[144:147], v[190:193], v[116:119]
	v_mfma_f32_16x16x32_bf16 v[112:115], v[152:155], v[190:193], v[112:115]
	v_mfma_f32_16x16x32_bf16 v[108:111], v[144:147], v[198:201], v[108:111]
	v_mfma_f32_16x16x32_bf16 v[104:107], v[152:155], v[198:201], v[104:107]
	v_mfma_f32_16x16x32_bf16 v[100:103], v[144:147], v[206:209], v[100:103]
	v_mfma_f32_16x16x32_bf16 v[96:99], v[152:155], v[206:209], v[96:99]
	v_mfma_f32_16x16x32_bf16 v[124:127], v[148:151], v[186:189], v[124:127]
	v_mfma_f32_16x16x32_bf16 v[120:123], v[162:165], v[186:189], v[120:123]
	v_mfma_f32_16x16x32_bf16 v[116:119], v[148:151], v[194:197], v[116:119]
	v_mfma_f32_16x16x32_bf16 v[112:115], v[162:165], v[194:197], v[112:115]
	v_mfma_f32_16x16x32_bf16 v[108:111], v[148:151], v[202:205], v[108:111]
	v_mfma_f32_16x16x32_bf16 v[104:107], v[162:165], v[202:205], v[104:107]
	v_mfma_f32_16x16x32_bf16 v[100:103], v[148:151], v[210:213], v[100:103]
	v_mfma_f32_16x16x32_bf16 v[96:99], v[162:165], v[210:213], v[96:99]
	v_mfma_f32_16x16x32_bf16 v[60:63], v[166:169], v[182:185], v[60:63]
	v_mfma_f32_16x16x32_bf16 v[56:59], v[174:177], v[182:185], v[56:59]
	v_mfma_f32_16x16x32_bf16 v[52:55], v[166:169], v[190:193], v[52:55]
	v_mfma_f32_16x16x32_bf16 v[48:51], v[174:177], v[190:193], v[48:51]
	v_mfma_f32_16x16x32_bf16 v[44:47], v[166:169], v[198:201], v[44:47]
	v_mfma_f32_16x16x32_bf16 v[40:43], v[174:177], v[198:201], v[40:43]
	v_mfma_f32_16x16x32_bf16 v[36:39], v[166:169], v[206:209], v[36:39]
	v_mfma_f32_16x16x32_bf16 v[32:35], v[174:177], v[206:209], v[32:35]
	v_mfma_f32_16x16x32_bf16 v[60:63], v[170:173], v[186:189], v[60:63]
	v_mfma_f32_16x16x32_bf16 v[56:59], v[178:181], v[186:189], v[56:59]
	v_mfma_f32_16x16x32_bf16 v[52:55], v[170:173], v[194:197], v[52:55]
	v_mfma_f32_16x16x32_bf16 v[48:51], v[178:181], v[194:197], v[48:51]
	v_mfma_f32_16x16x32_bf16 v[44:47], v[170:173], v[202:205], v[44:47]
	v_mfma_f32_16x16x32_bf16 v[40:43], v[178:181], v[202:205], v[40:43]
	v_mfma_f32_16x16x32_bf16 v[36:39], v[170:173], v[210:213], v[36:39]
	v_mfma_f32_16x16x32_bf16 v[32:35], v[178:181], v[210:213], v[32:35]
	s_barrier
	s_add_i32 s24, s50, s94
	s_add_u32 s98, s52, 0x80
	s_addc_u32 s99, s53, 0
	s_mov_b32 m0, s24
	ds_read_b128 v[182:185], v161 offset:49152
	global_load_lds_dwordx4 v132, s[98:99]
	s_add_i32 m0, s24, 0x2000
	s_add_u32 s24, s52, 0x40080
	s_addc_u32 s25, s53, 0
	s_add_i32 s50, s51, s94
	global_load_lds_dwordx4 v128, s[98:99]
	s_mov_b32 m0, s50
	ds_read_b128 v[186:189], v161 offset:50176
	global_load_lds_dwordx4 v132, s[24:25]
	s_add_i32 m0, s50, 0x2000
	ds_read_b128 v[190:193], v161 offset:51200
	global_load_lds_dwordx4 v128, s[24:25]
	s_add_u32 s100, s54, 0x80
	s_addc_u32 s101, s55, 0
	s_mov_b32 m0, s28
	ds_read_b128 v[194:197], v161 offset:52224
	global_load_lds_dwordx4 v134, s[100:101]
	s_mov_b32 m0, s29
	ds_read_b128 v[198:201], v161 offset:53248
	global_load_lds_dwordx4 v130, s[100:101]
	ds_read_b128 v[202:205], v161 offset:54272
	ds_read_b128 v[206:209], v161 offset:55296
	ds_read_b128 v[210:213], v161 offset:56320
	s_waitcnt vmcnt(8)
	s_waitcnt lgkmcnt(0)
	s_barrier
	v_mfma_f32_16x16x32_bf16 v[92:95], v[144:147], v[182:185], v[92:95]
	v_mfma_f32_16x16x32_bf16 v[88:91], v[152:155], v[182:185], v[88:91]
	v_mfma_f32_16x16x32_bf16 v[84:87], v[144:147], v[190:193], v[84:87]
	v_mfma_f32_16x16x32_bf16 v[80:83], v[152:155], v[190:193], v[80:83]
	v_mfma_f32_16x16x32_bf16 v[76:79], v[144:147], v[198:201], v[76:79]
	v_mfma_f32_16x16x32_bf16 v[72:75], v[152:155], v[198:201], v[72:75]
	v_mfma_f32_16x16x32_bf16 v[68:71], v[144:147], v[206:209], v[68:71]
	v_mfma_f32_16x16x32_bf16 v[64:67], v[152:155], v[206:209], v[64:67]
	v_mfma_f32_16x16x32_bf16 v[92:95], v[148:151], v[186:189], v[92:95]
	v_mfma_f32_16x16x32_bf16 v[88:91], v[162:165], v[186:189], v[88:91]
	v_mfma_f32_16x16x32_bf16 v[84:87], v[148:151], v[194:197], v[84:87]
	v_mfma_f32_16x16x32_bf16 v[80:83], v[162:165], v[194:197], v[80:83]
	v_mfma_f32_16x16x32_bf16 v[76:79], v[148:151], v[202:205], v[76:79]
	v_mfma_f32_16x16x32_bf16 v[72:75], v[162:165], v[202:205], v[72:75]
	v_mfma_f32_16x16x32_bf16 v[68:71], v[148:151], v[210:213], v[68:71]
	v_mfma_f32_16x16x32_bf16 v[64:67], v[162:165], v[210:213], v[64:67]
	v_mfma_f32_16x16x32_bf16 v[28:31], v[166:169], v[182:185], v[28:31]
	v_mfma_f32_16x16x32_bf16 v[24:27], v[174:177], v[182:185], v[24:27]
	v_mfma_f32_16x16x32_bf16 v[20:23], v[166:169], v[190:193], v[20:23]
	v_mfma_f32_16x16x32_bf16 v[16:19], v[174:177], v[190:193], v[16:19]
	v_mfma_f32_16x16x32_bf16 v[12:15], v[166:169], v[198:201], v[12:15]
	v_mfma_f32_16x16x32_bf16 v[8:11], v[174:177], v[198:201], v[8:11]
	v_mfma_f32_16x16x32_bf16 v[4:7], v[166:169], v[206:209], v[4:7]
	v_mfma_f32_16x16x32_bf16 v[0:3], v[174:177], v[206:209], v[0:3]
	v_mfma_f32_16x16x32_bf16 v[28:31], v[170:173], v[186:189], v[28:31]
	v_mfma_f32_16x16x32_bf16 v[24:27], v[178:181], v[186:189], v[24:27]
	v_mfma_f32_16x16x32_bf16 v[20:23], v[170:173], v[194:197], v[20:23]
	v_mfma_f32_16x16x32_bf16 v[16:19], v[178:181], v[194:197], v[16:19]
	v_mfma_f32_16x16x32_bf16 v[12:15], v[170:173], v[202:205], v[12:15]
	v_mfma_f32_16x16x32_bf16 v[8:11], v[178:181], v[202:205], v[8:11]
	v_mfma_f32_16x16x32_bf16 v[4:7], v[170:173], v[210:213], v[4:7]
	v_mfma_f32_16x16x32_bf16 v[0:3], v[178:181], v[210:213], v[0:3]
	s_barrier
	s_add_i32 s58, s58, 2
	s_add_u32 s45, s45, 0x100
	s_addc_u32 s57, s57, 0
	s_cmp_gt_u32 s58, 13
	s_mov_b64 s[50:51], s[6:7]
	s_cbranch_scc0 .LBB0_1692
	s_and_b64 vcc, exec, s[22:23]
	s_cbranch_vccz .LBB0_1695
	s_barrier

; #define PG8_STAGE(bufoff, gbase, voff) do { _Pragma("unroll") for (int _i = 0; _i < 2; ++_i) \
;         __builtin_amdgcn_global_load_lds((const unsigned*)((const char*)(gbase) + (voff)[_i]), (LAS unsigned*)(lds + (bufoff) + ldsw + _i * 8192), 16, 0, 0); } while (0)
; #define PG8_LDA(dst, b, h) do { _Pragma("unroll") for (int m = 0; m < 4; ++m) _Pragma("unroll") for (int k = 0; k < 2; ++k) dst[m][k] = *(const LAS bf16x8*)(lds + PG8_SA(b, h) + aoff + m * 2048 + k * 1024); } while (0)
; #define PG8_LDB(dst, b, h) do { _Pragma("unroll") for (int n = 0; n < 2; ++n) _Pragma("unroll") for (int k = 0; k < 2; ++k) dst[n][k] = *(const LAS bf16x8*)(lds + PG8_SB(b, h) + boff + n * 2048 + k * 1024); } while (0)
; #define PG8_MMA(ai, bj, At, Bt) do { __builtin_amdgcn_s_setprio(1); _Pragma("unroll") for (int m = 0; m < 4; ++m) _Pragma("unroll") for (int n = 0; n < 2; ++n) _Pragma("unroll") for (int k = 0; k < 2; ++k) \
;         acc[ai][bj][m][n] = __builtin_amdgcn_mfma_f32_16x16x32_bf16(Bt[n][k], At[m][k], acc[ai][bj][m][n], 0, 0, 0); __builtin_amdgcn_s_setprio(0); } while (0)
; #define PG8_WAIT_V(n) asm volatile("s_waitcnt vmcnt(" #n ")" ::: "memory")
; #define PG8_WAIT_L(n) asm volatile("s_waitcnt lgkmcnt(" #n ")" ::: "memory")
; #define PG8_BAR __builtin_amdgcn_s_barrier()
; #define PG8_SCHED __builtin_amdgcn_sched_barrier(0)
; template <class Epi>
; __device__ __forceinline__ void gemm_phase(LAS unsigned char* lds, const Gemm g, const StaticOrder& S, const Epi& E, const int wid) {
;     ...
;     for (;;) {
;         const bool has_next = S.next(ui + 1, nxt);
;         const char* nA = has_next ? PG8_TILEA(nxt.pm) : cA; const char* nB = has_next ? PG8_TILEB(nxt.pn) : cB;
;         for (int t = 0; t < nt; t += 2) {
;             const bool last = (t == nt - 2);
;             const char* a1 = cA + (size_t)(t + 1) * kstep;
;             const char* a2 = last ? nA : cA + (size_t)(t + 2) * kstep; const char* b2 = last ? nB : cB + (size_t)(t + 2) * kstep;
;             const char* a3 = a2 + kstep; const char* b3 = b2 + kstep;
;             PG8_LDB(B0, 0, 0); PG8_LDB(B1, 0, 1); PG8_SCHED; PG8_LDA(At, 0, 0); PG8_STAGE(PG8_SA(1, 1), a1 + hstepA, voffA);
;             PG8_WAIT_V(8); PG8_WAIT_L(0); PG8_BAR; PG8_MMA(0, 0, At, B0); PG8_MMA(0, 1, At, B1); PG8_BAR; PG8_SCHED;
.LBB0_1726:
	s_ashr_i32 s41, s40, 31
	s_lshl_b64 s[24:25], s[40:41], 20
	v_readlane_b32 s21, v251, 14
	s_add_u32 s44, s21, s24
	v_readlane_b32 s21, v251, 15
	s_addc_u32 s45, s21, s25
	s_and_b64 s[6:7], s[6:7], exec
	s_cselect_b32 s21, s45, s49
	s_cselect_b32 s41, s44, s48
	s_add_u32 s52, s48, 0x100
	v_mov_b32_e32 v0, 0
	s_addc_u32 s53, s49, 0
	s_mov_b32 s54, -2
	v_mov_b32_e32 v1, v0
	v_mov_b32_e32 v2, v0
	v_mov_b32_e32 v3, v0
	v_mov_b32_e32 v4, v0
	v_mov_b32_e32 v5, v0
	v_mov_b32_e32 v6, v0
	v_mov_b32_e32 v7, v0
	v_mov_b32_e32 v8, v0
	v_mov_b32_e32 v9, v0
	v_mov_b32_e32 v10, v0
	v_mov_b32_e32 v11, v0
	v_mov_b32_e32 v12, v0
	v_mov_b32_e32 v13, v0
	v_mov_b32_e32 v14, v0
	v_mov_b32_e32 v15, v0
	v_mov_b32_e32 v16, v0
	v_mov_b32_e32 v17, v0
	v_mov_b32_e32 v18, v0
	v_mov_b32_e32 v19, v0
	v_mov_b32_e32 v20, v0
	v_mov_b32_e32 v21, v0
	v_mov_b32_e32 v22, v0
	v_mov_b32_e32 v23, v0
	v_mov_b32_e32 v24, v0
	v_mov_b32_e32 v25, v0
	v_mov_b32_e32 v26, v0
	v_mov_b32_e32 v27, v0
	v_mov_b32_e32 v28, v0
	v_mov_b32_e32 v29, v0
	v_mov_b32_e32 v30, v0
	v_mov_b32_e32 v31, v0
	v_mov_b32_e32 v52, v0
	v_mov_b32_e32 v53, v0
	v_mov_b32_e32 v54, v0
	v_mov_b32_e32 v55, v0
	v_mov_b32_e32 v60, v0
	v_mov_b32_e32 v61, v0
	v_mov_b32_e32 v62, v0
	v_mov_b32_e32 v63, v0
	v_mov_b32_e32 v68, v0
	v_mov_b32_e32 v69, v0
	v_mov_b32_e32 v70, v0
	v_mov_b32_e32 v71, v0
	v_mov_b32_e32 v72, v0
	v_mov_b32_e32 v73, v0
	v_mov_b32_e32 v74, v0
	v_mov_b32_e32 v75, v0
	v_mov_b32_e32 v80, v0
	v_mov_b32_e32 v81, v0
	v_mov_b32_e32 v82, v0
	v_mov_b32_e32 v83, v0
	v_mov_b32_e32 v84, v0
	v_mov_b32_e32 v85, v0
	v_mov_b32_e32 v86, v0
	v_mov_b32_e32 v87, v0
	v_mov_b32_e32 v88, v0
	v_mov_b32_e32 v89, v0
	v_mov_b32_e32 v90, v0
	v_mov_b32_e32 v91, v0
	v_mov_b32_e32 v92, v0
	v_mov_b32_e32 v93, v0
	v_mov_b32_e32 v94, v0
	v_mov_b32_e32 v95, v0
	v_mov_b32_e32 v32, v0
	v_mov_b32_e32 v33, v0
	v_mov_b32_e32 v34, v0
	v_mov_b32_e32 v35, v0
	v_mov_b32_e32 v36, v0
	v_mov_b32_e32 v37, v0
	v_mov_b32_e32 v38, v0
	v_mov_b32_e32 v39, v0
	v_mov_b32_e32 v40, v0
	v_mov_b32_e32 v41, v0
	v_mov_b32_e32 v42, v0
	v_mov_b32_e32 v43, v0
	v_mov_b32_e32 v44, v0
	v_mov_b32_e32 v45, v0
	v_mov_b32_e32 v46, v0
	v_mov_b32_e32 v47, v0
	v_mov_b32_e32 v48, v0
	v_mov_b32_e32 v49, v0
	v_mov_b32_e32 v50, v0
	v_mov_b32_e32 v51, v0
	v_mov_b32_e32 v56, v0
	v_mov_b32_e32 v57, v0
	v_mov_b32_e32 v58, v0
	v_mov_b32_e32 v59, v0
	v_mov_b32_e32 v64, v0
	v_mov_b32_e32 v65, v0
	v_mov_b32_e32 v66, v0
	v_mov_b32_e32 v67, v0
	v_mov_b32_e32 v76, v0
	v_mov_b32_e32 v77, v0
	v_mov_b32_e32 v78, v0
	v_mov_b32_e32 v79, v0
	v_mov_b32_e32 v96, v0
	v_mov_b32_e32 v97, v0
	v_mov_b32_e32 v98, v0
	v_mov_b32_e32 v99, v0
	v_mov_b32_e32 v100, v0
	v_mov_b32_e32 v101, v0
	v_mov_b32_e32 v102, v0
	v_mov_b32_e32 v103, v0
	v_mov_b32_e32 v104, v0
	v_mov_b32_e32 v105, v0
	v_mov_b32_e32 v106, v0
	v_mov_b32_e32 v107, v0
	v_mov_b32_e32 v108, v0
	v_mov_b32_e32 v109, v0
	v_mov_b32_e32 v110, v0
	v_mov_b32_e32 v111, v0
	v_mov_b32_e32 v112, v0
	v_mov_b32_e32 v113, v0
	v_mov_b32_e32 v114, v0
	v_mov_b32_e32 v115, v0
	v_mov_b32_e32 v116, v0
	v_mov_b32_e32 v117, v0
	v_mov_b32_e32 v118, v0
	v_mov_b32_e32 v119, v0
	v_mov_b32_e32 v120, v0
	v_mov_b32_e32 v121, v0
	v_mov_b32_e32 v122, v0
	v_mov_b32_e32 v123, v0
	v_mov_b32_e32 v124, v0
	v_mov_b32_e32 v125, v0
	v_mov_b32_e32 v126, v0
	v_mov_b32_e32 v127, v0
	v_add_u32_e32 v252, 0x18000, v154
.LBB0_1727:
	ds_read_b128 v[144:147], v157
	ds_read_b128 v[148:151], v157 offset:1024
	ds_read_b128 v[160:163], v157 offset:2048
	ds_read_b128 v[164:167], v157 offset:3072
	ds_read_b128 v[168:171], v158
	ds_read_b128 v[172:175], v158 offset:1024
	ds_read_b128 v[176:179], v158 offset:2048
	ds_read_b128 v[180:183], v158 offset:3072
	s_add_u32 s6, s46, 0x100
	s_addc_u32 s7, s47, 0
	s_cmp_eq_u32 s54, 28
	s_cselect_b32 s51, s43, s7
	s_cselect_b32 s50, s42, s6
	s_cselect_b32 s49, s21, s53
	s_cselect_b32 s48, s41, s52
	s_add_i32 m0, s1, 0xc000
	ds_read_b128 v[184:187], v159
	global_load_lds_dwordx4 v136, s[46:47]
	s_add_i32 m0, s1, 0xe000
	ds_read_b128 v[188:191], v159 offset:1024
	global_load_lds_dwordx4 v138, s[46:47]
	ds_read_b128 v[192:195], v159 offset:2048
	ds_read_b128 v[196:199], v159 offset:3072
	ds_read_b128 v[200:203], v159 offset:4096
	ds_read_b128 v[204:207], v159 offset:5120
	ds_read_b128 v[208:211], v159 offset:6144
	ds_read_b128 v[212:215], v159 offset:7168
	s_waitcnt vmcnt(8)
	s_waitcnt lgkmcnt(0)
	s_barrier
	v_mfma_f32_16x16x32_bf16 v[124:127], v[144:147], v[184:187], v[124:127]
	v_mfma_f32_16x16x32_bf16 v[120:123], v[160:163], v[184:187], v[120:123]
	v_mfma_f32_16x16x32_bf16 v[116:119], v[144:147], v[192:195], v[116:119]
	v_mfma_f32_16x16x32_bf16 v[112:115], v[160:163], v[192:195], v[112:115]
	v_mfma_f32_16x16x32_bf16 v[108:111], v[144:147], v[200:203], v[108:111]
	v_mfma_f32_16x16x32_bf16 v[104:107], v[160:163], v[200:203], v[104:107]
	v_mfma_f32_16x16x32_bf16 v[100:103], v[144:147], v[208:211], v[100:103]
	v_mfma_f32_16x16x32_bf16 v[96:99], v[160:163], v[208:211], v[96:99]
	v_mfma_f32_16x16x32_bf16 v[124:127], v[148:151], v[188:191], v[124:127]
	v_mfma_f32_16x16x32_bf16 v[120:123], v[164:167], v[188:191], v[120:123]
	v_mfma_f32_16x16x32_bf16 v[116:119], v[148:151], v[196:199], v[116:119]
	v_mfma_f32_16x16x32_bf16 v[112:115], v[164:167], v[196:199], v[112:115]
	v_mfma_f32_16x16x32_bf16 v[108:111], v[148:151], v[204:207], v[108:111]
	v_mfma_f32_16x16x32_bf16 v[104:107], v[164:167], v[204:207], v[104:107]
	v_mfma_f32_16x16x32_bf16 v[100:103], v[148:151], v[212:215], v[100:103]
	v_mfma_f32_16x16x32_bf16 v[96:99], v[164:167], v[212:215], v[96:99]
	v_mfma_f32_16x16x32_bf16 v[76:79], v[168:171], v[184:187], v[76:79]
	v_mfma_f32_16x16x32_bf16 v[64:67], v[176:179], v[184:187], v[64:67]
	v_mfma_f32_16x16x32_bf16 v[56:59], v[168:171], v[192:195], v[56:59]
	v_mfma_f32_16x16x32_bf16 v[48:51], v[176:179], v[192:195], v[48:51]
	v_mfma_f32_16x16x32_bf16 v[44:47], v[168:171], v[200:203], v[44:47]
	v_mfma_f32_16x16x32_bf16 v[40:43], v[176:179], v[200:203], v[40:43]
	v_mfma_f32_16x16x32_bf16 v[36:39], v[168:171], v[208:211], v[36:39]
	v_mfma_f32_16x16x32_bf16 v[32:35], v[176:179], v[208:211], v[32:35]
	v_mfma_f32_16x16x32_bf16 v[76:79], v[172:175], v[188:191], v[76:79]
	v_mfma_f32_16x16x32_bf16 v[64:67], v[180:183], v[188:191], v[64:67]
	v_mfma_f32_16x16x32_bf16 v[56:59], v[172:175], v[196:199], v[56:59]
	v_mfma_f32_16x16x32_bf16 v[48:51], v[180:183], v[196:199], v[48:51]
	v_mfma_f32_16x16x32_bf16 v[44:47], v[172:175], v[204:207], v[44:47]
	v_mfma_f32_16x16x32_bf16 v[40:43], v[180:183], v[204:207], v[40:43]
	v_mfma_f32_16x16x32_bf16 v[36:39], v[172:175], v[212:215], v[36:39]
	v_mfma_f32_16x16x32_bf16 v[32:35], v[180:183], v[212:215], v[32:35]
	s_barrier
; #define PG8_STAGE(bufoff, gbase, voff) do { _Pragma("unroll") for (int _i = 0; _i < 2; ++_i) \
;         __builtin_amdgcn_global_load_lds((const unsigned*)((const char*)(gbase) + (voff)[_i]), (LAS unsigned*)(lds + (bufoff) + ldsw + _i * 8192), 16, 0, 0); } while (0)
; #define PG8_LDA(dst, b, h) do { _Pragma("unroll") for (int m = 0; m < 4; ++m) _Pragma("unroll") for (int k = 0; k < 2; ++k) dst[m][k] = *(const LAS bf16x8*)(lds + PG8_SA(b, h) + aoff + m * 2048 + k * 1024); } while (0)
; #define PG8_LDB(dst, b, h) do { _Pragma("unroll") for (int n = 0; n < 2; ++n) _Pragma("unroll") for (int k = 0; k < 2; ++k) dst[n][k] = *(const LAS bf16x8*)(lds + PG8_SB(b, h) + boff + n * 2048 + k * 1024); } while (0)
; #define PG8_MMA(ai, bj, At, Bt) do { __builtin_amdgcn_s_setprio(1); _Pragma("unroll") for (int m = 0; m < 4; ++m) _Pragma("unroll") for (int n = 0; n < 2; ++n) _Pragma("unroll") for (int k = 0; k < 2; ++k) \
;         acc[ai][bj][m][n] = __builtin_amdgcn_mfma_f32_16x16x32_bf16(Bt[n][k], At[m][k], acc[ai][bj][m][n], 0, 0, 0); __builtin_amdgcn_s_setprio(0); } while (0)
; #define PG8_WAIT_V(n) asm volatile("s_waitcnt vmcnt(" #n ")" ::: "memory")
; #define PG8_WAIT_L(n) asm volatile("s_waitcnt lgkmcnt(" #n ")" ::: "memory")
; #define PG8_BAR __builtin_amdgcn_s_barrier()
; #define PG8_SCHED __builtin_amdgcn_sched_barrier(0)
; template <class Epi>
; __device__ __forceinline__ void gemm_phase(LAS unsigned char* lds, const Gemm g, const StaticOrder& S, const Epi& E, const int wid) {
;     ...
;             PG8_LDA(At, 0, 1); PG8_STAGE(PG8_SB(0, 0), b2, voffB); PG8_STAGE(PG8_SB(0, 1), b2 + hstepB, voffB); PG8_STAGE(PG8_SA(0, 0), a2, voffA);
;             PG8_WAIT_V(8); PG8_WAIT_L(0); PG8_BAR; PG8_MMA(1, 0, At, B0); PG8_MMA(1, 1, At, B1); PG8_BAR; PG8_SCHED;
;             PG8_LDB(B0, 1, 0); PG8_LDB(B1, 1, 1); PG8_SCHED; PG8_LDA(At, 1, 0); PG8_STAGE(PG8_SA(0, 1), a2 + hstepA, voffA);
;             PG8_WAIT_V(8); PG8_WAIT_L(0); PG8_BAR; PG8_MMA(0, 0, At, B0); PG8_MMA(0, 1, At, B1); PG8_BAR; PG8_SCHED;
	s_add_i32 s24, s35, s94
	s_mov_b32 m0, s24
	ds_read_b128 v[184:187], v159 offset:16384
	global_load_lds_dwordx4 v132, s[48:49]
	s_add_i32 m0, s24, 0x2000
	s_add_u32 s24, s48, 0x80000
	s_addc_u32 s25, s49, 0
	s_add_i32 s46, s36, s94
	global_load_lds_dwordx4 v128, s[48:49]
	s_mov_b32 m0, s46
	ds_read_b128 v[188:191], v159 offset:17408
	global_load_lds_dwordx4 v132, s[24:25]
	s_add_i32 m0, s46, 0x2000
	ds_read_b128 v[192:195], v159 offset:18432
	global_load_lds_dwordx4 v128, s[24:25]
	s_mov_b32 m0, s1
	ds_read_b128 v[196:199], v159 offset:19456
	global_load_lds_dwordx4 v134, s[50:51]
	s_mov_b32 m0, s15
	ds_read_b128 v[200:203], v159 offset:20480
	global_load_lds_dwordx4 v130, s[50:51]
	ds_read_b128 v[204:207], v159 offset:21504
	ds_read_b128 v[208:211], v159 offset:22528
	ds_read_b128 v[212:215], v159 offset:23552
	s_waitcnt vmcnt(8)
	s_waitcnt lgkmcnt(0)
	s_barrier
	v_mfma_f32_16x16x32_bf16 v[92:95], v[144:147], v[184:187], v[92:95]
	v_mfma_f32_16x16x32_bf16 v[88:91], v[160:163], v[184:187], v[88:91]
	v_mfma_f32_16x16x32_bf16 v[84:87], v[144:147], v[192:195], v[84:87]
	v_mfma_f32_16x16x32_bf16 v[80:83], v[160:163], v[192:195], v[80:83]
	v_mfma_f32_16x16x32_bf16 v[72:75], v[144:147], v[200:203], v[72:75]
	v_mfma_f32_16x16x32_bf16 v[68:71], v[160:163], v[200:203], v[68:71]
	v_mfma_f32_16x16x32_bf16 v[60:63], v[144:147], v[208:211], v[60:63]
	v_mfma_f32_16x16x32_bf16 v[52:55], v[160:163], v[208:211], v[52:55]
	v_mfma_f32_16x16x32_bf16 v[92:95], v[148:151], v[188:191], v[92:95]
	v_mfma_f32_16x16x32_bf16 v[88:91], v[164:167], v[188:191], v[88:91]
	v_mfma_f32_16x16x32_bf16 v[84:87], v[148:151], v[196:199], v[84:87]
	v_mfma_f32_16x16x32_bf16 v[80:83], v[164:167], v[196:199], v[80:83]
	v_mfma_f32_16x16x32_bf16 v[72:75], v[148:151], v[204:207], v[72:75]
	v_mfma_f32_16x16x32_bf16 v[68:71], v[164:167], v[204:207], v[68:71]
	v_mfma_f32_16x16x32_bf16 v[60:63], v[148:151], v[212:215], v[60:63]
	v_mfma_f32_16x16x32_bf16 v[52:55], v[164:167], v[212:215], v[52:55]
	v_mfma_f32_16x16x32_bf16 v[28:31], v[168:171], v[184:187], v[28:31]
	v_mfma_f32_16x16x32_bf16 v[24:27], v[176:179], v[184:187], v[24:27]
	v_mfma_f32_16x16x32_bf16 v[20:23], v[168:171], v[192:195], v[20:23]
	v_mfma_f32_16x16x32_bf16 v[16:19], v[176:179], v[192:195], v[16:19]
	v_mfma_f32_16x16x32_bf16 v[12:15], v[168:171], v[200:203], v[12:15]
	v_mfma_f32_16x16x32_bf16 v[8:11], v[176:179], v[200:203], v[8:11]
	v_mfma_f32_16x16x32_bf16 v[4:7], v[168:171], v[208:211], v[4:7]
	v_mfma_f32_16x16x32_bf16 v[0:3], v[176:179], v[208:211], v[0:3]
	v_mfma_f32_16x16x32_bf16 v[28:31], v[172:175], v[188:191], v[28:31]
	v_mfma_f32_16x16x32_bf16 v[24:27], v[180:183], v[188:191], v[24:27]
	v_mfma_f32_16x16x32_bf16 v[20:23], v[172:175], v[196:199], v[20:23]
	v_mfma_f32_16x16x32_bf16 v[16:19], v[180:183], v[196:199], v[16:19]
	v_mfma_f32_16x16x32_bf16 v[12:15], v[172:175], v[204:207], v[12:15]
	v_mfma_f32_16x16x32_bf16 v[8:11], v[180:183], v[204:207], v[8:11]
	v_mfma_f32_16x16x32_bf16 v[4:7], v[172:175], v[212:215], v[4:7]
	v_mfma_f32_16x16x32_bf16 v[0:3], v[180:183], v[212:215], v[0:3]
	s_barrier
	s_add_i32 s46, 0, 0x18000
	s_add_i32 s47, 0, 0x1c000
	ds_read_b128 v[144:147], v252
	ds_read_b128 v[148:151], v252 offset:1024
	ds_read_b128 v[160:163], v252 offset:2048
	ds_read_b128 v[164:167], v252 offset:3072
	ds_read_b128 v[168:171], v252 offset:16384
	ds_read_b128 v[172:175], v252 offset:17408
	ds_read_b128 v[176:179], v252 offset:18432
	ds_read_b128 v[180:183], v252 offset:19456
	s_add_u32 s24, s50, 0x80000
	s_addc_u32 s25, s51, 0
	s_mov_b32 m0, s26
	ds_read_b128 v[184:187], v159 offset:32768
	global_load_lds_dwordx4 v134, s[24:25]
	s_mov_b32 m0, s27
	ds_read_b128 v[188:191], v159 offset:33792
	global_load_lds_dwordx4 v130, s[24:25]
	ds_read_b128 v[192:195], v159 offset:34816
	ds_read_b128 v[196:199], v159 offset:35840
	ds_read_b128 v[200:203], v159 offset:36864
	ds_read_b128 v[204:207], v159 offset:37888
	ds_read_b128 v[208:211], v159 offset:38912
	ds_read_b128 v[212:215], v159 offset:39936
	s_waitcnt vmcnt(8)
	s_waitcnt lgkmcnt(0)
	s_barrier
; #define PG8_STAGE(bufoff, gbase, voff) do { _Pragma("unroll") for (int _i = 0; _i < 2; ++_i) \
;         __builtin_amdgcn_global_load_lds((const unsigned*)((const char*)(gbase) + (voff)[_i]), (LAS unsigned*)(lds + (bufoff) + ldsw + _i * 8192), 16, 0, 0); } while (0)
; #define PG8_LDA(dst, b, h) do { _Pragma("unroll") for (int m = 0; m < 4; ++m) _Pragma("unroll") for (int k = 0; k < 2; ++k) dst[m][k] = *(const LAS bf16x8*)(lds + PG8_SA(b, h) + aoff + m * 2048 + k * 1024); } while (0)
; #define PG8_MMA(ai, bj, At, Bt) do { __builtin_amdgcn_s_setprio(1); _Pragma("unroll") for (int m = 0; m < 4; ++m) _Pragma("unroll") for (int n = 0; n < 2; ++n) _Pragma("unroll") for (int k = 0; k < 2; ++k) \
;         acc[ai][bj][m][n] = __builtin_amdgcn_mfma_f32_16x16x32_bf16(Bt[n][k], At[m][k], acc[ai][bj][m][n], 0, 0, 0); __builtin_amdgcn_s_setprio(0); } while (0)
; #define PG8_WAIT_V(n) asm volatile("s_waitcnt vmcnt(" #n ")" ::: "memory")
; #define PG8_WAIT_L(n) asm volatile("s_waitcnt lgkmcnt(" #n ")" ::: "memory")
; #define PG8_BAR __builtin_amdgcn_s_barrier()
; #define PG8_SCHED __builtin_amdgcn_sched_barrier(0)
; template <class Epi>
; __device__ __forceinline__ void gemm_phase(LAS unsigned char* lds, const Gemm g, const StaticOrder& S, const Epi& E, const int wid) {
;     ...
;             PG8_WAIT_V(8); PG8_WAIT_L(0); PG8_BAR; PG8_MMA(0, 0, At, B0); PG8_MMA(0, 1, At, B1); PG8_BAR; PG8_SCHED;
;             PG8_LDA(At, 1, 1); PG8_STAGE(PG8_SB(1, 0), b3, voffB); PG8_STAGE(PG8_SB(1, 1), b3 + hstepB, voffB); PG8_STAGE(PG8_SA(1, 0), a3, voffA);
;             PG8_WAIT_V(8); PG8_WAIT_L(0); PG8_BAR; PG8_MMA(1, 0, At, B0); PG8_MMA(1, 1, At, B1); PG8_BAR; PG8_SCHED;
;         }
;         if (wr == 0) PG8_BAR;
	v_mfma_f32_16x16x32_bf16 v[124:127], v[144:147], v[184:187], v[124:127]
	v_mfma_f32_16x16x32_bf16 v[120:123], v[160:163], v[184:187], v[120:123]
	v_mfma_f32_16x16x32_bf16 v[116:119], v[144:147], v[192:195], v[116:119]
	v_mfma_f32_16x16x32_bf16 v[112:115], v[160:163], v[192:195], v[112:115]
	v_mfma_f32_16x16x32_bf16 v[108:111], v[144:147], v[200:203], v[108:111]
	v_mfma_f32_16x16x32_bf16 v[104:107], v[160:163], v[200:203], v[104:107]
	v_mfma_f32_16x16x32_bf16 v[100:103], v[144:147], v[208:211], v[100:103]
	v_mfma_f32_16x16x32_bf16 v[96:99], v[160:163], v[208:211], v[96:99]
	v_mfma_f32_16x16x32_bf16 v[124:127], v[148:151], v[188:191], v[124:127]
	v_mfma_f32_16x16x32_bf16 v[120:123], v[164:167], v[188:191], v[120:123]
	v_mfma_f32_16x16x32_bf16 v[116:119], v[148:151], v[196:199], v[116:119]
	v_mfma_f32_16x16x32_bf16 v[112:115], v[164:167], v[196:199], v[112:115]
	v_mfma_f32_16x16x32_bf16 v[108:111], v[148:151], v[204:207], v[108:111]
	v_mfma_f32_16x16x32_bf16 v[104:107], v[164:167], v[204:207], v[104:107]
	v_mfma_f32_16x16x32_bf16 v[100:103], v[148:151], v[212:215], v[100:103]
	v_mfma_f32_16x16x32_bf16 v[96:99], v[164:167], v[212:215], v[96:99]
	v_mfma_f32_16x16x32_bf16 v[76:79], v[168:171], v[184:187], v[76:79]
	v_mfma_f32_16x16x32_bf16 v[64:67], v[176:179], v[184:187], v[64:67]
	v_mfma_f32_16x16x32_bf16 v[56:59], v[168:171], v[192:195], v[56:59]
	v_mfma_f32_16x16x32_bf16 v[48:51], v[176:179], v[192:195], v[48:51]
	v_mfma_f32_16x16x32_bf16 v[44:47], v[168:171], v[200:203], v[44:47]
	v_mfma_f32_16x16x32_bf16 v[40:43], v[176:179], v[200:203], v[40:43]
	v_mfma_f32_16x16x32_bf16 v[36:39], v[168:171], v[208:211], v[36:39]
	v_mfma_f32_16x16x32_bf16 v[32:35], v[176:179], v[208:211], v[32:35]
	v_mfma_f32_16x16x32_bf16 v[76:79], v[172:175], v[188:191], v[76:79]
	v_mfma_f32_16x16x32_bf16 v[64:67], v[180:183], v[188:191], v[64:67]
	v_mfma_f32_16x16x32_bf16 v[56:59], v[172:175], v[196:199], v[56:59]
	v_mfma_f32_16x16x32_bf16 v[48:51], v[180:183], v[196:199], v[48:51]
	v_mfma_f32_16x16x32_bf16 v[44:47], v[172:175], v[204:207], v[44:47]
	v_mfma_f32_16x16x32_bf16 v[40:43], v[180:183], v[204:207], v[40:43]
	v_mfma_f32_16x16x32_bf16 v[36:39], v[172:175], v[212:215], v[36:39]
	v_mfma_f32_16x16x32_bf16 v[32:35], v[180:183], v[212:215], v[32:35]
	s_barrier
	s_add_i32 s24, s46, s94
	s_add_u32 s98, s48, 0x80
	s_addc_u32 s99, s49, 0
	s_mov_b32 m0, s24
	ds_read_b128 v[184:187], v159 offset:49152
	global_load_lds_dwordx4 v132, s[98:99]
	s_add_i32 m0, s24, 0x2000
	s_add_u32 s24, s48, 0x80080
	s_addc_u32 s25, s49, 0
	s_add_i32 s46, s47, s94
	global_load_lds_dwordx4 v128, s[98:99]
	s_mov_b32 m0, s46
	ds_read_b128 v[188:191], v159 offset:50176
	global_load_lds_dwordx4 v132, s[24:25]
	s_add_i32 m0, s46, 0x2000
	ds_read_b128 v[192:195], v159 offset:51200
	global_load_lds_dwordx4 v128, s[24:25]
	s_add_u32 s100, s50, 0x80
	s_addc_u32 s101, s51, 0
	s_mov_b32 m0, s29
	ds_read_b128 v[196:199], v159 offset:52224
	global_load_lds_dwordx4 v134, s[100:101]
	s_mov_b32 m0, s34
	ds_read_b128 v[200:203], v159 offset:53248
	global_load_lds_dwordx4 v130, s[100:101]
	ds_read_b128 v[204:207], v159 offset:54272
	ds_read_b128 v[208:211], v159 offset:55296
	ds_read_b128 v[212:215], v159 offset:56320
	s_waitcnt vmcnt(8)
	s_waitcnt lgkmcnt(0)
	s_barrier
	v_mfma_f32_16x16x32_bf16 v[92:95], v[144:147], v[184:187], v[92:95]
	v_mfma_f32_16x16x32_bf16 v[88:91], v[160:163], v[184:187], v[88:91]
	v_mfma_f32_16x16x32_bf16 v[84:87], v[144:147], v[192:195], v[84:87]
	v_mfma_f32_16x16x32_bf16 v[80:83], v[160:163], v[192:195], v[80:83]
	v_mfma_f32_16x16x32_bf16 v[72:75], v[144:147], v[200:203], v[72:75]
	v_mfma_f32_16x16x32_bf16 v[68:71], v[160:163], v[200:203], v[68:71]
	v_mfma_f32_16x16x32_bf16 v[60:63], v[144:147], v[208:211], v[60:63]
	v_mfma_f32_16x16x32_bf16 v[52:55], v[160:163], v[208:211], v[52:55]
	v_mfma_f32_16x16x32_bf16 v[92:95], v[148:151], v[188:191], v[92:95]
	v_mfma_f32_16x16x32_bf16 v[88:91], v[164:167], v[188:191], v[88:91]
	v_mfma_f32_16x16x32_bf16 v[84:87], v[148:151], v[196:199], v[84:87]
	v_mfma_f32_16x16x32_bf16 v[80:83], v[164:167], v[196:199], v[80:83]
	v_mfma_f32_16x16x32_bf16 v[72:75], v[148:151], v[204:207], v[72:75]
	v_mfma_f32_16x16x32_bf16 v[68:71], v[164:167], v[204:207], v[68:71]
	v_mfma_f32_16x16x32_bf16 v[60:63], v[148:151], v[212:215], v[60:63]
	v_mfma_f32_16x16x32_bf16 v[52:55], v[164:167], v[212:215], v[52:55]
	v_mfma_f32_16x16x32_bf16 v[28:31], v[168:171], v[184:187], v[28:31]
	v_mfma_f32_16x16x32_bf16 v[24:27], v[176:179], v[184:187], v[24:27]
	v_mfma_f32_16x16x32_bf16 v[20:23], v[168:171], v[192:195], v[20:23]
	v_mfma_f32_16x16x32_bf16 v[16:19], v[176:179], v[192:195], v[16:19]
	v_mfma_f32_16x16x32_bf16 v[12:15], v[168:171], v[200:203], v[12:15]
	v_mfma_f32_16x16x32_bf16 v[8:11], v[176:179], v[200:203], v[8:11]
	v_mfma_f32_16x16x32_bf16 v[4:7], v[168:171], v[208:211], v[4:7]
	v_mfma_f32_16x16x32_bf16 v[0:3], v[176:179], v[208:211], v[0:3]
	v_mfma_f32_16x16x32_bf16 v[28:31], v[172:175], v[188:191], v[28:31]
	v_mfma_f32_16x16x32_bf16 v[24:27], v[180:183], v[188:191], v[24:27]
	v_mfma_f32_16x16x32_bf16 v[20:23], v[172:175], v[196:199], v[20:23]
	v_mfma_f32_16x16x32_bf16 v[16:19], v[180:183], v[196:199], v[16:19]
	v_mfma_f32_16x16x32_bf16 v[12:15], v[172:175], v[204:207], v[12:15]
	v_mfma_f32_16x16x32_bf16 v[8:11], v[180:183], v[204:207], v[8:11]
	v_mfma_f32_16x16x32_bf16 v[4:7], v[172:175], v[212:215], v[4:7]
	v_mfma_f32_16x16x32_bf16 v[0:3], v[180:183], v[212:215], v[0:3]
	s_barrier
	s_add_i32 s54, s54, 2
	s_add_u32 s52, s52, 0x100
	s_addc_u32 s53, s53, 0
	s_cmp_gt_u32 s54, 29
	s_mov_b64 s[46:47], s[6:7]
	s_cbranch_scc0 .LBB0_1727
	s_and_b64 vcc, exec, s[22:23]
	s_cbranch_vccz .LBB0_1730
	s_barrier

; #define PG8_STAGE(bufoff, gbase, voff) do { _Pragma("unroll") for (int _i = 0; _i < 2; ++_i) \
;         __builtin_amdgcn_global_load_lds((const unsigned*)((const char*)(gbase) + (voff)[_i]), (LAS unsigned*)(lds + (bufoff) + ldsw + _i * 8192), 16, 0, 0); } while (0)
; #define PG8_LDA(dst, b, h) do { _Pragma("unroll") for (int m = 0; m < 4; ++m) _Pragma("unroll") for (int k = 0; k < 2; ++k) dst[m][k] = *(const LAS bf16x8*)(lds + PG8_SA(b, h) + aoff + m * 2048 + k * 1024); } while (0)
; #define PG8_LDB(dst, b, h) do { _Pragma("unroll") for (int n = 0; n < 2; ++n) _Pragma("unroll") for (int k = 0; k < 2; ++k) dst[n][k] = *(const LAS bf16x8*)(lds + PG8_SB(b, h) + boff + n * 2048 + k * 1024); } while (0)
; #define PG8_MMA(ai, bj, At, Bt) do { __builtin_amdgcn_s_setprio(1); _Pragma("unroll") for (int m = 0; m < 4; ++m) _Pragma("unroll") for (int n = 0; n < 2; ++n) _Pragma("unroll") for (int k = 0; k < 2; ++k) \
;         acc[ai][bj][m][n] = __builtin_amdgcn_mfma_f32_16x16x32_bf16(Bt[n][k], At[m][k], acc[ai][bj][m][n], 0, 0, 0); __builtin_amdgcn_s_setprio(0); } while (0)
; #define PG8_WAIT_V(n) asm volatile("s_waitcnt vmcnt(" #n ")" ::: "memory")
; #define PG8_WAIT_L(n) asm volatile("s_waitcnt lgkmcnt(" #n ")" ::: "memory")
; #define PG8_BAR __builtin_amdgcn_s_barrier()
; #define PG8_SCHED __builtin_amdgcn_sched_barrier(0)
; template <class Epi>
; __device__ __forceinline__ void gemm_phase(LAS unsigned char* lds, const Gemm g, const StaticOrder& S, const Epi& E, const int wid) {
;     ...
;     for (;;) {
;         const bool has_next = S.next(ui + 1, nxt);
;         const char* nA = has_next ? PG8_TILEA(nxt.pm) : cA; const char* nB = has_next ? PG8_TILEB(nxt.pn) : cB;
;         for (int t = 0; t < nt; t += 2) {
;             const bool last = (t == nt - 2);
;             const char* a1 = cA + (size_t)(t + 1) * kstep;
;             const char* a2 = last ? nA : cA + (size_t)(t + 2) * kstep; const char* b2 = last ? nB : cB + (size_t)(t + 2) * kstep;
;             const char* a3 = a2 + kstep; const char* b3 = b2 + kstep;
;             PG8_LDB(B0, 0, 0); PG8_LDB(B1, 0, 1); PG8_SCHED; PG8_LDA(At, 0, 0); PG8_STAGE(PG8_SA(1, 1), a1 + hstepA, voffA);
;             PG8_WAIT_V(8); PG8_WAIT_L(0); PG8_BAR; PG8_MMA(0, 0, At, B0); PG8_MMA(0, 1, At, B1); PG8_BAR; PG8_SCHED;
.LBB0_1772:
	s_ashr_i32 s19, s18, 31
	s_lshl_b64 s[24:25], s[18:19], 20
	v_readlane_b32 s19, v251, 18
	s_add_u32 s40, s19, s24
	v_readlane_b32 s19, v251, 19
	s_addc_u32 s41, s19, s25
	s_and_b64 s[6:7], s[6:7], exec
	s_cselect_b32 s19, s41, s45
	s_cselect_b32 s51, s40, s44
	s_add_u32 s52, s44, 0x100
	v_mov_b32_e32 v0, 0
	s_addc_u32 s53, s45, 0
	s_mov_b32 s54, -2
	v_mov_b32_e32 v1, v0
	v_mov_b32_e32 v2, v0
	v_mov_b32_e32 v3, v0
	v_mov_b32_e32 v4, v0
	v_mov_b32_e32 v5, v0
	v_mov_b32_e32 v6, v0
	v_mov_b32_e32 v7, v0
	v_mov_b32_e32 v16, v0
	v_mov_b32_e32 v17, v0
	v_mov_b32_e32 v18, v0
	v_mov_b32_e32 v19, v0
	v_mov_b32_e32 v20, v0
	v_mov_b32_e32 v21, v0
	v_mov_b32_e32 v22, v0
	v_mov_b32_e32 v23, v0
	v_mov_b32_e32 v32, v0
	v_mov_b32_e32 v33, v0
	v_mov_b32_e32 v34, v0
	v_mov_b32_e32 v35, v0
	v_mov_b32_e32 v36, v0
	v_mov_b32_e32 v37, v0
	v_mov_b32_e32 v38, v0
	v_mov_b32_e32 v39, v0
	v_mov_b32_e32 v48, v0
	v_mov_b32_e32 v49, v0
	v_mov_b32_e32 v50, v0
	v_mov_b32_e32 v51, v0
	v_mov_b32_e32 v52, v0
	v_mov_b32_e32 v53, v0
	v_mov_b32_e32 v54, v0
	v_mov_b32_e32 v55, v0
	v_mov_b32_e32 v8, v0
	v_mov_b32_e32 v9, v0
	v_mov_b32_e32 v10, v0
	v_mov_b32_e32 v11, v0
	v_mov_b32_e32 v12, v0
	v_mov_b32_e32 v13, v0
	v_mov_b32_e32 v14, v0
	v_mov_b32_e32 v15, v0
	v_mov_b32_e32 v24, v0
	v_mov_b32_e32 v25, v0
	v_mov_b32_e32 v26, v0
	v_mov_b32_e32 v27, v0
	v_mov_b32_e32 v28, v0
	v_mov_b32_e32 v29, v0
	v_mov_b32_e32 v30, v0
	v_mov_b32_e32 v31, v0
	v_mov_b32_e32 v40, v0
	v_mov_b32_e32 v41, v0
	v_mov_b32_e32 v42, v0
	v_mov_b32_e32 v43, v0
	v_mov_b32_e32 v44, v0
	v_mov_b32_e32 v45, v0
	v_mov_b32_e32 v46, v0
	v_mov_b32_e32 v47, v0
	v_mov_b32_e32 v56, v0
	v_mov_b32_e32 v57, v0
	v_mov_b32_e32 v58, v0
	v_mov_b32_e32 v59, v0
	v_mov_b32_e32 v60, v0
	v_mov_b32_e32 v61, v0
	v_mov_b32_e32 v62, v0
	v_mov_b32_e32 v63, v0
	v_mov_b32_e32 v64, v0
	v_mov_b32_e32 v65, v0
	v_mov_b32_e32 v66, v0
	v_mov_b32_e32 v67, v0
	v_mov_b32_e32 v68, v0
	v_mov_b32_e32 v69, v0
	v_mov_b32_e32 v70, v0
	v_mov_b32_e32 v71, v0
	v_mov_b32_e32 v80, v0
	v_mov_b32_e32 v81, v0
	v_mov_b32_e32 v82, v0
	v_mov_b32_e32 v83, v0
	v_mov_b32_e32 v84, v0
	v_mov_b32_e32 v85, v0
	v_mov_b32_e32 v86, v0
	v_mov_b32_e32 v87, v0
	v_mov_b32_e32 v96, v0
	v_mov_b32_e32 v97, v0
	v_mov_b32_e32 v98, v0
	v_mov_b32_e32 v99, v0
	v_mov_b32_e32 v100, v0
	v_mov_b32_e32 v101, v0
	v_mov_b32_e32 v102, v0
	v_mov_b32_e32 v103, v0
	v_mov_b32_e32 v112, v0
	v_mov_b32_e32 v113, v0
	v_mov_b32_e32 v114, v0
	v_mov_b32_e32 v115, v0
	v_mov_b32_e32 v116, v0
	v_mov_b32_e32 v117, v0
	v_mov_b32_e32 v118, v0
	v_mov_b32_e32 v119, v0
	v_mov_b32_e32 v72, v0
	v_mov_b32_e32 v73, v0
	v_mov_b32_e32 v74, v0
	v_mov_b32_e32 v75, v0
	v_mov_b32_e32 v76, v0
	v_mov_b32_e32 v77, v0
	v_mov_b32_e32 v78, v0
	v_mov_b32_e32 v79, v0
	v_mov_b32_e32 v88, v0
	v_mov_b32_e32 v89, v0
	v_mov_b32_e32 v90, v0
	v_mov_b32_e32 v91, v0
	v_mov_b32_e32 v92, v0
	v_mov_b32_e32 v93, v0
	v_mov_b32_e32 v94, v0
	v_mov_b32_e32 v95, v0
	v_mov_b32_e32 v104, v0
	v_mov_b32_e32 v105, v0
	v_mov_b32_e32 v106, v0
	v_mov_b32_e32 v107, v0
	v_mov_b32_e32 v108, v0
	v_mov_b32_e32 v109, v0
	v_mov_b32_e32 v110, v0
	v_mov_b32_e32 v111, v0
	v_mov_b32_e32 v120, v0
	v_mov_b32_e32 v121, v0
	v_mov_b32_e32 v122, v0
	v_mov_b32_e32 v123, v0
	v_mov_b32_e32 v124, v0
	v_mov_b32_e32 v125, v0
	v_mov_b32_e32 v126, v0
	v_mov_b32_e32 v127, v0
	v_add_u32_e32 v252, 0x18000, v144
.LBB0_1773:
	ds_read_b128 v[150:153], v147
	ds_read_b128 v[154:157], v147 offset:1024
	ds_read_b128 v[158:161], v147 offset:2048
	ds_read_b128 v[162:165], v147 offset:3072
	ds_read_b128 v[166:169], v148
	ds_read_b128 v[170:173], v148 offset:1024
	ds_read_b128 v[174:177], v148 offset:2048
	ds_read_b128 v[178:181], v148 offset:3072
	s_add_u32 s6, s42, 0x100
	s_addc_u32 s7, s43, 0
	s_cmp_eq_u32 s54, 28
	s_cselect_b32 s47, s21, s7
	s_cselect_b32 s46, s20, s6
	s_cselect_b32 s45, s19, s53
	s_cselect_b32 s44, s51, s52
	s_add_i32 m0, s15, 0xc000
	ds_read_b128 v[182:185], v149
	global_load_lds_dwordx4 v136, s[42:43]
	s_add_i32 m0, s15, 0xe000
	ds_read_b128 v[186:189], v149 offset:1024
	global_load_lds_dwordx4 v138, s[42:43]
	ds_read_b128 v[190:193], v149 offset:2048
	ds_read_b128 v[194:197], v149 offset:3072
	ds_read_b128 v[198:201], v149 offset:4096
	ds_read_b128 v[202:205], v149 offset:5120
	ds_read_b128 v[206:209], v149 offset:6144
	ds_read_b128 v[210:213], v149 offset:7168
	s_waitcnt vmcnt(8)
	s_waitcnt lgkmcnt(0)
	s_barrier
	v_mfma_f32_16x16x32_bf16 v[124:127], v[150:153], v[182:185], v[124:127]
	v_mfma_f32_16x16x32_bf16 v[120:123], v[158:161], v[182:185], v[120:123]
	v_mfma_f32_16x16x32_bf16 v[108:111], v[150:153], v[190:193], v[108:111]
	v_mfma_f32_16x16x32_bf16 v[104:107], v[158:161], v[190:193], v[104:107]
	v_mfma_f32_16x16x32_bf16 v[92:95], v[150:153], v[198:201], v[92:95]
	v_mfma_f32_16x16x32_bf16 v[88:91], v[158:161], v[198:201], v[88:91]
	v_mfma_f32_16x16x32_bf16 v[76:79], v[150:153], v[206:209], v[76:79]
	v_mfma_f32_16x16x32_bf16 v[72:75], v[158:161], v[206:209], v[72:75]
	v_mfma_f32_16x16x32_bf16 v[124:127], v[154:157], v[186:189], v[124:127]
	v_mfma_f32_16x16x32_bf16 v[120:123], v[162:165], v[186:189], v[120:123]
	v_mfma_f32_16x16x32_bf16 v[108:111], v[154:157], v[194:197], v[108:111]
	v_mfma_f32_16x16x32_bf16 v[104:107], v[162:165], v[194:197], v[104:107]
	v_mfma_f32_16x16x32_bf16 v[92:95], v[154:157], v[202:205], v[92:95]
	v_mfma_f32_16x16x32_bf16 v[88:91], v[162:165], v[202:205], v[88:91]
	v_mfma_f32_16x16x32_bf16 v[76:79], v[154:157], v[210:213], v[76:79]
	v_mfma_f32_16x16x32_bf16 v[72:75], v[162:165], v[210:213], v[72:75]
	v_mfma_f32_16x16x32_bf16 v[116:119], v[166:169], v[182:185], v[116:119]
	v_mfma_f32_16x16x32_bf16 v[112:115], v[174:177], v[182:185], v[112:115]
	v_mfma_f32_16x16x32_bf16 v[100:103], v[166:169], v[190:193], v[100:103]
	v_mfma_f32_16x16x32_bf16 v[96:99], v[174:177], v[190:193], v[96:99]
	v_mfma_f32_16x16x32_bf16 v[84:87], v[166:169], v[198:201], v[84:87]
	v_mfma_f32_16x16x32_bf16 v[80:83], v[174:177], v[198:201], v[80:83]
	v_mfma_f32_16x16x32_bf16 v[68:71], v[166:169], v[206:209], v[68:71]
	v_mfma_f32_16x16x32_bf16 v[64:67], v[174:177], v[206:209], v[64:67]
	v_mfma_f32_16x16x32_bf16 v[116:119], v[170:173], v[186:189], v[116:119]
	v_mfma_f32_16x16x32_bf16 v[112:115], v[178:181], v[186:189], v[112:115]
	v_mfma_f32_16x16x32_bf16 v[100:103], v[170:173], v[194:197], v[100:103]
	v_mfma_f32_16x16x32_bf16 v[96:99], v[178:181], v[194:197], v[96:99]
	v_mfma_f32_16x16x32_bf16 v[84:87], v[170:173], v[202:205], v[84:87]
	v_mfma_f32_16x16x32_bf16 v[80:83], v[178:181], v[202:205], v[80:83]
	v_mfma_f32_16x16x32_bf16 v[68:71], v[170:173], v[210:213], v[68:71]
	v_mfma_f32_16x16x32_bf16 v[64:67], v[178:181], v[210:213], v[64:67]
	s_barrier
; #define PG8_STAGE(bufoff, gbase, voff) do { _Pragma("unroll") for (int _i = 0; _i < 2; ++_i) \
;         __builtin_amdgcn_global_load_lds((const unsigned*)((const char*)(gbase) + (voff)[_i]), (LAS unsigned*)(lds + (bufoff) + ldsw + _i * 8192), 16, 0, 0); } while (0)
; #define PG8_LDA(dst, b, h) do { _Pragma("unroll") for (int m = 0; m < 4; ++m) _Pragma("unroll") for (int k = 0; k < 2; ++k) dst[m][k] = *(const LAS bf16x8*)(lds + PG8_SA(b, h) + aoff + m * 2048 + k * 1024); } while (0)
; #define PG8_LDB(dst, b, h) do { _Pragma("unroll") for (int n = 0; n < 2; ++n) _Pragma("unroll") for (int k = 0; k < 2; ++k) dst[n][k] = *(const LAS bf16x8*)(lds + PG8_SB(b, h) + boff + n * 2048 + k * 1024); } while (0)
; #define PG8_MMA(ai, bj, At, Bt) do { __builtin_amdgcn_s_setprio(1); _Pragma("unroll") for (int m = 0; m < 4; ++m) _Pragma("unroll") for (int n = 0; n < 2; ++n) _Pragma("unroll") for (int k = 0; k < 2; ++k) \
;         acc[ai][bj][m][n] = __builtin_amdgcn_mfma_f32_16x16x32_bf16(Bt[n][k], At[m][k], acc[ai][bj][m][n], 0, 0, 0); __builtin_amdgcn_s_setprio(0); } while (0)
; #define PG8_WAIT_V(n) asm volatile("s_waitcnt vmcnt(" #n ")" ::: "memory")
; #define PG8_WAIT_L(n) asm volatile("s_waitcnt lgkmcnt(" #n ")" ::: "memory")
; #define PG8_BAR __builtin_amdgcn_s_barrier()
; #define PG8_SCHED __builtin_amdgcn_sched_barrier(0)
; template <class Epi>
; __device__ __forceinline__ void gemm_phase(LAS unsigned char* lds, const Gemm g, const StaticOrder& S, const Epi& E, const int wid) {
;     ...
;             PG8_LDA(At, 0, 1); PG8_STAGE(PG8_SB(0, 0), b2, voffB); PG8_STAGE(PG8_SB(0, 1), b2 + hstepB, voffB); PG8_STAGE(PG8_SA(0, 0), a2, voffA);
;             PG8_WAIT_V(8); PG8_WAIT_L(0); PG8_BAR; PG8_MMA(1, 0, At, B0); PG8_MMA(1, 1, At, B1); PG8_BAR; PG8_SCHED;
;             PG8_LDB(B0, 1, 0); PG8_LDB(B1, 1, 1); PG8_SCHED; PG8_LDA(At, 1, 0); PG8_STAGE(PG8_SA(0, 1), a2 + hstepA, voffA);
;             PG8_WAIT_V(8); PG8_WAIT_L(0); PG8_BAR; PG8_MMA(0, 0, At, B0); PG8_MMA(0, 1, At, B1); PG8_BAR; PG8_SCHED;
	s_add_i32 s24, s36, s94
	s_mov_b32 m0, s24
	ds_read_b128 v[182:185], v149 offset:16384
	global_load_lds_dwordx4 v132, s[44:45]
	s_add_i32 m0, s24, 0x2000
	s_add_u32 s24, s44, 0x80000
	s_addc_u32 s25, s45, 0
	s_add_i32 s42, s37, s94
	global_load_lds_dwordx4 v128, s[44:45]
	s_mov_b32 m0, s42
	ds_read_b128 v[186:189], v149 offset:17408
	global_load_lds_dwordx4 v132, s[24:25]
	s_add_i32 m0, s42, 0x2000
	ds_read_b128 v[190:193], v149 offset:18432
	global_load_lds_dwordx4 v128, s[24:25]
	s_mov_b32 m0, s15
	ds_read_b128 v[194:197], v149 offset:19456
	global_load_lds_dwordx4 v134, s[46:47]
	s_mov_b32 m0, s26
	ds_read_b128 v[198:201], v149 offset:20480
	global_load_lds_dwordx4 v130, s[46:47]
	ds_read_b128 v[202:205], v149 offset:21504
	ds_read_b128 v[206:209], v149 offset:22528
	ds_read_b128 v[210:213], v149 offset:23552
	s_waitcnt vmcnt(8)
	s_waitcnt lgkmcnt(0)
	s_barrier
	v_mfma_f32_16x16x32_bf16 v[60:63], v[150:153], v[182:185], v[60:63]
	v_mfma_f32_16x16x32_bf16 v[56:59], v[158:161], v[182:185], v[56:59]
	v_mfma_f32_16x16x32_bf16 v[44:47], v[150:153], v[190:193], v[44:47]
	v_mfma_f32_16x16x32_bf16 v[40:43], v[158:161], v[190:193], v[40:43]
	v_mfma_f32_16x16x32_bf16 v[28:31], v[150:153], v[198:201], v[28:31]
	v_mfma_f32_16x16x32_bf16 v[24:27], v[158:161], v[198:201], v[24:27]
	v_mfma_f32_16x16x32_bf16 v[12:15], v[150:153], v[206:209], v[12:15]
	v_mfma_f32_16x16x32_bf16 v[8:11], v[158:161], v[206:209], v[8:11]
	v_mfma_f32_16x16x32_bf16 v[60:63], v[154:157], v[186:189], v[60:63]
	v_mfma_f32_16x16x32_bf16 v[56:59], v[162:165], v[186:189], v[56:59]
	v_mfma_f32_16x16x32_bf16 v[44:47], v[154:157], v[194:197], v[44:47]
	v_mfma_f32_16x16x32_bf16 v[40:43], v[162:165], v[194:197], v[40:43]
	v_mfma_f32_16x16x32_bf16 v[28:31], v[154:157], v[202:205], v[28:31]
	v_mfma_f32_16x16x32_bf16 v[24:27], v[162:165], v[202:205], v[24:27]
	v_mfma_f32_16x16x32_bf16 v[12:15], v[154:157], v[210:213], v[12:15]
	v_mfma_f32_16x16x32_bf16 v[8:11], v[162:165], v[210:213], v[8:11]
	v_mfma_f32_16x16x32_bf16 v[52:55], v[166:169], v[182:185], v[52:55]
	v_mfma_f32_16x16x32_bf16 v[48:51], v[174:177], v[182:185], v[48:51]
	v_mfma_f32_16x16x32_bf16 v[36:39], v[166:169], v[190:193], v[36:39]
	v_mfma_f32_16x16x32_bf16 v[32:35], v[174:177], v[190:193], v[32:35]
	v_mfma_f32_16x16x32_bf16 v[20:23], v[166:169], v[198:201], v[20:23]
	v_mfma_f32_16x16x32_bf16 v[16:19], v[174:177], v[198:201], v[16:19]
	v_mfma_f32_16x16x32_bf16 v[4:7], v[166:169], v[206:209], v[4:7]
	v_mfma_f32_16x16x32_bf16 v[0:3], v[174:177], v[206:209], v[0:3]
	v_mfma_f32_16x16x32_bf16 v[52:55], v[170:173], v[186:189], v[52:55]
	v_mfma_f32_16x16x32_bf16 v[48:51], v[178:181], v[186:189], v[48:51]
	v_mfma_f32_16x16x32_bf16 v[36:39], v[170:173], v[194:197], v[36:39]
	v_mfma_f32_16x16x32_bf16 v[32:35], v[178:181], v[194:197], v[32:35]
	v_mfma_f32_16x16x32_bf16 v[20:23], v[170:173], v[202:205], v[20:23]
	v_mfma_f32_16x16x32_bf16 v[16:19], v[178:181], v[202:205], v[16:19]
	v_mfma_f32_16x16x32_bf16 v[4:7], v[170:173], v[210:213], v[4:7]
	v_mfma_f32_16x16x32_bf16 v[0:3], v[178:181], v[210:213], v[0:3]
	s_barrier
	s_add_i32 s42, 0, 0x18000
	s_add_i32 s43, 0, 0x1c000
	ds_read_b128 v[150:153], v252
	ds_read_b128 v[154:157], v252 offset:1024
	ds_read_b128 v[158:161], v252 offset:2048
	ds_read_b128 v[162:165], v252 offset:3072
	ds_read_b128 v[166:169], v252 offset:16384
	ds_read_b128 v[170:173], v252 offset:17408
	ds_read_b128 v[174:177], v252 offset:18432
	ds_read_b128 v[178:181], v252 offset:19456
	s_add_u32 s24, s46, 0x80000
	s_addc_u32 s25, s47, 0
	s_mov_b32 m0, s27
	ds_read_b128 v[182:185], v149 offset:32768
	global_load_lds_dwordx4 v134, s[24:25]
	s_mov_b32 m0, s28
	ds_read_b128 v[186:189], v149 offset:33792
	global_load_lds_dwordx4 v130, s[24:25]
	ds_read_b128 v[190:193], v149 offset:34816
	ds_read_b128 v[194:197], v149 offset:35840
	ds_read_b128 v[198:201], v149 offset:36864
	ds_read_b128 v[202:205], v149 offset:37888
	ds_read_b128 v[206:209], v149 offset:38912
	ds_read_b128 v[210:213], v149 offset:39936
	s_waitcnt vmcnt(8)
	s_waitcnt lgkmcnt(0)
	s_barrier
; #define PG8_STAGE(bufoff, gbase, voff) do { _Pragma("unroll") for (int _i = 0; _i < 2; ++_i) \
;         __builtin_amdgcn_global_load_lds((const unsigned*)((const char*)(gbase) + (voff)[_i]), (LAS unsigned*)(lds + (bufoff) + ldsw + _i * 8192), 16, 0, 0); } while (0)
; #define PG8_LDA(dst, b, h) do { _Pragma("unroll") for (int m = 0; m < 4; ++m) _Pragma("unroll") for (int k = 0; k < 2; ++k) dst[m][k] = *(const LAS bf16x8*)(lds + PG8_SA(b, h) + aoff + m * 2048 + k * 1024); } while (0)
; #define PG8_MMA(ai, bj, At, Bt) do { __builtin_amdgcn_s_setprio(1); _Pragma("unroll") for (int m = 0; m < 4; ++m) _Pragma("unroll") for (int n = 0; n < 2; ++n) _Pragma("unroll") for (int k = 0; k < 2; ++k) \
;         acc[ai][bj][m][n] = __builtin_amdgcn_mfma_f32_16x16x32_bf16(Bt[n][k], At[m][k], acc[ai][bj][m][n], 0, 0, 0); __builtin_amdgcn_s_setprio(0); } while (0)
; #define PG8_WAIT_V(n) asm volatile("s_waitcnt vmcnt(" #n ")" ::: "memory")
; #define PG8_WAIT_L(n) asm volatile("s_waitcnt lgkmcnt(" #n ")" ::: "memory")
; #define PG8_BAR __builtin_amdgcn_s_barrier()
; #define PG8_SCHED __builtin_amdgcn_sched_barrier(0)
; template <class Epi>
; __device__ __forceinline__ void gemm_phase(LAS unsigned char* lds, const Gemm g, const StaticOrder& S, const Epi& E, const int wid) {
;     ...
;             PG8_WAIT_V(8); PG8_WAIT_L(0); PG8_BAR; PG8_MMA(0, 0, At, B0); PG8_MMA(0, 1, At, B1); PG8_BAR; PG8_SCHED;
;             PG8_LDA(At, 1, 1); PG8_STAGE(PG8_SB(1, 0), b3, voffB); PG8_STAGE(PG8_SB(1, 1), b3 + hstepB, voffB); PG8_STAGE(PG8_SA(1, 0), a3, voffA);
;             PG8_WAIT_V(8); PG8_WAIT_L(0); PG8_BAR; PG8_MMA(1, 0, At, B0); PG8_MMA(1, 1, At, B1); PG8_BAR; PG8_SCHED;
;         }
;         if (wr == 0) PG8_BAR;
	v_mfma_f32_16x16x32_bf16 v[124:127], v[150:153], v[182:185], v[124:127]
	v_mfma_f32_16x16x32_bf16 v[120:123], v[158:161], v[182:185], v[120:123]
	v_mfma_f32_16x16x32_bf16 v[108:111], v[150:153], v[190:193], v[108:111]
	v_mfma_f32_16x16x32_bf16 v[104:107], v[158:161], v[190:193], v[104:107]
	v_mfma_f32_16x16x32_bf16 v[92:95], v[150:153], v[198:201], v[92:95]
	v_mfma_f32_16x16x32_bf16 v[88:91], v[158:161], v[198:201], v[88:91]
	v_mfma_f32_16x16x32_bf16 v[76:79], v[150:153], v[206:209], v[76:79]
	v_mfma_f32_16x16x32_bf16 v[72:75], v[158:161], v[206:209], v[72:75]
	v_mfma_f32_16x16x32_bf16 v[124:127], v[154:157], v[186:189], v[124:127]
	v_mfma_f32_16x16x32_bf16 v[120:123], v[162:165], v[186:189], v[120:123]
	v_mfma_f32_16x16x32_bf16 v[108:111], v[154:157], v[194:197], v[108:111]
	v_mfma_f32_16x16x32_bf16 v[104:107], v[162:165], v[194:197], v[104:107]
	v_mfma_f32_16x16x32_bf16 v[92:95], v[154:157], v[202:205], v[92:95]
	v_mfma_f32_16x16x32_bf16 v[88:91], v[162:165], v[202:205], v[88:91]
	v_mfma_f32_16x16x32_bf16 v[76:79], v[154:157], v[210:213], v[76:79]
	v_mfma_f32_16x16x32_bf16 v[72:75], v[162:165], v[210:213], v[72:75]
	v_mfma_f32_16x16x32_bf16 v[116:119], v[166:169], v[182:185], v[116:119]
	v_mfma_f32_16x16x32_bf16 v[112:115], v[174:177], v[182:185], v[112:115]
	v_mfma_f32_16x16x32_bf16 v[100:103], v[166:169], v[190:193], v[100:103]
	v_mfma_f32_16x16x32_bf16 v[96:99], v[174:177], v[190:193], v[96:99]
	v_mfma_f32_16x16x32_bf16 v[84:87], v[166:169], v[198:201], v[84:87]
	v_mfma_f32_16x16x32_bf16 v[80:83], v[174:177], v[198:201], v[80:83]
	v_mfma_f32_16x16x32_bf16 v[68:71], v[166:169], v[206:209], v[68:71]
	v_mfma_f32_16x16x32_bf16 v[64:67], v[174:177], v[206:209], v[64:67]
	v_mfma_f32_16x16x32_bf16 v[116:119], v[170:173], v[186:189], v[116:119]
	v_mfma_f32_16x16x32_bf16 v[112:115], v[178:181], v[186:189], v[112:115]
	v_mfma_f32_16x16x32_bf16 v[100:103], v[170:173], v[194:197], v[100:103]
	v_mfma_f32_16x16x32_bf16 v[96:99], v[178:181], v[194:197], v[96:99]
	v_mfma_f32_16x16x32_bf16 v[84:87], v[170:173], v[202:205], v[84:87]
	v_mfma_f32_16x16x32_bf16 v[80:83], v[178:181], v[202:205], v[80:83]
	v_mfma_f32_16x16x32_bf16 v[68:71], v[170:173], v[210:213], v[68:71]
	v_mfma_f32_16x16x32_bf16 v[64:67], v[178:181], v[210:213], v[64:67]
	s_barrier
	s_add_i32 s24, s42, s94
	s_add_u32 s98, s44, 0x80
	s_addc_u32 s99, s45, 0
	s_mov_b32 m0, s24
	ds_read_b128 v[182:185], v149 offset:49152
	global_load_lds_dwordx4 v132, s[98:99]
	s_add_i32 m0, s24, 0x2000
	s_add_u32 s24, s44, 0x80080
	s_addc_u32 s25, s45, 0
	s_add_i32 s42, s43, s94
	global_load_lds_dwordx4 v128, s[98:99]
	s_mov_b32 m0, s42
	ds_read_b128 v[186:189], v149 offset:50176
	global_load_lds_dwordx4 v132, s[24:25]
	s_add_i32 m0, s42, 0x2000
	ds_read_b128 v[190:193], v149 offset:51200
	global_load_lds_dwordx4 v128, s[24:25]
	s_add_u32 s100, s46, 0x80
	s_addc_u32 s101, s47, 0
	s_mov_b32 m0, s34
	ds_read_b128 v[194:197], v149 offset:52224
	global_load_lds_dwordx4 v134, s[100:101]
	s_mov_b32 m0, s35
	ds_read_b128 v[198:201], v149 offset:53248
	global_load_lds_dwordx4 v130, s[100:101]
	ds_read_b128 v[202:205], v149 offset:54272
	ds_read_b128 v[206:209], v149 offset:55296
	ds_read_b128 v[210:213], v149 offset:56320
	s_waitcnt vmcnt(8)
	s_waitcnt lgkmcnt(0)
	s_barrier
	v_mfma_f32_16x16x32_bf16 v[60:63], v[150:153], v[182:185], v[60:63]
	v_mfma_f32_16x16x32_bf16 v[56:59], v[158:161], v[182:185], v[56:59]
	v_mfma_f32_16x16x32_bf16 v[44:47], v[150:153], v[190:193], v[44:47]
	v_mfma_f32_16x16x32_bf16 v[40:43], v[158:161], v[190:193], v[40:43]
	v_mfma_f32_16x16x32_bf16 v[28:31], v[150:153], v[198:201], v[28:31]
	v_mfma_f32_16x16x32_bf16 v[24:27], v[158:161], v[198:201], v[24:27]
	v_mfma_f32_16x16x32_bf16 v[12:15], v[150:153], v[206:209], v[12:15]
	v_mfma_f32_16x16x32_bf16 v[8:11], v[158:161], v[206:209], v[8:11]
	v_mfma_f32_16x16x32_bf16 v[60:63], v[154:157], v[186:189], v[60:63]
	v_mfma_f32_16x16x32_bf16 v[56:59], v[162:165], v[186:189], v[56:59]
	v_mfma_f32_16x16x32_bf16 v[44:47], v[154:157], v[194:197], v[44:47]
	v_mfma_f32_16x16x32_bf16 v[40:43], v[162:165], v[194:197], v[40:43]
	v_mfma_f32_16x16x32_bf16 v[28:31], v[154:157], v[202:205], v[28:31]
	v_mfma_f32_16x16x32_bf16 v[24:27], v[162:165], v[202:205], v[24:27]
	v_mfma_f32_16x16x32_bf16 v[12:15], v[154:157], v[210:213], v[12:15]
	v_mfma_f32_16x16x32_bf16 v[8:11], v[162:165], v[210:213], v[8:11]
	v_mfma_f32_16x16x32_bf16 v[52:55], v[166:169], v[182:185], v[52:55]
	v_mfma_f32_16x16x32_bf16 v[48:51], v[174:177], v[182:185], v[48:51]
	v_mfma_f32_16x16x32_bf16 v[36:39], v[166:169], v[190:193], v[36:39]
	v_mfma_f32_16x16x32_bf16 v[32:35], v[174:177], v[190:193], v[32:35]
	v_mfma_f32_16x16x32_bf16 v[20:23], v[166:169], v[198:201], v[20:23]
	v_mfma_f32_16x16x32_bf16 v[16:19], v[174:177], v[198:201], v[16:19]
	v_mfma_f32_16x16x32_bf16 v[4:7], v[166:169], v[206:209], v[4:7]
	v_mfma_f32_16x16x32_bf16 v[0:3], v[174:177], v[206:209], v[0:3]
	v_mfma_f32_16x16x32_bf16 v[52:55], v[170:173], v[186:189], v[52:55]
	v_mfma_f32_16x16x32_bf16 v[48:51], v[178:181], v[186:189], v[48:51]
	v_mfma_f32_16x16x32_bf16 v[36:39], v[170:173], v[194:197], v[36:39]
	v_mfma_f32_16x16x32_bf16 v[32:35], v[178:181], v[194:197], v[32:35]
	v_mfma_f32_16x16x32_bf16 v[20:23], v[170:173], v[202:205], v[20:23]
	v_mfma_f32_16x16x32_bf16 v[16:19], v[178:181], v[202:205], v[16:19]
	v_mfma_f32_16x16x32_bf16 v[4:7], v[170:173], v[210:213], v[4:7]
	v_mfma_f32_16x16x32_bf16 v[0:3], v[178:181], v[210:213], v[0:3]
	s_barrier
	s_add_i32 s54, s54, 2
	s_add_u32 s52, s52, 0x100
	s_addc_u32 s53, s53, 0
	s_cmp_gt_u32 s54, 29
	s_mov_b64 s[42:43], s[6:7]
	s_cbranch_scc0 .LBB0_1773
	s_and_b64 vcc, exec, s[22:23]
	s_cbranch_vccz .LBB0_1776
	s_barrier

; #define PG8_STAGE(bufoff, gbase, voff) do { _Pragma("unroll") for (int _i = 0; _i < 2; ++_i) \
;         __builtin_amdgcn_global_load_lds((const unsigned*)((const char*)(gbase) + (voff)[_i]), (LAS unsigned*)(lds + (bufoff) + ldsw + _i * 8192), 16, 0, 0); } while (0)
; #define PG8_LDA(dst, b, h) do { _Pragma("unroll") for (int m = 0; m < 4; ++m) _Pragma("unroll") for (int k = 0; k < 2; ++k) dst[m][k] = *(const LAS bf16x8*)(lds + PG8_SA(b, h) + aoff + m * 2048 + k * 1024); } while (0)
; #define PG8_LDB(dst, b, h) do { _Pragma("unroll") for (int n = 0; n < 2; ++n) _Pragma("unroll") for (int k = 0; k < 2; ++k) dst[n][k] = *(const LAS bf16x8*)(lds + PG8_SB(b, h) + boff + n * 2048 + k * 1024); } while (0)
; #define PG8_MMA(ai, bj, At, Bt) do { __builtin_amdgcn_s_setprio(1); _Pragma("unroll") for (int m = 0; m < 4; ++m) _Pragma("unroll") for (int n = 0; n < 2; ++n) _Pragma("unroll") for (int k = 0; k < 2; ++k) \
;         acc[ai][bj][m][n] = __builtin_amdgcn_mfma_f32_16x16x32_bf16(Bt[n][k], At[m][k], acc[ai][bj][m][n], 0, 0, 0); __builtin_amdgcn_s_setprio(0); } while (0)
; #define PG8_WAIT_V(n) asm volatile("s_waitcnt vmcnt(" #n ")" ::: "memory")
; #define PG8_WAIT_L(n) asm volatile("s_waitcnt lgkmcnt(" #n ")" ::: "memory")
; #define PG8_BAR __builtin_amdgcn_s_barrier()
; #define PG8_SCHED __builtin_amdgcn_sched_barrier(0)
; template <class Epi>
; __device__ __forceinline__ void gemm_phase(LAS unsigned char* lds, const Gemm g, const StaticOrder& S, const Epi& E, const int wid) {
;     ...
;     for (;;) {
;         const bool has_next = S.next(ui + 1, nxt);
;         const char* nA = has_next ? PG8_TILEA(nxt.pm) : cA; const char* nB = has_next ? PG8_TILEB(nxt.pn) : cB;
;         for (int t = 0; t < nt; t += 2) {
;             const bool last = (t == nt - 2);
;             const char* a1 = cA + (size_t)(t + 1) * kstep;
;             const char* a2 = last ? nA : cA + (size_t)(t + 2) * kstep; const char* b2 = last ? nB : cB + (size_t)(t + 2) * kstep;
;             const char* a3 = a2 + kstep; const char* b3 = b2 + kstep;
;             PG8_LDB(B0, 0, 0); PG8_LDB(B1, 0, 1); PG8_SCHED; PG8_LDA(At, 0, 0); PG8_STAGE(PG8_SA(1, 1), a1 + hstepA, voffA);
;             PG8_WAIT_V(8); PG8_WAIT_L(0); PG8_BAR; PG8_MMA(0, 0, At, B0); PG8_MMA(0, 1, At, B1); PG8_BAR; PG8_SCHED;
.LBB0_1809:
	s_add_u32 s43, s28, 0x100
	v_mov_b32_e32 v0, 0
	s_addc_u32 s44, s29, 0
	s_mov_b32 s45, -2
	v_mov_b32_e32 v1, v0
	v_mov_b32_e32 v2, v0
	v_mov_b32_e32 v3, v0
	v_mov_b32_e32 v4, v0
	v_mov_b32_e32 v5, v0
	v_mov_b32_e32 v6, v0
	v_mov_b32_e32 v7, v0
	v_mov_b32_e32 v8, v0
	v_mov_b32_e32 v9, v0
	v_mov_b32_e32 v10, v0
	v_mov_b32_e32 v11, v0
	v_mov_b32_e32 v12, v0
	v_mov_b32_e32 v13, v0
	v_mov_b32_e32 v14, v0
	v_mov_b32_e32 v15, v0
	v_mov_b32_e32 v16, v0
	v_mov_b32_e32 v17, v0
	v_mov_b32_e32 v18, v0
	v_mov_b32_e32 v19, v0
	v_mov_b32_e32 v20, v0
	v_mov_b32_e32 v21, v0
	v_mov_b32_e32 v22, v0
	v_mov_b32_e32 v23, v0
	v_mov_b32_e32 v24, v0
	v_mov_b32_e32 v25, v0
	v_mov_b32_e32 v26, v0
	v_mov_b32_e32 v27, v0
	v_mov_b32_e32 v28, v0
	v_mov_b32_e32 v29, v0
	v_mov_b32_e32 v30, v0
	v_mov_b32_e32 v31, v0
	v_mov_b32_e32 v56, v0
	v_mov_b32_e32 v57, v0
	v_mov_b32_e32 v58, v0
	v_mov_b32_e32 v59, v0
	v_mov_b32_e32 v60, v0
	v_mov_b32_e32 v61, v0
	v_mov_b32_e32 v62, v0
	v_mov_b32_e32 v63, v0
	v_mov_b32_e32 v72, v0
	v_mov_b32_e32 v73, v0
	v_mov_b32_e32 v74, v0
	v_mov_b32_e32 v75, v0
	v_mov_b32_e32 v76, v0
	v_mov_b32_e32 v77, v0
	v_mov_b32_e32 v78, v0
	v_mov_b32_e32 v79, v0
	v_mov_b32_e32 v80, v0
	v_mov_b32_e32 v81, v0
	v_mov_b32_e32 v82, v0
	v_mov_b32_e32 v83, v0
	v_mov_b32_e32 v84, v0
	v_mov_b32_e32 v85, v0
	v_mov_b32_e32 v86, v0
	v_mov_b32_e32 v87, v0
	v_mov_b32_e32 v88, v0
	v_mov_b32_e32 v89, v0
	v_mov_b32_e32 v90, v0
	v_mov_b32_e32 v91, v0
	v_mov_b32_e32 v92, v0
	v_mov_b32_e32 v93, v0
	v_mov_b32_e32 v94, v0
	v_mov_b32_e32 v95, v0
	v_mov_b32_e32 v32, v0
	v_mov_b32_e32 v33, v0
	v_mov_b32_e32 v34, v0
	v_mov_b32_e32 v35, v0
	v_mov_b32_e32 v36, v0
	v_mov_b32_e32 v37, v0
	v_mov_b32_e32 v38, v0
	v_mov_b32_e32 v39, v0
	v_mov_b32_e32 v40, v0
	v_mov_b32_e32 v41, v0
	v_mov_b32_e32 v42, v0
	v_mov_b32_e32 v43, v0
	v_mov_b32_e32 v44, v0
	v_mov_b32_e32 v45, v0
	v_mov_b32_e32 v46, v0
	v_mov_b32_e32 v47, v0
	v_mov_b32_e32 v48, v0
	v_mov_b32_e32 v49, v0
	v_mov_b32_e32 v50, v0
	v_mov_b32_e32 v51, v0
	v_mov_b32_e32 v52, v0
	v_mov_b32_e32 v53, v0
	v_mov_b32_e32 v54, v0
	v_mov_b32_e32 v55, v0
	v_mov_b32_e32 v64, v0
	v_mov_b32_e32 v65, v0
	v_mov_b32_e32 v66, v0
	v_mov_b32_e32 v67, v0
	v_mov_b32_e32 v68, v0
	v_mov_b32_e32 v69, v0
	v_mov_b32_e32 v70, v0
	v_mov_b32_e32 v71, v0
	v_mov_b32_e32 v96, v0
	v_mov_b32_e32 v97, v0
	v_mov_b32_e32 v98, v0
	v_mov_b32_e32 v99, v0
	v_mov_b32_e32 v100, v0
	v_mov_b32_e32 v101, v0
	v_mov_b32_e32 v102, v0
	v_mov_b32_e32 v103, v0
	v_mov_b32_e32 v104, v0
	v_mov_b32_e32 v105, v0
	v_mov_b32_e32 v106, v0
	v_mov_b32_e32 v107, v0
	v_mov_b32_e32 v108, v0
	v_mov_b32_e32 v109, v0
	v_mov_b32_e32 v110, v0
	v_mov_b32_e32 v111, v0
	v_mov_b32_e32 v112, v0
	v_mov_b32_e32 v113, v0
	v_mov_b32_e32 v114, v0
	v_mov_b32_e32 v115, v0
	v_mov_b32_e32 v116, v0
	v_mov_b32_e32 v117, v0
	v_mov_b32_e32 v118, v0
	v_mov_b32_e32 v119, v0
	v_mov_b32_e32 v120, v0
	v_mov_b32_e32 v121, v0
	v_mov_b32_e32 v122, v0
	v_mov_b32_e32 v123, v0
	v_mov_b32_e32 v124, v0
	v_mov_b32_e32 v125, v0
	v_mov_b32_e32 v126, v0
	v_mov_b32_e32 v127, v0
	v_add_u32_e32 v252, 0x18000, v150
.LBB0_1810:
	ds_read_b128 v[144:147], v153
	ds_read_b128 v[156:159], v153 offset:1024
	ds_read_b128 v[160:163], v153 offset:2048
	ds_read_b128 v[164:167], v153 offset:3072
	ds_read_b128 v[168:171], v154
	ds_read_b128 v[172:175], v154 offset:1024
	ds_read_b128 v[176:179], v154 offset:2048
	ds_read_b128 v[180:183], v154 offset:3072
	s_add_u32 s26, s20, 0x100
	s_addc_u32 s27, s21, 0
	s_cmpk_eq_i32 s45, 0x54
	s_cselect_b32 s31, s7, s27
	s_cselect_b32 s30, s6, s26
	s_cselect_b32 s29, s19, s44
	s_cselect_b32 s28, s18, s43
	s_add_i32 m0, s1, 0xc000
	ds_read_b128 v[184:187], v155
	global_load_lds_dwordx4 v136, s[20:21]
	s_add_i32 m0, s1, 0xe000
	ds_read_b128 v[188:191], v155 offset:1024
	global_load_lds_dwordx4 v138, s[20:21]
	ds_read_b128 v[192:195], v155 offset:2048
	ds_read_b128 v[196:199], v155 offset:3072
	ds_read_b128 v[200:203], v155 offset:4096
	ds_read_b128 v[204:207], v155 offset:5120
	ds_read_b128 v[208:211], v155 offset:6144
	ds_read_b128 v[212:215], v155 offset:7168
	s_waitcnt vmcnt(8)
	s_waitcnt lgkmcnt(0)
	s_barrier
	v_mfma_f32_16x16x32_bf16 v[124:127], v[144:147], v[184:187], v[124:127]
	v_mfma_f32_16x16x32_bf16 v[120:123], v[160:163], v[184:187], v[120:123]
	v_mfma_f32_16x16x32_bf16 v[116:119], v[144:147], v[192:195], v[116:119]
	v_mfma_f32_16x16x32_bf16 v[112:115], v[160:163], v[192:195], v[112:115]
	v_mfma_f32_16x16x32_bf16 v[108:111], v[144:147], v[200:203], v[108:111]
	v_mfma_f32_16x16x32_bf16 v[104:107], v[160:163], v[200:203], v[104:107]
	v_mfma_f32_16x16x32_bf16 v[100:103], v[144:147], v[208:211], v[100:103]
	v_mfma_f32_16x16x32_bf16 v[96:99], v[160:163], v[208:211], v[96:99]
	v_mfma_f32_16x16x32_bf16 v[124:127], v[156:159], v[188:191], v[124:127]
	v_mfma_f32_16x16x32_bf16 v[120:123], v[164:167], v[188:191], v[120:123]
	v_mfma_f32_16x16x32_bf16 v[116:119], v[156:159], v[196:199], v[116:119]
	v_mfma_f32_16x16x32_bf16 v[112:115], v[164:167], v[196:199], v[112:115]
	v_mfma_f32_16x16x32_bf16 v[108:111], v[156:159], v[204:207], v[108:111]
	v_mfma_f32_16x16x32_bf16 v[104:107], v[164:167], v[204:207], v[104:107]
	v_mfma_f32_16x16x32_bf16 v[100:103], v[156:159], v[212:215], v[100:103]
	v_mfma_f32_16x16x32_bf16 v[96:99], v[164:167], v[212:215], v[96:99]
	v_mfma_f32_16x16x32_bf16 v[68:71], v[168:171], v[184:187], v[68:71]
	v_mfma_f32_16x16x32_bf16 v[64:67], v[176:179], v[184:187], v[64:67]
	v_mfma_f32_16x16x32_bf16 v[52:55], v[168:171], v[192:195], v[52:55]
	v_mfma_f32_16x16x32_bf16 v[48:51], v[176:179], v[192:195], v[48:51]
	v_mfma_f32_16x16x32_bf16 v[44:47], v[168:171], v[200:203], v[44:47]
	v_mfma_f32_16x16x32_bf16 v[40:43], v[176:179], v[200:203], v[40:43]
	v_mfma_f32_16x16x32_bf16 v[36:39], v[168:171], v[208:211], v[36:39]
	v_mfma_f32_16x16x32_bf16 v[32:35], v[176:179], v[208:211], v[32:35]
	v_mfma_f32_16x16x32_bf16 v[68:71], v[172:175], v[188:191], v[68:71]
	v_mfma_f32_16x16x32_bf16 v[64:67], v[180:183], v[188:191], v[64:67]
	v_mfma_f32_16x16x32_bf16 v[52:55], v[172:175], v[196:199], v[52:55]
	v_mfma_f32_16x16x32_bf16 v[48:51], v[180:183], v[196:199], v[48:51]
	v_mfma_f32_16x16x32_bf16 v[44:47], v[172:175], v[204:207], v[44:47]
	v_mfma_f32_16x16x32_bf16 v[40:43], v[180:183], v[204:207], v[40:43]
	v_mfma_f32_16x16x32_bf16 v[36:39], v[172:175], v[212:215], v[36:39]
	v_mfma_f32_16x16x32_bf16 v[32:35], v[180:183], v[212:215], v[32:35]
	s_barrier
; #define PG8_STAGE(bufoff, gbase, voff) do { _Pragma("unroll") for (int _i = 0; _i < 2; ++_i) \
;         __builtin_amdgcn_global_load_lds((const unsigned*)((const char*)(gbase) + (voff)[_i]), (LAS unsigned*)(lds + (bufoff) + ldsw + _i * 8192), 16, 0, 0); } while (0)
; #define PG8_LDA(dst, b, h) do { _Pragma("unroll") for (int m = 0; m < 4; ++m) _Pragma("unroll") for (int k = 0; k < 2; ++k) dst[m][k] = *(const LAS bf16x8*)(lds + PG8_SA(b, h) + aoff + m * 2048 + k * 1024); } while (0)
; #define PG8_LDB(dst, b, h) do { _Pragma("unroll") for (int n = 0; n < 2; ++n) _Pragma("unroll") for (int k = 0; k < 2; ++k) dst[n][k] = *(const LAS bf16x8*)(lds + PG8_SB(b, h) + boff + n * 2048 + k * 1024); } while (0)
; #define PG8_MMA(ai, bj, At, Bt) do { __builtin_amdgcn_s_setprio(1); _Pragma("unroll") for (int m = 0; m < 4; ++m) _Pragma("unroll") for (int n = 0; n < 2; ++n) _Pragma("unroll") for (int k = 0; k < 2; ++k) \
;         acc[ai][bj][m][n] = __builtin_amdgcn_mfma_f32_16x16x32_bf16(Bt[n][k], At[m][k], acc[ai][bj][m][n], 0, 0, 0); __builtin_amdgcn_s_setprio(0); } while (0)
; #define PG8_WAIT_V(n) asm volatile("s_waitcnt vmcnt(" #n ")" ::: "memory")
; #define PG8_WAIT_L(n) asm volatile("s_waitcnt lgkmcnt(" #n ")" ::: "memory")
; #define PG8_BAR __builtin_amdgcn_s_barrier()
; #define PG8_SCHED __builtin_amdgcn_sched_barrier(0)
; template <class Epi>
; __device__ __forceinline__ void gemm_phase(LAS unsigned char* lds, const Gemm g, const StaticOrder& S, const Epi& E, const int wid) {
;     ...
;             PG8_LDA(At, 0, 1); PG8_STAGE(PG8_SB(0, 0), b2, voffB); PG8_STAGE(PG8_SB(0, 1), b2 + hstepB, voffB); PG8_STAGE(PG8_SA(0, 0), a2, voffA);
;             PG8_WAIT_V(8); PG8_WAIT_L(0); PG8_BAR; PG8_MMA(1, 0, At, B0); PG8_MMA(1, 1, At, B1); PG8_BAR; PG8_SCHED;
;             PG8_LDB(B0, 1, 0); PG8_LDB(B1, 1, 1); PG8_SCHED; PG8_LDA(At, 1, 0); PG8_STAGE(PG8_SA(0, 1), a2 + hstepA, voffA);
;             PG8_WAIT_V(8); PG8_WAIT_L(0); PG8_BAR; PG8_MMA(0, 0, At, B0); PG8_MMA(0, 1, At, B1); PG8_BAR; PG8_SCHED;
	s_add_i32 s20, s0, s94
	s_mov_b32 m0, s20
	ds_read_b128 v[184:187], v155 offset:16384
	global_load_lds_dwordx4 v132, s[28:29]
	s_add_i32 m0, s20, 0x2000
	s_add_u32 s20, s28, 0x160000
	s_addc_u32 s21, s29, 0
	s_add_i32 s24, s38, s94
	global_load_lds_dwordx4 v128, s[28:29]
	s_mov_b32 m0, s24
	ds_read_b128 v[188:191], v155 offset:17408
	global_load_lds_dwordx4 v132, s[20:21]
	s_add_i32 m0, s24, 0x2000
	ds_read_b128 v[192:195], v155 offset:18432
	global_load_lds_dwordx4 v128, s[20:21]
	s_mov_b32 m0, s1
	ds_read_b128 v[196:199], v155 offset:19456
	global_load_lds_dwordx4 v134, s[30:31]
	s_mov_b32 m0, s12
	ds_read_b128 v[200:203], v155 offset:20480
	global_load_lds_dwordx4 v130, s[30:31]
	ds_read_b128 v[204:207], v155 offset:21504
	ds_read_b128 v[208:211], v155 offset:22528
	ds_read_b128 v[212:215], v155 offset:23552
	s_waitcnt vmcnt(8)
	s_waitcnt lgkmcnt(0)
	s_barrier
	v_mfma_f32_16x16x32_bf16 v[92:95], v[144:147], v[184:187], v[92:95]
	v_mfma_f32_16x16x32_bf16 v[88:91], v[160:163], v[184:187], v[88:91]
	v_mfma_f32_16x16x32_bf16 v[84:87], v[144:147], v[192:195], v[84:87]
	v_mfma_f32_16x16x32_bf16 v[80:83], v[160:163], v[192:195], v[80:83]
	v_mfma_f32_16x16x32_bf16 v[76:79], v[144:147], v[200:203], v[76:79]
	v_mfma_f32_16x16x32_bf16 v[72:75], v[160:163], v[200:203], v[72:75]
	v_mfma_f32_16x16x32_bf16 v[60:63], v[144:147], v[208:211], v[60:63]
	v_mfma_f32_16x16x32_bf16 v[56:59], v[160:163], v[208:211], v[56:59]
	v_mfma_f32_16x16x32_bf16 v[92:95], v[156:159], v[188:191], v[92:95]
	v_mfma_f32_16x16x32_bf16 v[88:91], v[164:167], v[188:191], v[88:91]
	v_mfma_f32_16x16x32_bf16 v[84:87], v[156:159], v[196:199], v[84:87]
	v_mfma_f32_16x16x32_bf16 v[80:83], v[164:167], v[196:199], v[80:83]
	v_mfma_f32_16x16x32_bf16 v[76:79], v[156:159], v[204:207], v[76:79]
	v_mfma_f32_16x16x32_bf16 v[72:75], v[164:167], v[204:207], v[72:75]
	v_mfma_f32_16x16x32_bf16 v[60:63], v[156:159], v[212:215], v[60:63]
	v_mfma_f32_16x16x32_bf16 v[56:59], v[164:167], v[212:215], v[56:59]
	v_mfma_f32_16x16x32_bf16 v[28:31], v[168:171], v[184:187], v[28:31]
	v_mfma_f32_16x16x32_bf16 v[24:27], v[176:179], v[184:187], v[24:27]
	v_mfma_f32_16x16x32_bf16 v[20:23], v[168:171], v[192:195], v[20:23]
	v_mfma_f32_16x16x32_bf16 v[16:19], v[176:179], v[192:195], v[16:19]
	v_mfma_f32_16x16x32_bf16 v[12:15], v[168:171], v[200:203], v[12:15]
	v_mfma_f32_16x16x32_bf16 v[8:11], v[176:179], v[200:203], v[8:11]
	v_mfma_f32_16x16x32_bf16 v[4:7], v[168:171], v[208:211], v[4:7]
	v_mfma_f32_16x16x32_bf16 v[0:3], v[176:179], v[208:211], v[0:3]
	v_mfma_f32_16x16x32_bf16 v[28:31], v[172:175], v[188:191], v[28:31]
	v_mfma_f32_16x16x32_bf16 v[24:27], v[180:183], v[188:191], v[24:27]
	v_mfma_f32_16x16x32_bf16 v[20:23], v[172:175], v[196:199], v[20:23]
	v_mfma_f32_16x16x32_bf16 v[16:19], v[180:183], v[196:199], v[16:19]
	v_mfma_f32_16x16x32_bf16 v[12:15], v[172:175], v[204:207], v[12:15]
	v_mfma_f32_16x16x32_bf16 v[8:11], v[180:183], v[204:207], v[8:11]
	v_mfma_f32_16x16x32_bf16 v[4:7], v[172:175], v[212:215], v[4:7]
	v_mfma_f32_16x16x32_bf16 v[0:3], v[180:183], v[212:215], v[0:3]
	s_barrier
	s_add_i32 s24, 0, 0x18000
	s_add_i32 s25, 0, 0x1c000
	ds_read_b128 v[144:147], v252
	ds_read_b128 v[156:159], v252 offset:1024
	ds_read_b128 v[160:163], v252 offset:2048
	ds_read_b128 v[164:167], v252 offset:3072
	ds_read_b128 v[168:171], v252 offset:16384
	ds_read_b128 v[172:175], v252 offset:17408
	ds_read_b128 v[176:179], v252 offset:18432
	ds_read_b128 v[180:183], v252 offset:19456
	s_add_u32 s20, s30, 0x160000
	s_addc_u32 s21, s31, 0
	s_mov_b32 m0, s15
	ds_read_b128 v[184:187], v155 offset:32768
	global_load_lds_dwordx4 v134, s[20:21]
	s_mov_b32 m0, s34
	ds_read_b128 v[188:191], v155 offset:33792
	global_load_lds_dwordx4 v130, s[20:21]
	ds_read_b128 v[192:195], v155 offset:34816
	ds_read_b128 v[196:199], v155 offset:35840
	ds_read_b128 v[200:203], v155 offset:36864
	ds_read_b128 v[204:207], v155 offset:37888
	ds_read_b128 v[208:211], v155 offset:38912
	ds_read_b128 v[212:215], v155 offset:39936
	s_waitcnt vmcnt(8)
	s_waitcnt lgkmcnt(0)
	s_barrier
; #define PG8_STAGE(bufoff, gbase, voff) do { _Pragma("unroll") for (int _i = 0; _i < 2; ++_i) \
;         __builtin_amdgcn_global_load_lds((const unsigned*)((const char*)(gbase) + (voff)[_i]), (LAS unsigned*)(lds + (bufoff) + ldsw + _i * 8192), 16, 0, 0); } while (0)
; #define PG8_LDA(dst, b, h) do { _Pragma("unroll") for (int m = 0; m < 4; ++m) _Pragma("unroll") for (int k = 0; k < 2; ++k) dst[m][k] = *(const LAS bf16x8*)(lds + PG8_SA(b, h) + aoff + m * 2048 + k * 1024); } while (0)
; #define PG8_MMA(ai, bj, At, Bt) do { __builtin_amdgcn_s_setprio(1); _Pragma("unroll") for (int m = 0; m < 4; ++m) _Pragma("unroll") for (int n = 0; n < 2; ++n) _Pragma("unroll") for (int k = 0; k < 2; ++k) \
;         acc[ai][bj][m][n] = __builtin_amdgcn_mfma_f32_16x16x32_bf16(Bt[n][k], At[m][k], acc[ai][bj][m][n], 0, 0, 0); __builtin_amdgcn_s_setprio(0); } while (0)
; #define PG8_WAIT_V(n) asm volatile("s_waitcnt vmcnt(" #n ")" ::: "memory")
; #define PG8_WAIT_L(n) asm volatile("s_waitcnt lgkmcnt(" #n ")" ::: "memory")
; #define PG8_BAR __builtin_amdgcn_s_barrier()
; #define PG8_SCHED __builtin_amdgcn_sched_barrier(0)
; template <class Epi>
; __device__ __forceinline__ void gemm_phase(LAS unsigned char* lds, const Gemm g, const StaticOrder& S, const Epi& E, const int wid) {
;     ...
;             PG8_WAIT_V(8); PG8_WAIT_L(0); PG8_BAR; PG8_MMA(0, 0, At, B0); PG8_MMA(0, 1, At, B1); PG8_BAR; PG8_SCHED;
;             PG8_LDA(At, 1, 1); PG8_STAGE(PG8_SB(1, 0), b3, voffB); PG8_STAGE(PG8_SB(1, 1), b3 + hstepB, voffB); PG8_STAGE(PG8_SA(1, 0), a3, voffA);
;             PG8_WAIT_V(8); PG8_WAIT_L(0); PG8_BAR; PG8_MMA(1, 0, At, B0); PG8_MMA(1, 1, At, B1); PG8_BAR; PG8_SCHED;
;         }
;         if (wr == 0) PG8_BAR;
	v_mfma_f32_16x16x32_bf16 v[124:127], v[144:147], v[184:187], v[124:127]
	v_mfma_f32_16x16x32_bf16 v[120:123], v[160:163], v[184:187], v[120:123]
	v_mfma_f32_16x16x32_bf16 v[116:119], v[144:147], v[192:195], v[116:119]
	v_mfma_f32_16x16x32_bf16 v[112:115], v[160:163], v[192:195], v[112:115]
	v_mfma_f32_16x16x32_bf16 v[108:111], v[144:147], v[200:203], v[108:111]
	v_mfma_f32_16x16x32_bf16 v[104:107], v[160:163], v[200:203], v[104:107]
	v_mfma_f32_16x16x32_bf16 v[100:103], v[144:147], v[208:211], v[100:103]
	v_mfma_f32_16x16x32_bf16 v[96:99], v[160:163], v[208:211], v[96:99]
	v_mfma_f32_16x16x32_bf16 v[124:127], v[156:159], v[188:191], v[124:127]
	v_mfma_f32_16x16x32_bf16 v[120:123], v[164:167], v[188:191], v[120:123]
	v_mfma_f32_16x16x32_bf16 v[116:119], v[156:159], v[196:199], v[116:119]
	v_mfma_f32_16x16x32_bf16 v[112:115], v[164:167], v[196:199], v[112:115]
	v_mfma_f32_16x16x32_bf16 v[108:111], v[156:159], v[204:207], v[108:111]
	v_mfma_f32_16x16x32_bf16 v[104:107], v[164:167], v[204:207], v[104:107]
	v_mfma_f32_16x16x32_bf16 v[100:103], v[156:159], v[212:215], v[100:103]
	v_mfma_f32_16x16x32_bf16 v[96:99], v[164:167], v[212:215], v[96:99]
	v_mfma_f32_16x16x32_bf16 v[68:71], v[168:171], v[184:187], v[68:71]
	v_mfma_f32_16x16x32_bf16 v[64:67], v[176:179], v[184:187], v[64:67]
	v_mfma_f32_16x16x32_bf16 v[52:55], v[168:171], v[192:195], v[52:55]
	v_mfma_f32_16x16x32_bf16 v[48:51], v[176:179], v[192:195], v[48:51]
	v_mfma_f32_16x16x32_bf16 v[44:47], v[168:171], v[200:203], v[44:47]
	v_mfma_f32_16x16x32_bf16 v[40:43], v[176:179], v[200:203], v[40:43]
	v_mfma_f32_16x16x32_bf16 v[36:39], v[168:171], v[208:211], v[36:39]
	v_mfma_f32_16x16x32_bf16 v[32:35], v[176:179], v[208:211], v[32:35]
	v_mfma_f32_16x16x32_bf16 v[68:71], v[172:175], v[188:191], v[68:71]
	v_mfma_f32_16x16x32_bf16 v[64:67], v[180:183], v[188:191], v[64:67]
	v_mfma_f32_16x16x32_bf16 v[52:55], v[172:175], v[196:199], v[52:55]
	v_mfma_f32_16x16x32_bf16 v[48:51], v[180:183], v[196:199], v[48:51]
	v_mfma_f32_16x16x32_bf16 v[44:47], v[172:175], v[204:207], v[44:47]
	v_mfma_f32_16x16x32_bf16 v[40:43], v[180:183], v[204:207], v[40:43]
	v_mfma_f32_16x16x32_bf16 v[36:39], v[172:175], v[212:215], v[36:39]
	v_mfma_f32_16x16x32_bf16 v[32:35], v[180:183], v[212:215], v[32:35]
	s_barrier
	s_add_i32 s20, s24, s94
	s_add_u32 s98, s28, 0x80
	s_addc_u32 s99, s29, 0
	s_mov_b32 m0, s20
	ds_read_b128 v[184:187], v155 offset:49152
	global_load_lds_dwordx4 v132, s[98:99]
	s_add_i32 m0, s20, 0x2000
	s_add_u32 s20, s28, 0x160080
	s_addc_u32 s21, s29, 0
	s_add_i32 s24, s25, s94
	global_load_lds_dwordx4 v128, s[98:99]
	s_mov_b32 m0, s24
	ds_read_b128 v[188:191], v155 offset:50176
	global_load_lds_dwordx4 v132, s[20:21]
	s_add_i32 m0, s24, 0x2000
	ds_read_b128 v[192:195], v155 offset:51200
	global_load_lds_dwordx4 v128, s[20:21]
	s_add_u32 s100, s30, 0x80
	s_addc_u32 s101, s31, 0
	s_mov_b32 m0, s36
	ds_read_b128 v[196:199], v155 offset:52224
	global_load_lds_dwordx4 v134, s[100:101]
	s_mov_b32 m0, s37
	ds_read_b128 v[200:203], v155 offset:53248
	global_load_lds_dwordx4 v130, s[100:101]
	ds_read_b128 v[204:207], v155 offset:54272
	ds_read_b128 v[208:211], v155 offset:55296
	ds_read_b128 v[212:215], v155 offset:56320
	s_waitcnt vmcnt(8)
	s_waitcnt lgkmcnt(0)
	s_barrier
	v_mfma_f32_16x16x32_bf16 v[92:95], v[144:147], v[184:187], v[92:95]
	v_mfma_f32_16x16x32_bf16 v[88:91], v[160:163], v[184:187], v[88:91]
	v_mfma_f32_16x16x32_bf16 v[84:87], v[144:147], v[192:195], v[84:87]
	v_mfma_f32_16x16x32_bf16 v[80:83], v[160:163], v[192:195], v[80:83]
	v_mfma_f32_16x16x32_bf16 v[76:79], v[144:147], v[200:203], v[76:79]
	v_mfma_f32_16x16x32_bf16 v[72:75], v[160:163], v[200:203], v[72:75]
	v_mfma_f32_16x16x32_bf16 v[60:63], v[144:147], v[208:211], v[60:63]
	v_mfma_f32_16x16x32_bf16 v[56:59], v[160:163], v[208:211], v[56:59]
	v_mfma_f32_16x16x32_bf16 v[92:95], v[156:159], v[188:191], v[92:95]
	v_mfma_f32_16x16x32_bf16 v[88:91], v[164:167], v[188:191], v[88:91]
	v_mfma_f32_16x16x32_bf16 v[84:87], v[156:159], v[196:199], v[84:87]
	v_mfma_f32_16x16x32_bf16 v[80:83], v[164:167], v[196:199], v[80:83]
	v_mfma_f32_16x16x32_bf16 v[76:79], v[156:159], v[204:207], v[76:79]
	v_mfma_f32_16x16x32_bf16 v[72:75], v[164:167], v[204:207], v[72:75]
	v_mfma_f32_16x16x32_bf16 v[60:63], v[156:159], v[212:215], v[60:63]
	v_mfma_f32_16x16x32_bf16 v[56:59], v[164:167], v[212:215], v[56:59]
	v_mfma_f32_16x16x32_bf16 v[28:31], v[168:171], v[184:187], v[28:31]
	v_mfma_f32_16x16x32_bf16 v[24:27], v[176:179], v[184:187], v[24:27]
	v_mfma_f32_16x16x32_bf16 v[20:23], v[168:171], v[192:195], v[20:23]
	v_mfma_f32_16x16x32_bf16 v[16:19], v[176:179], v[192:195], v[16:19]
	v_mfma_f32_16x16x32_bf16 v[12:15], v[168:171], v[200:203], v[12:15]
	v_mfma_f32_16x16x32_bf16 v[8:11], v[176:179], v[200:203], v[8:11]
	v_mfma_f32_16x16x32_bf16 v[4:7], v[168:171], v[208:211], v[4:7]
	v_mfma_f32_16x16x32_bf16 v[0:3], v[176:179], v[208:211], v[0:3]
	v_mfma_f32_16x16x32_bf16 v[28:31], v[172:175], v[188:191], v[28:31]
	v_mfma_f32_16x16x32_bf16 v[24:27], v[180:183], v[188:191], v[24:27]
	v_mfma_f32_16x16x32_bf16 v[20:23], v[172:175], v[196:199], v[20:23]
	v_mfma_f32_16x16x32_bf16 v[16:19], v[180:183], v[196:199], v[16:19]
	v_mfma_f32_16x16x32_bf16 v[12:15], v[172:175], v[204:207], v[12:15]
	v_mfma_f32_16x16x32_bf16 v[8:11], v[180:183], v[204:207], v[8:11]
	v_mfma_f32_16x16x32_bf16 v[4:7], v[172:175], v[212:215], v[4:7]
	v_mfma_f32_16x16x32_bf16 v[0:3], v[180:183], v[212:215], v[0:3]
	s_barrier
	s_add_i32 s45, s45, 2
	s_add_u32 s43, s43, 0x100
	s_addc_u32 s44, s44, 0
	s_cmpk_gt_u32 s45, 0x55
	s_mov_b64 s[20:21], s[26:27]
	s_cbranch_scc0 .LBB0_1810
	s_and_b64 vcc, exec, s[22:23]
	s_cbranch_vccz .LBB0_1813
	s_barrier
